# v29 with the per-phase s_setprio toggling removed from all GEMM K-loops (attention priority kept)
# speedup vs baseline: 1.0027x; 1.0027x over previous
.LBB0_132:
	v_add_u32_e32 v153, s43, v161
	ds_read_b128 v[156:159], v153
	ds_read_b128 v[164:167], v153 offset:1024
	ds_read_b128 v[168:171], v153 offset:2048
	ds_read_b128 v[172:175], v153 offset:3072
	v_add_u32_e32 v153, s44, v161
	ds_read_b128 v[176:179], v153
	ds_read_b128 v[180:183], v153 offset:1024
	ds_read_b128 v[184:187], v153 offset:2048
	ds_read_b128 v[188:191], v153 offset:3072
	s_add_u32 s34, s28, 0xfff80080
	s_addc_u32 s35, s29, -1
	s_and_b64 s[30:31], s[30:31], exec
	s_cselect_b32 s35, s23, s35
	s_cselect_b32 s34, s48, s34
	s_cselect_b32 s31, s21, s53
	s_cselect_b32 s30, s49, s51
	s_add_i32 m0, s19, 0xc000
	ds_read_b128 v[192:195], v163
	ds_read_b128 v[196:199], v163 offset:1024
	ds_read_b128 v[200:203], v163 offset:2048
	ds_read_b128 v[204:207], v163 offset:3072
	ds_read_b128 v[208:211], v163 offset:4096
	ds_read_b128 v[212:215], v163 offset:5120
	ds_read_b128 v[216:219], v163 offset:6144
	ds_read_b128 v[222:225], v163 offset:7168
	global_load_lds_dwordx4 v136, s[28:29]
	s_add_i32 m0, s19, 0xe000
	s_nop 0
	global_load_lds_dwordx4 v138, s[28:29]
	s_waitcnt vmcnt(8)
	s_waitcnt lgkmcnt(0)
	s_waitcnt lgkmcnt(0)
	v_mfma_f32_16x16x32_bf16 v[124:127], v[156:159], v[192:195], v[124:127]
	v_mfma_f32_16x16x32_bf16 v[120:123], v[168:171], v[192:195], v[120:123]
	v_mfma_f32_16x16x32_bf16 v[124:127], v[164:167], v[196:199], v[124:127]
	v_mfma_f32_16x16x32_bf16 v[120:123], v[172:175], v[196:199], v[120:123]
	s_barrier
	v_mfma_f32_16x16x32_bf16 v[108:111], v[156:159], v[200:203], v[108:111]
	v_mfma_f32_16x16x32_bf16 v[104:107], v[168:171], v[200:203], v[104:107]
	v_mfma_f32_16x16x32_bf16 v[92:95], v[156:159], v[208:211], v[92:95]
	v_mfma_f32_16x16x32_bf16 v[88:91], v[168:171], v[208:211], v[88:91]
	v_mfma_f32_16x16x32_bf16 v[76:79], v[156:159], v[216:219], v[76:79]
	v_mfma_f32_16x16x32_bf16 v[72:75], v[168:171], v[216:219], v[72:75]
	v_mfma_f32_16x16x32_bf16 v[116:119], v[176:179], v[192:195], v[116:119]
	v_mfma_f32_16x16x32_bf16 v[112:115], v[184:187], v[192:195], v[112:115]
	v_mfma_f32_16x16x32_bf16 v[100:103], v[176:179], v[200:203], v[100:103]
	v_mfma_f32_16x16x32_bf16 v[96:99], v[184:187], v[200:203], v[96:99]
	v_mfma_f32_16x16x32_bf16 v[84:87], v[176:179], v[208:211], v[84:87]
	v_mfma_f32_16x16x32_bf16 v[80:83], v[184:187], v[208:211], v[80:83]
	v_mfma_f32_16x16x32_bf16 v[68:71], v[176:179], v[216:219], v[68:71]
	v_mfma_f32_16x16x32_bf16 v[64:67], v[184:187], v[216:219], v[64:67]
	v_mfma_f32_16x16x32_bf16 v[108:111], v[164:167], v[204:207], v[108:111]
	v_mfma_f32_16x16x32_bf16 v[104:107], v[172:175], v[204:207], v[104:107]
	v_mfma_f32_16x16x32_bf16 v[92:95], v[164:167], v[212:215], v[92:95]
	v_mfma_f32_16x16x32_bf16 v[88:91], v[172:175], v[212:215], v[88:91]
	v_mfma_f32_16x16x32_bf16 v[76:79], v[164:167], v[222:225], v[76:79]
	v_mfma_f32_16x16x32_bf16 v[72:75], v[172:175], v[222:225], v[72:75]
	v_mfma_f32_16x16x32_bf16 v[116:119], v[180:183], v[196:199], v[116:119]
	v_mfma_f32_16x16x32_bf16 v[112:115], v[188:191], v[196:199], v[112:115]
	v_mfma_f32_16x16x32_bf16 v[100:103], v[180:183], v[204:207], v[100:103]
	v_mfma_f32_16x16x32_bf16 v[96:99], v[188:191], v[204:207], v[96:99]
	v_mfma_f32_16x16x32_bf16 v[84:87], v[180:183], v[212:215], v[84:87]
	v_mfma_f32_16x16x32_bf16 v[80:83], v[188:191], v[212:215], v[80:83]
	v_mfma_f32_16x16x32_bf16 v[68:71], v[180:183], v[222:225], v[68:71]
	v_mfma_f32_16x16x32_bf16 v[64:67], v[188:191], v[222:225], v[64:67]
	s_barrier
	s_add_i32 s56, s43, s2
	v_lshl_add_u64 v[226:227], s[30:31], 0, v[132:133]
	s_mov_b32 m0, s56
	ds_read_b128 v[192:195], v163 offset:16384
	ds_read_b128 v[196:199], v163 offset:17408
	ds_read_b128 v[200:203], v163 offset:18432
	ds_read_b128 v[204:207], v163 offset:19456
	ds_read_b128 v[208:211], v163 offset:20480
	ds_read_b128 v[212:215], v163 offset:21504
	ds_read_b128 v[216:219], v163 offset:22528
	ds_read_b128 v[222:225], v163 offset:23552
	global_load_lds_dwordx4 v[226:227], off
	s_add_i32 m0, s56, 0x2000
	s_add_u32 s56, s30, 0x80000
	v_lshl_add_u64 v[228:229], s[30:31], 0, v[128:129]
	s_addc_u32 s57, s31, 0
	s_add_i32 s58, s44, s2
	global_load_lds_dwordx4 v[228:229], off
	s_mov_b32 m0, s58
	v_lshl_add_u64 v[232:233], s[34:35], 0, v[130:131]
	global_load_lds_dwordx4 v132, s[56:57]
	s_add_i32 m0, s58, 0x2000
	s_nop 0
	global_load_lds_dwordx4 v128, s[56:57]
	v_lshl_add_u64 v[230:231], s[34:35], 0, v[134:135]
	s_mov_b32 m0, s19
	s_nop 0
	global_load_lds_dwordx4 v[230:231], off
	s_mov_b32 m0, s33
	s_nop 0
	global_load_lds_dwordx4 v[232:233], off
	s_waitcnt vmcnt(8)
	s_waitcnt lgkmcnt(0)
	s_waitcnt lgkmcnt(0)
	v_mfma_f32_16x16x32_bf16 v[60:63], v[156:159], v[192:195], v[60:63]
	v_mfma_f32_16x16x32_bf16 v[56:59], v[168:171], v[192:195], v[56:59]
	v_mfma_f32_16x16x32_bf16 v[60:63], v[164:167], v[196:199], v[60:63]
	v_mfma_f32_16x16x32_bf16 v[56:59], v[172:175], v[196:199], v[56:59]
	s_barrier
	v_mfma_f32_16x16x32_bf16 v[44:47], v[156:159], v[200:203], v[44:47]
	v_mfma_f32_16x16x32_bf16 v[40:43], v[168:171], v[200:203], v[40:43]
	v_mfma_f32_16x16x32_bf16 v[28:31], v[156:159], v[208:211], v[28:31]
	v_mfma_f32_16x16x32_bf16 v[24:27], v[168:171], v[208:211], v[24:27]
	v_mfma_f32_16x16x32_bf16 v[12:15], v[156:159], v[216:219], v[12:15]
	v_mfma_f32_16x16x32_bf16 v[8:11], v[168:171], v[216:219], v[8:11]
	v_mfma_f32_16x16x32_bf16 v[52:55], v[176:179], v[192:195], v[52:55]
	v_mfma_f32_16x16x32_bf16 v[48:51], v[184:187], v[192:195], v[48:51]
	v_mfma_f32_16x16x32_bf16 v[36:39], v[176:179], v[200:203], v[36:39]
	v_mfma_f32_16x16x32_bf16 v[32:35], v[184:187], v[200:203], v[32:35]
	v_mfma_f32_16x16x32_bf16 v[20:23], v[176:179], v[208:211], v[20:23]
	v_mfma_f32_16x16x32_bf16 v[16:19], v[184:187], v[208:211], v[16:19]
	v_mfma_f32_16x16x32_bf16 v[4:7], v[176:179], v[216:219], v[4:7]
	v_mfma_f32_16x16x32_bf16 v[0:3], v[184:187], v[216:219], v[0:3]
	v_mfma_f32_16x16x32_bf16 v[44:47], v[164:167], v[204:207], v[44:47]
	v_mfma_f32_16x16x32_bf16 v[40:43], v[172:175], v[204:207], v[40:43]
	v_mfma_f32_16x16x32_bf16 v[28:31], v[164:167], v[212:215], v[28:31]
	v_mfma_f32_16x16x32_bf16 v[24:27], v[172:175], v[212:215], v[24:27]
	v_mfma_f32_16x16x32_bf16 v[12:15], v[164:167], v[222:225], v[12:15]
	v_mfma_f32_16x16x32_bf16 v[8:11], v[172:175], v[222:225], v[8:11]
	v_mfma_f32_16x16x32_bf16 v[52:55], v[180:183], v[196:199], v[52:55]
	v_mfma_f32_16x16x32_bf16 v[48:51], v[188:191], v[196:199], v[48:51]
	v_mfma_f32_16x16x32_bf16 v[36:39], v[180:183], v[204:207], v[36:39]
	v_mfma_f32_16x16x32_bf16 v[32:35], v[188:191], v[204:207], v[32:35]
	v_mfma_f32_16x16x32_bf16 v[20:23], v[180:183], v[212:215], v[20:23]
	v_mfma_f32_16x16x32_bf16 v[16:19], v[188:191], v[212:215], v[16:19]
	v_mfma_f32_16x16x32_bf16 v[4:7], v[180:183], v[222:225], v[4:7]
	v_mfma_f32_16x16x32_bf16 v[0:3], v[188:191], v[222:225], v[0:3]
	s_barrier
	s_add_i32 s56, 0, 0x18000
	v_add_u32_e32 v153, s56, v161
	s_add_i32 s57, 0, 0x1c000
	ds_read_b128 v[156:159], v153
	ds_read_b128 v[164:167], v153 offset:1024
	ds_read_b128 v[168:171], v153 offset:2048
	ds_read_b128 v[172:175], v153 offset:3072
	v_add_u32_e32 v153, s57, v161
	ds_read_b128 v[176:179], v153
	ds_read_b128 v[180:183], v153 offset:1024
	ds_read_b128 v[184:187], v153 offset:2048
	ds_read_b128 v[188:191], v153 offset:3072
	s_add_u32 s34, s34, 0x80000
	s_addc_u32 s35, s35, 0
	s_mov_b32 m0, s36
	ds_read_b128 v[192:195], v163 offset:32768
	ds_read_b128 v[196:199], v163 offset:33792
	ds_read_b128 v[200:203], v163 offset:34816
	ds_read_b128 v[204:207], v163 offset:35840
	ds_read_b128 v[208:211], v163 offset:36864
	ds_read_b128 v[212:215], v163 offset:37888
	ds_read_b128 v[216:219], v163 offset:38912
	ds_read_b128 v[222:225], v163 offset:39936
	global_load_lds_dwordx4 v134, s[34:35]
	s_mov_b32 m0, s37
	s_nop 0
	global_load_lds_dwordx4 v130, s[34:35]
	s_waitcnt vmcnt(8)
	s_waitcnt lgkmcnt(0)
	s_waitcnt lgkmcnt(0)
	v_mfma_f32_16x16x32_bf16 v[124:127], v[156:159], v[192:195], v[124:127]
	v_mfma_f32_16x16x32_bf16 v[120:123], v[168:171], v[192:195], v[120:123]
	v_mfma_f32_16x16x32_bf16 v[124:127], v[164:167], v[196:199], v[124:127]
	v_mfma_f32_16x16x32_bf16 v[120:123], v[172:175], v[196:199], v[120:123]
	s_barrier
	v_mfma_f32_16x16x32_bf16 v[108:111], v[156:159], v[200:203], v[108:111]
	v_mfma_f32_16x16x32_bf16 v[104:107], v[168:171], v[200:203], v[104:107]
	v_mfma_f32_16x16x32_bf16 v[92:95], v[156:159], v[208:211], v[92:95]
	v_mfma_f32_16x16x32_bf16 v[88:91], v[168:171], v[208:211], v[88:91]
	v_mfma_f32_16x16x32_bf16 v[76:79], v[156:159], v[216:219], v[76:79]
	v_mfma_f32_16x16x32_bf16 v[72:75], v[168:171], v[216:219], v[72:75]
	v_mfma_f32_16x16x32_bf16 v[116:119], v[176:179], v[192:195], v[116:119]
	v_mfma_f32_16x16x32_bf16 v[112:115], v[184:187], v[192:195], v[112:115]
	v_mfma_f32_16x16x32_bf16 v[100:103], v[176:179], v[200:203], v[100:103]
	v_mfma_f32_16x16x32_bf16 v[96:99], v[184:187], v[200:203], v[96:99]
	v_mfma_f32_16x16x32_bf16 v[84:87], v[176:179], v[208:211], v[84:87]
	v_mfma_f32_16x16x32_bf16 v[80:83], v[184:187], v[208:211], v[80:83]
	v_mfma_f32_16x16x32_bf16 v[68:71], v[176:179], v[216:219], v[68:71]
	v_mfma_f32_16x16x32_bf16 v[64:67], v[184:187], v[216:219], v[64:67]
	v_mfma_f32_16x16x32_bf16 v[108:111], v[164:167], v[204:207], v[108:111]
	v_mfma_f32_16x16x32_bf16 v[104:107], v[172:175], v[204:207], v[104:107]
	v_mfma_f32_16x16x32_bf16 v[92:95], v[164:167], v[212:215], v[92:95]
	v_mfma_f32_16x16x32_bf16 v[88:91], v[172:175], v[212:215], v[88:91]
	v_mfma_f32_16x16x32_bf16 v[76:79], v[164:167], v[222:225], v[76:79]
	v_mfma_f32_16x16x32_bf16 v[72:75], v[172:175], v[222:225], v[72:75]
	v_mfma_f32_16x16x32_bf16 v[116:119], v[180:183], v[196:199], v[116:119]
	v_mfma_f32_16x16x32_bf16 v[112:115], v[188:191], v[196:199], v[112:115]
	v_mfma_f32_16x16x32_bf16 v[100:103], v[180:183], v[204:207], v[100:103]
	v_mfma_f32_16x16x32_bf16 v[96:99], v[188:191], v[204:207], v[96:99]
	v_mfma_f32_16x16x32_bf16 v[84:87], v[180:183], v[212:215], v[84:87]
	v_mfma_f32_16x16x32_bf16 v[80:83], v[188:191], v[212:215], v[80:83]
	v_mfma_f32_16x16x32_bf16 v[68:71], v[180:183], v[222:225], v[68:71]
	v_mfma_f32_16x16x32_bf16 v[64:67], v[188:191], v[222:225], v[64:67]
	s_barrier
	s_add_i32 s34, s56, s2
	v_lshl_add_u64 v[226:227], v[226:227], 0, s[8:9]
	s_mov_b32 m0, s34
	ds_read_b128 v[192:195], v163 offset:49152
	ds_read_b128 v[196:199], v163 offset:50176
	ds_read_b128 v[200:203], v163 offset:51200
	ds_read_b128 v[204:207], v163 offset:52224
	ds_read_b128 v[208:211], v163 offset:53248
	ds_read_b128 v[212:215], v163 offset:54272
	ds_read_b128 v[216:219], v163 offset:55296
	ds_read_b128 v[222:225], v163 offset:56320
	global_load_lds_dwordx4 v[226:227], off
	s_add_i32 m0, s34, 0x2000
	s_add_u32 s30, s30, 0x80080
	v_lshl_add_u64 v[226:227], v[228:229], 0, s[8:9]
	s_addc_u32 s31, s31, 0
	s_add_i32 s34, s57, s2
	global_load_lds_dwordx4 v[226:227], off
	s_mov_b32 m0, s34
	s_nop 0
	global_load_lds_dwordx4 v132, s[30:31]
	s_add_i32 m0, s34, 0x2000
	s_nop 0
	global_load_lds_dwordx4 v128, s[30:31]
	v_lshl_add_u64 v[226:227], v[230:231], 0, s[8:9]
	s_mov_b32 m0, s39
	s_nop 0
	global_load_lds_dwordx4 v[226:227], off
	v_lshl_add_u64 v[226:227], v[232:233], 0, s[8:9]
	s_mov_b32 m0, s40
	s_nop 0
	global_load_lds_dwordx4 v[226:227], off
	s_waitcnt vmcnt(8)
	s_waitcnt lgkmcnt(0)
	s_waitcnt lgkmcnt(0)
	v_mfma_f32_16x16x32_bf16 v[60:63], v[156:159], v[192:195], v[60:63]
	v_mfma_f32_16x16x32_bf16 v[56:59], v[168:171], v[192:195], v[56:59]
	v_mfma_f32_16x16x32_bf16 v[60:63], v[164:167], v[196:199], v[60:63]
	v_mfma_f32_16x16x32_bf16 v[56:59], v[172:175], v[196:199], v[56:59]
	s_barrier
	v_mfma_f32_16x16x32_bf16 v[44:47], v[156:159], v[200:203], v[44:47]
	v_mfma_f32_16x16x32_bf16 v[40:43], v[168:171], v[200:203], v[40:43]
	v_mfma_f32_16x16x32_bf16 v[28:31], v[156:159], v[208:211], v[28:31]
	v_mfma_f32_16x16x32_bf16 v[24:27], v[168:171], v[208:211], v[24:27]
	v_mfma_f32_16x16x32_bf16 v[12:15], v[156:159], v[216:219], v[12:15]
	v_mfma_f32_16x16x32_bf16 v[8:11], v[168:171], v[216:219], v[8:11]
	v_mfma_f32_16x16x32_bf16 v[52:55], v[176:179], v[192:195], v[52:55]
	v_mfma_f32_16x16x32_bf16 v[48:51], v[184:187], v[192:195], v[48:51]
	v_mfma_f32_16x16x32_bf16 v[36:39], v[176:179], v[200:203], v[36:39]
	v_mfma_f32_16x16x32_bf16 v[32:35], v[184:187], v[200:203], v[32:35]
	v_mfma_f32_16x16x32_bf16 v[20:23], v[176:179], v[208:211], v[20:23]
	v_mfma_f32_16x16x32_bf16 v[16:19], v[184:187], v[208:211], v[16:19]
	v_mfma_f32_16x16x32_bf16 v[4:7], v[176:179], v[216:219], v[4:7]
	v_mfma_f32_16x16x32_bf16 v[0:3], v[184:187], v[216:219], v[0:3]
	v_mfma_f32_16x16x32_bf16 v[44:47], v[164:167], v[204:207], v[44:47]
	v_mfma_f32_16x16x32_bf16 v[40:43], v[172:175], v[204:207], v[40:43]
	v_mfma_f32_16x16x32_bf16 v[28:31], v[164:167], v[212:215], v[28:31]
	v_mfma_f32_16x16x32_bf16 v[24:27], v[172:175], v[212:215], v[24:27]
	v_mfma_f32_16x16x32_bf16 v[12:15], v[164:167], v[222:225], v[12:15]
	v_mfma_f32_16x16x32_bf16 v[8:11], v[172:175], v[222:225], v[8:11]
	v_mfma_f32_16x16x32_bf16 v[52:55], v[180:183], v[196:199], v[52:55]
	v_mfma_f32_16x16x32_bf16 v[48:51], v[188:191], v[196:199], v[48:51]
	v_mfma_f32_16x16x32_bf16 v[36:39], v[180:183], v[204:207], v[36:39]
	v_mfma_f32_16x16x32_bf16 v[32:35], v[188:191], v[204:207], v[32:35]
	v_mfma_f32_16x16x32_bf16 v[20:23], v[180:183], v[212:215], v[20:23]
	v_mfma_f32_16x16x32_bf16 v[16:19], v[188:191], v[212:215], v[16:19]
	v_mfma_f32_16x16x32_bf16 v[4:7], v[180:183], v[222:225], v[4:7]
	v_mfma_f32_16x16x32_bf16 v[0:3], v[188:191], v[222:225], v[0:3]
	s_barrier
	s_add_i32 s55, s55, 2
	s_add_u32 s28, s28, 0x100
	s_addc_u32 s29, s29, 0
	s_add_u32 s51, s51, 0x100
	s_addc_u32 s53, s53, 0
	s_cmp_gt_u32 s55, 29
	s_cbranch_scc1 .LBB0_135

.LBB0_237:
	ds_read_b128 v[144:147], v151
	ds_read_b128 v[156:159], v151 offset:1024
	ds_read_b128 v[160:163], v151 offset:2048
	ds_read_b128 v[164:167], v151 offset:3072
	ds_read_b128 v[168:171], v152
	ds_read_b128 v[172:175], v152 offset:1024
	ds_read_b128 v[176:179], v152 offset:2048
	ds_read_b128 v[180:183], v152 offset:3072
	s_add_u32 s24, s22, 0x100
	s_addc_u32 s25, s23, 0
	s_cmpk_eq_i32 s51, 0x54
	s_cselect_b32 s29, s1, s25
	s_cselect_b32 s28, s0, s24
	s_cselect_b32 s27, s21, s49
	s_cselect_b32 s26, s20, s48
	v_lshl_add_u64 v[216:217], s[22:23], 0, v[136:137]
	s_add_i32 m0, s31, 0xc000
	ds_read_b128 v[184:187], v153
	ds_read_b128 v[188:191], v153 offset:1024
	ds_read_b128 v[192:195], v153 offset:2048
	ds_read_b128 v[196:199], v153 offset:3072
	ds_read_b128 v[200:203], v153 offset:4096
	ds_read_b128 v[204:207], v153 offset:5120
	ds_read_b128 v[208:211], v153 offset:6144
	ds_read_b128 v[212:215], v153 offset:7168
	global_load_lds_dwordx4 v[216:217], off
	v_lshl_add_u64 v[216:217], s[22:23], 0, v[138:139]
	s_add_i32 m0, s31, 0xe000
	s_nop 0
	global_load_lds_dwordx4 v[216:217], off
	s_waitcnt vmcnt(8)
	s_waitcnt lgkmcnt(0)
	s_waitcnt lgkmcnt(0)
	v_mfma_f32_16x16x32_bf16 v[124:127], v[144:147], v[184:187], v[124:127]
	v_mfma_f32_16x16x32_bf16 v[120:123], v[160:163], v[184:187], v[120:123]
	v_mfma_f32_16x16x32_bf16 v[124:127], v[156:159], v[188:191], v[124:127]
	v_mfma_f32_16x16x32_bf16 v[120:123], v[164:167], v[188:191], v[120:123]
	s_barrier
	v_mfma_f32_16x16x32_bf16 v[108:111], v[144:147], v[192:195], v[108:111]
	v_mfma_f32_16x16x32_bf16 v[104:107], v[160:163], v[192:195], v[104:107]
	v_mfma_f32_16x16x32_bf16 v[92:95], v[144:147], v[200:203], v[92:95]
	v_mfma_f32_16x16x32_bf16 v[88:91], v[160:163], v[200:203], v[88:91]
	v_mfma_f32_16x16x32_bf16 v[76:79], v[144:147], v[208:211], v[76:79]
	v_mfma_f32_16x16x32_bf16 v[72:75], v[160:163], v[208:211], v[72:75]
	v_mfma_f32_16x16x32_bf16 v[116:119], v[168:171], v[184:187], v[116:119]
	v_mfma_f32_16x16x32_bf16 v[112:115], v[176:179], v[184:187], v[112:115]
	v_mfma_f32_16x16x32_bf16 v[100:103], v[168:171], v[192:195], v[100:103]
	v_mfma_f32_16x16x32_bf16 v[96:99], v[176:179], v[192:195], v[96:99]
	v_mfma_f32_16x16x32_bf16 v[84:87], v[168:171], v[200:203], v[84:87]
	v_mfma_f32_16x16x32_bf16 v[80:83], v[176:179], v[200:203], v[80:83]
	v_mfma_f32_16x16x32_bf16 v[68:71], v[168:171], v[208:211], v[68:71]
	v_mfma_f32_16x16x32_bf16 v[64:67], v[176:179], v[208:211], v[64:67]
	v_mfma_f32_16x16x32_bf16 v[108:111], v[156:159], v[196:199], v[108:111]
	v_mfma_f32_16x16x32_bf16 v[104:107], v[164:167], v[196:199], v[104:107]
	v_mfma_f32_16x16x32_bf16 v[92:95], v[156:159], v[204:207], v[92:95]
	v_mfma_f32_16x16x32_bf16 v[88:91], v[164:167], v[204:207], v[88:91]
	v_mfma_f32_16x16x32_bf16 v[76:79], v[156:159], v[212:215], v[76:79]
	v_mfma_f32_16x16x32_bf16 v[72:75], v[164:167], v[212:215], v[72:75]
	v_mfma_f32_16x16x32_bf16 v[116:119], v[172:175], v[188:191], v[116:119]
	v_mfma_f32_16x16x32_bf16 v[112:115], v[180:183], v[188:191], v[112:115]
	v_mfma_f32_16x16x32_bf16 v[100:103], v[172:175], v[196:199], v[100:103]
	v_mfma_f32_16x16x32_bf16 v[96:99], v[180:183], v[196:199], v[96:99]
	v_mfma_f32_16x16x32_bf16 v[84:87], v[172:175], v[204:207], v[84:87]
	v_mfma_f32_16x16x32_bf16 v[80:83], v[180:183], v[204:207], v[80:83]
	v_mfma_f32_16x16x32_bf16 v[68:71], v[172:175], v[212:215], v[68:71]
	v_mfma_f32_16x16x32_bf16 v[64:67], v[180:183], v[212:215], v[64:67]
	s_barrier
	s_add_i32 s22, s42, s30
	v_lshl_add_u64 v[216:217], s[26:27], 0, v[130:131]
	s_mov_b32 m0, s22
	ds_read_b128 v[184:187], v153 offset:16384
	ds_read_b128 v[188:191], v153 offset:17408
	ds_read_b128 v[192:195], v153 offset:18432
	ds_read_b128 v[196:199], v153 offset:19456
	ds_read_b128 v[200:203], v153 offset:20480
	ds_read_b128 v[204:207], v153 offset:21504
	ds_read_b128 v[208:211], v153 offset:22528
	ds_read_b128 v[212:215], v153 offset:23552
	global_load_lds_dwordx4 v[216:217], off
	s_add_i32 m0, s22, 0x2000
	s_add_u32 s22, s26, 0x160000
	v_lshl_add_u64 v[218:219], s[26:27], 0, v[134:135]
	s_addc_u32 s23, s27, 0
	s_add_i32 s53, s43, s30
	global_load_lds_dwordx4 v[218:219], off
	s_mov_b32 m0, s53
	v_lshl_add_u64 v[224:225], s[28:29], 0, v[132:133]
	global_load_lds_dwordx4 v130, s[22:23]
	s_add_i32 m0, s53, 0x2000
	s_nop 0
	global_load_lds_dwordx4 v134, s[22:23]
	v_lshl_add_u64 v[222:223], s[28:29], 0, v[128:129]
	s_mov_b32 m0, s31
	s_nop 0
	global_load_lds_dwordx4 v[222:223], off
	s_mov_b32 m0, s33
	s_nop 0
	global_load_lds_dwordx4 v[224:225], off
	s_waitcnt vmcnt(8)
	s_waitcnt lgkmcnt(0)
	s_waitcnt lgkmcnt(0)
	v_mfma_f32_16x16x32_bf16 v[60:63], v[144:147], v[184:187], v[60:63]
	v_mfma_f32_16x16x32_bf16 v[56:59], v[160:163], v[184:187], v[56:59]
	v_mfma_f32_16x16x32_bf16 v[60:63], v[156:159], v[188:191], v[60:63]
	v_mfma_f32_16x16x32_bf16 v[56:59], v[164:167], v[188:191], v[56:59]
	s_barrier
	v_mfma_f32_16x16x32_bf16 v[44:47], v[144:147], v[192:195], v[44:47]
	v_mfma_f32_16x16x32_bf16 v[40:43], v[160:163], v[192:195], v[40:43]
	v_mfma_f32_16x16x32_bf16 v[28:31], v[144:147], v[200:203], v[28:31]
	v_mfma_f32_16x16x32_bf16 v[24:27], v[160:163], v[200:203], v[24:27]
	v_mfma_f32_16x16x32_bf16 v[12:15], v[144:147], v[208:211], v[12:15]
	v_mfma_f32_16x16x32_bf16 v[8:11], v[160:163], v[208:211], v[8:11]
	v_mfma_f32_16x16x32_bf16 v[52:55], v[168:171], v[184:187], v[52:55]
	v_mfma_f32_16x16x32_bf16 v[48:51], v[176:179], v[184:187], v[48:51]
	v_mfma_f32_16x16x32_bf16 v[36:39], v[168:171], v[192:195], v[36:39]
	v_mfma_f32_16x16x32_bf16 v[32:35], v[176:179], v[192:195], v[32:35]
	v_mfma_f32_16x16x32_bf16 v[20:23], v[168:171], v[200:203], v[20:23]
	v_mfma_f32_16x16x32_bf16 v[16:19], v[176:179], v[200:203], v[16:19]
	v_mfma_f32_16x16x32_bf16 v[4:7], v[168:171], v[208:211], v[4:7]
	v_mfma_f32_16x16x32_bf16 v[0:3], v[176:179], v[208:211], v[0:3]
	v_mfma_f32_16x16x32_bf16 v[44:47], v[156:159], v[196:199], v[44:47]
	v_mfma_f32_16x16x32_bf16 v[40:43], v[164:167], v[196:199], v[40:43]
	v_mfma_f32_16x16x32_bf16 v[28:31], v[156:159], v[204:207], v[28:31]
	v_mfma_f32_16x16x32_bf16 v[24:27], v[164:167], v[204:207], v[24:27]
	v_mfma_f32_16x16x32_bf16 v[12:15], v[156:159], v[212:215], v[12:15]
	v_mfma_f32_16x16x32_bf16 v[8:11], v[164:167], v[212:215], v[8:11]
	v_mfma_f32_16x16x32_bf16 v[52:55], v[172:175], v[188:191], v[52:55]
	v_mfma_f32_16x16x32_bf16 v[48:51], v[180:183], v[188:191], v[48:51]
	v_mfma_f32_16x16x32_bf16 v[36:39], v[172:175], v[196:199], v[36:39]
	v_mfma_f32_16x16x32_bf16 v[32:35], v[180:183], v[196:199], v[32:35]
	v_mfma_f32_16x16x32_bf16 v[20:23], v[172:175], v[204:207], v[20:23]
	v_mfma_f32_16x16x32_bf16 v[16:19], v[180:183], v[204:207], v[16:19]
	v_mfma_f32_16x16x32_bf16 v[4:7], v[172:175], v[212:215], v[4:7]
	v_mfma_f32_16x16x32_bf16 v[0:3], v[180:183], v[212:215], v[0:3]
	s_barrier
	s_add_i32 s53, 0, 0x18000
	v_add_u32_e32 v155, s53, v149
	s_add_i32 s55, 0, 0x1c000
	ds_read_b128 v[144:147], v155
	ds_read_b128 v[156:159], v155 offset:1024
	ds_read_b128 v[160:163], v155 offset:2048
	ds_read_b128 v[164:167], v155 offset:3072
	v_add_u32_e32 v155, s55, v149
	ds_read_b128 v[168:171], v155
	ds_read_b128 v[172:175], v155 offset:1024
	ds_read_b128 v[176:179], v155 offset:2048
	ds_read_b128 v[180:183], v155 offset:3072
	s_add_u32 s22, s28, 0x160000
	s_addc_u32 s23, s29, 0
	s_mov_b32 m0, s34
	ds_read_b128 v[184:187], v153 offset:32768
	ds_read_b128 v[188:191], v153 offset:33792
	ds_read_b128 v[192:195], v153 offset:34816
	ds_read_b128 v[196:199], v153 offset:35840
	ds_read_b128 v[200:203], v153 offset:36864
	ds_read_b128 v[204:207], v153 offset:37888
	ds_read_b128 v[208:211], v153 offset:38912
	ds_read_b128 v[212:215], v153 offset:39936
	global_load_lds_dwordx4 v128, s[22:23]
	s_mov_b32 m0, s35
	s_nop 0
	global_load_lds_dwordx4 v132, s[22:23]
	s_waitcnt vmcnt(8)
	s_waitcnt lgkmcnt(0)
	s_waitcnt lgkmcnt(0)
	v_mfma_f32_16x16x32_bf16 v[124:127], v[144:147], v[184:187], v[124:127]
	v_mfma_f32_16x16x32_bf16 v[120:123], v[160:163], v[184:187], v[120:123]
	v_mfma_f32_16x16x32_bf16 v[124:127], v[156:159], v[188:191], v[124:127]
	v_mfma_f32_16x16x32_bf16 v[120:123], v[164:167], v[188:191], v[120:123]
	s_barrier
	v_mfma_f32_16x16x32_bf16 v[108:111], v[144:147], v[192:195], v[108:111]
	v_mfma_f32_16x16x32_bf16 v[104:107], v[160:163], v[192:195], v[104:107]
	v_mfma_f32_16x16x32_bf16 v[92:95], v[144:147], v[200:203], v[92:95]
	v_mfma_f32_16x16x32_bf16 v[88:91], v[160:163], v[200:203], v[88:91]
	v_mfma_f32_16x16x32_bf16 v[76:79], v[144:147], v[208:211], v[76:79]
	v_mfma_f32_16x16x32_bf16 v[72:75], v[160:163], v[208:211], v[72:75]
	v_mfma_f32_16x16x32_bf16 v[116:119], v[168:171], v[184:187], v[116:119]
	v_mfma_f32_16x16x32_bf16 v[112:115], v[176:179], v[184:187], v[112:115]
	v_mfma_f32_16x16x32_bf16 v[100:103], v[168:171], v[192:195], v[100:103]
	v_mfma_f32_16x16x32_bf16 v[96:99], v[176:179], v[192:195], v[96:99]
	v_mfma_f32_16x16x32_bf16 v[84:87], v[168:171], v[200:203], v[84:87]
	v_mfma_f32_16x16x32_bf16 v[80:83], v[176:179], v[200:203], v[80:83]
	v_mfma_f32_16x16x32_bf16 v[68:71], v[168:171], v[208:211], v[68:71]
	v_mfma_f32_16x16x32_bf16 v[64:67], v[176:179], v[208:211], v[64:67]
	v_mfma_f32_16x16x32_bf16 v[108:111], v[156:159], v[196:199], v[108:111]
	v_mfma_f32_16x16x32_bf16 v[104:107], v[164:167], v[196:199], v[104:107]
	v_mfma_f32_16x16x32_bf16 v[92:95], v[156:159], v[204:207], v[92:95]
	v_mfma_f32_16x16x32_bf16 v[88:91], v[164:167], v[204:207], v[88:91]
	v_mfma_f32_16x16x32_bf16 v[76:79], v[156:159], v[212:215], v[76:79]
	v_mfma_f32_16x16x32_bf16 v[72:75], v[164:167], v[212:215], v[72:75]
	v_mfma_f32_16x16x32_bf16 v[116:119], v[172:175], v[188:191], v[116:119]
	v_mfma_f32_16x16x32_bf16 v[112:115], v[180:183], v[188:191], v[112:115]
	v_mfma_f32_16x16x32_bf16 v[100:103], v[172:175], v[196:199], v[100:103]
	v_mfma_f32_16x16x32_bf16 v[96:99], v[180:183], v[196:199], v[96:99]
	v_mfma_f32_16x16x32_bf16 v[84:87], v[172:175], v[204:207], v[84:87]
	v_mfma_f32_16x16x32_bf16 v[80:83], v[180:183], v[204:207], v[80:83]
	v_mfma_f32_16x16x32_bf16 v[68:71], v[172:175], v[212:215], v[68:71]
	v_mfma_f32_16x16x32_bf16 v[64:67], v[180:183], v[212:215], v[64:67]
	s_barrier
	s_add_i32 s22, s53, s30
	v_lshl_add_u64 v[216:217], v[216:217], 0, s[12:13]
	s_mov_b32 m0, s22
	ds_read_b128 v[184:187], v153 offset:49152
	ds_read_b128 v[188:191], v153 offset:50176
	ds_read_b128 v[192:195], v153 offset:51200
	ds_read_b128 v[196:199], v153 offset:52224
	ds_read_b128 v[200:203], v153 offset:53248
	ds_read_b128 v[204:207], v153 offset:54272
	ds_read_b128 v[208:211], v153 offset:55296
	ds_read_b128 v[212:215], v153 offset:56320
	global_load_lds_dwordx4 v[216:217], off
	s_add_i32 m0, s22, 0x2000
	s_add_u32 s22, s26, 0x160080
	v_lshl_add_u64 v[216:217], v[218:219], 0, s[12:13]
	s_addc_u32 s23, s27, 0
	s_add_i32 s26, s55, s30
	global_load_lds_dwordx4 v[216:217], off
	s_mov_b32 m0, s26
	s_nop 0
	global_load_lds_dwordx4 v130, s[22:23]
	s_add_i32 m0, s26, 0x2000
	s_nop 0
	global_load_lds_dwordx4 v134, s[22:23]
	v_lshl_add_u64 v[216:217], v[222:223], 0, s[12:13]
	s_mov_b32 m0, s37
	s_nop 0
	global_load_lds_dwordx4 v[216:217], off
	v_lshl_add_u64 v[216:217], v[224:225], 0, s[12:13]
	s_mov_b32 m0, s38
	s_nop 0
	global_load_lds_dwordx4 v[216:217], off
	s_waitcnt vmcnt(8)
	s_waitcnt lgkmcnt(0)
	s_waitcnt lgkmcnt(0)
	v_mfma_f32_16x16x32_bf16 v[60:63], v[144:147], v[184:187], v[60:63]
	v_mfma_f32_16x16x32_bf16 v[56:59], v[160:163], v[184:187], v[56:59]
	v_mfma_f32_16x16x32_bf16 v[60:63], v[156:159], v[188:191], v[60:63]
	v_mfma_f32_16x16x32_bf16 v[56:59], v[164:167], v[188:191], v[56:59]
	s_barrier
	v_mfma_f32_16x16x32_bf16 v[44:47], v[144:147], v[192:195], v[44:47]
	v_mfma_f32_16x16x32_bf16 v[40:43], v[160:163], v[192:195], v[40:43]
	v_mfma_f32_16x16x32_bf16 v[28:31], v[144:147], v[200:203], v[28:31]
	v_mfma_f32_16x16x32_bf16 v[24:27], v[160:163], v[200:203], v[24:27]
	v_mfma_f32_16x16x32_bf16 v[12:15], v[144:147], v[208:211], v[12:15]
	v_mfma_f32_16x16x32_bf16 v[8:11], v[160:163], v[208:211], v[8:11]
	v_mfma_f32_16x16x32_bf16 v[52:55], v[168:171], v[184:187], v[52:55]
	v_mfma_f32_16x16x32_bf16 v[48:51], v[176:179], v[184:187], v[48:51]
	v_mfma_f32_16x16x32_bf16 v[36:39], v[168:171], v[192:195], v[36:39]
	v_mfma_f32_16x16x32_bf16 v[32:35], v[176:179], v[192:195], v[32:35]
	v_mfma_f32_16x16x32_bf16 v[20:23], v[168:171], v[200:203], v[20:23]
	v_mfma_f32_16x16x32_bf16 v[16:19], v[176:179], v[200:203], v[16:19]
	v_mfma_f32_16x16x32_bf16 v[4:7], v[168:171], v[208:211], v[4:7]
	v_mfma_f32_16x16x32_bf16 v[0:3], v[176:179], v[208:211], v[0:3]
	v_mfma_f32_16x16x32_bf16 v[44:47], v[156:159], v[196:199], v[44:47]
	v_mfma_f32_16x16x32_bf16 v[40:43], v[164:167], v[196:199], v[40:43]
	v_mfma_f32_16x16x32_bf16 v[28:31], v[156:159], v[204:207], v[28:31]
	v_mfma_f32_16x16x32_bf16 v[24:27], v[164:167], v[204:207], v[24:27]
	v_mfma_f32_16x16x32_bf16 v[12:15], v[156:159], v[212:215], v[12:15]
	v_mfma_f32_16x16x32_bf16 v[8:11], v[164:167], v[212:215], v[8:11]
	v_mfma_f32_16x16x32_bf16 v[52:55], v[172:175], v[188:191], v[52:55]
	v_mfma_f32_16x16x32_bf16 v[48:51], v[180:183], v[188:191], v[48:51]
	v_mfma_f32_16x16x32_bf16 v[36:39], v[172:175], v[196:199], v[36:39]
	v_mfma_f32_16x16x32_bf16 v[32:35], v[180:183], v[196:199], v[32:35]
	v_mfma_f32_16x16x32_bf16 v[20:23], v[172:175], v[204:207], v[20:23]
	v_mfma_f32_16x16x32_bf16 v[16:19], v[180:183], v[204:207], v[16:19]
	v_mfma_f32_16x16x32_bf16 v[4:7], v[172:175], v[212:215], v[4:7]
	v_mfma_f32_16x16x32_bf16 v[0:3], v[180:183], v[212:215], v[0:3]
	s_barrier
	s_add_i32 s51, s51, 2
	s_add_u32 s48, s48, 0x100
	s_addc_u32 s49, s49, 0
	s_cmpk_gt_u32 s51, 0x55
	s_mov_b64 s[22:23], s[24:25]
	s_cbranch_scc0 .LBB0_237
	s_and_b64 vcc, exec, s[18:19]
	s_cbranch_vccz .LBB0_240
	s_barrier

.LBB0_331:
	v_add_u32_e32 v161, s43, v149
	ds_read_b128 v[162:165], v161
	ds_read_b128 v[166:169], v161 offset:1024
	ds_read_b128 v[170:173], v161 offset:2048
	ds_read_b128 v[174:177], v161 offset:3072
	v_add_u32_e32 v161, s44, v149
	ds_read_b128 v[178:181], v161
	ds_read_b128 v[182:185], v161 offset:1024
	ds_read_b128 v[186:189], v161 offset:2048
	ds_read_b128 v[190:193], v161 offset:3072
	s_add_u32 s34, s8, 0xfff80080
	s_addc_u32 s35, s9, -1
	s_and_b64 s[30:31], s[30:31], exec
	s_cselect_b32 s35, s23, s35
	s_cselect_b32 s34, s46, s34
	s_cselect_b32 s31, s21, s49
	s_cselect_b32 s30, s47, s48
	s_add_i32 m0, s3, 0xc000
	ds_read_b128 v[194:197], v151
	ds_read_b128 v[198:201], v151 offset:1024
	ds_read_b128 v[202:205], v151 offset:2048
	ds_read_b128 v[206:209], v151 offset:3072
	ds_read_b128 v[210:213], v151 offset:4096
	ds_read_b128 v[214:217], v151 offset:5120
	ds_read_b128 v[222:225], v151 offset:6144
	ds_read_b128 v[226:229], v151 offset:7168
	global_load_lds_dwordx4 v136, s[8:9]
	s_add_i32 m0, s3, 0xe000
	s_nop 0
	global_load_lds_dwordx4 v138, s[8:9]
	s_waitcnt vmcnt(8)
	s_waitcnt lgkmcnt(0)
	s_waitcnt lgkmcnt(0)
	v_mfma_f32_16x16x32_bf16 v[124:127], v[162:165], v[194:197], v[124:127]
	v_mfma_f32_16x16x32_bf16 v[120:123], v[170:173], v[194:197], v[120:123]
	v_mfma_f32_16x16x32_bf16 v[124:127], v[166:169], v[198:201], v[124:127]
	v_mfma_f32_16x16x32_bf16 v[120:123], v[174:177], v[198:201], v[120:123]
	s_barrier
	v_mfma_f32_16x16x32_bf16 v[108:111], v[162:165], v[202:205], v[108:111]
	v_mfma_f32_16x16x32_bf16 v[104:107], v[170:173], v[202:205], v[104:107]
	v_mfma_f32_16x16x32_bf16 v[92:95], v[162:165], v[210:213], v[92:95]
	v_mfma_f32_16x16x32_bf16 v[88:91], v[170:173], v[210:213], v[88:91]
	v_mfma_f32_16x16x32_bf16 v[76:79], v[162:165], v[222:225], v[76:79]
	v_mfma_f32_16x16x32_bf16 v[72:75], v[170:173], v[222:225], v[72:75]
	v_mfma_f32_16x16x32_bf16 v[116:119], v[178:181], v[194:197], v[116:119]
	v_mfma_f32_16x16x32_bf16 v[112:115], v[186:189], v[194:197], v[112:115]
	v_mfma_f32_16x16x32_bf16 v[100:103], v[178:181], v[202:205], v[100:103]
	v_mfma_f32_16x16x32_bf16 v[96:99], v[186:189], v[202:205], v[96:99]
	v_mfma_f32_16x16x32_bf16 v[84:87], v[178:181], v[210:213], v[84:87]
	v_mfma_f32_16x16x32_bf16 v[80:83], v[186:189], v[210:213], v[80:83]
	v_mfma_f32_16x16x32_bf16 v[68:71], v[178:181], v[222:225], v[68:71]
	v_mfma_f32_16x16x32_bf16 v[64:67], v[186:189], v[222:225], v[64:67]
	v_mfma_f32_16x16x32_bf16 v[108:111], v[166:169], v[206:209], v[108:111]
	v_mfma_f32_16x16x32_bf16 v[104:107], v[174:177], v[206:209], v[104:107]
	v_mfma_f32_16x16x32_bf16 v[92:95], v[166:169], v[214:217], v[92:95]
	v_mfma_f32_16x16x32_bf16 v[88:91], v[174:177], v[214:217], v[88:91]
	v_mfma_f32_16x16x32_bf16 v[76:79], v[166:169], v[226:229], v[76:79]
	v_mfma_f32_16x16x32_bf16 v[72:75], v[174:177], v[226:229], v[72:75]
	v_mfma_f32_16x16x32_bf16 v[116:119], v[182:185], v[198:201], v[116:119]
	v_mfma_f32_16x16x32_bf16 v[112:115], v[190:193], v[198:201], v[112:115]
	v_mfma_f32_16x16x32_bf16 v[100:103], v[182:185], v[206:209], v[100:103]
	v_mfma_f32_16x16x32_bf16 v[96:99], v[190:193], v[206:209], v[96:99]
	v_mfma_f32_16x16x32_bf16 v[84:87], v[182:185], v[214:217], v[84:87]
	v_mfma_f32_16x16x32_bf16 v[80:83], v[190:193], v[214:217], v[80:83]
	v_mfma_f32_16x16x32_bf16 v[68:71], v[182:185], v[226:229], v[68:71]
	v_mfma_f32_16x16x32_bf16 v[64:67], v[190:193], v[226:229], v[64:67]
	s_barrier
	s_add_i32 s53, s43, s2
	v_lshl_add_u64 v[218:219], s[30:31], 0, v[130:131]
	s_mov_b32 m0, s53
	ds_read_b128 v[194:197], v151 offset:16384
	ds_read_b128 v[198:201], v151 offset:17408
	ds_read_b128 v[202:205], v151 offset:18432
	ds_read_b128 v[206:209], v151 offset:19456
	ds_read_b128 v[210:213], v151 offset:20480
	ds_read_b128 v[214:217], v151 offset:21504
	ds_read_b128 v[222:225], v151 offset:22528
	ds_read_b128 v[226:229], v151 offset:23552
	global_load_lds_dwordx4 v[218:219], off
	s_add_i32 m0, s53, 0x2000
	s_add_u32 s56, s30, 0x80000
	v_lshl_add_u64 v[230:231], s[30:31], 0, v[134:135]
	s_addc_u32 s57, s31, 0
	s_add_i32 s53, s44, s2
	global_load_lds_dwordx4 v[230:231], off
	s_mov_b32 m0, s53
	v_lshl_add_u64 v[234:235], s[34:35], 0, v[132:133]
	global_load_lds_dwordx4 v130, s[56:57]
	s_add_i32 m0, s53, 0x2000
	s_nop 0
	global_load_lds_dwordx4 v134, s[56:57]
	v_lshl_add_u64 v[232:233], s[34:35], 0, v[128:129]
	s_mov_b32 m0, s3
	s_nop 0
	global_load_lds_dwordx4 v[232:233], off
	s_mov_b32 m0, s29
	s_nop 0
	global_load_lds_dwordx4 v[234:235], off
	s_waitcnt vmcnt(8)
	s_waitcnt lgkmcnt(0)
	s_waitcnt lgkmcnt(0)
	v_mfma_f32_16x16x32_bf16 v[60:63], v[162:165], v[194:197], v[60:63]
	v_mfma_f32_16x16x32_bf16 v[56:59], v[170:173], v[194:197], v[56:59]
	v_mfma_f32_16x16x32_bf16 v[60:63], v[166:169], v[198:201], v[60:63]
	v_mfma_f32_16x16x32_bf16 v[56:59], v[174:177], v[198:201], v[56:59]
	s_barrier
	v_mfma_f32_16x16x32_bf16 v[44:47], v[162:165], v[202:205], v[44:47]
	v_mfma_f32_16x16x32_bf16 v[40:43], v[170:173], v[202:205], v[40:43]
	v_mfma_f32_16x16x32_bf16 v[28:31], v[162:165], v[210:213], v[28:31]
	v_mfma_f32_16x16x32_bf16 v[24:27], v[170:173], v[210:213], v[24:27]
	v_mfma_f32_16x16x32_bf16 v[12:15], v[162:165], v[222:225], v[12:15]
	v_mfma_f32_16x16x32_bf16 v[8:11], v[170:173], v[222:225], v[8:11]
	v_mfma_f32_16x16x32_bf16 v[52:55], v[178:181], v[194:197], v[52:55]
	v_mfma_f32_16x16x32_bf16 v[48:51], v[186:189], v[194:197], v[48:51]
	v_mfma_f32_16x16x32_bf16 v[36:39], v[178:181], v[202:205], v[36:39]
	v_mfma_f32_16x16x32_bf16 v[32:35], v[186:189], v[202:205], v[32:35]
	v_mfma_f32_16x16x32_bf16 v[20:23], v[178:181], v[210:213], v[20:23]
	v_mfma_f32_16x16x32_bf16 v[16:19], v[186:189], v[210:213], v[16:19]
	v_mfma_f32_16x16x32_bf16 v[4:7], v[178:181], v[222:225], v[4:7]
	v_mfma_f32_16x16x32_bf16 v[0:3], v[186:189], v[222:225], v[0:3]
	v_mfma_f32_16x16x32_bf16 v[44:47], v[166:169], v[206:209], v[44:47]
	v_mfma_f32_16x16x32_bf16 v[40:43], v[174:177], v[206:209], v[40:43]
	v_mfma_f32_16x16x32_bf16 v[28:31], v[166:169], v[214:217], v[28:31]
	v_mfma_f32_16x16x32_bf16 v[24:27], v[174:177], v[214:217], v[24:27]
	v_mfma_f32_16x16x32_bf16 v[12:15], v[166:169], v[226:229], v[12:15]
	v_mfma_f32_16x16x32_bf16 v[8:11], v[174:177], v[226:229], v[8:11]
	v_mfma_f32_16x16x32_bf16 v[52:55], v[182:185], v[198:201], v[52:55]
	v_mfma_f32_16x16x32_bf16 v[48:51], v[190:193], v[198:201], v[48:51]
	v_mfma_f32_16x16x32_bf16 v[36:39], v[182:185], v[206:209], v[36:39]
	v_mfma_f32_16x16x32_bf16 v[32:35], v[190:193], v[206:209], v[32:35]
	v_mfma_f32_16x16x32_bf16 v[20:23], v[182:185], v[214:217], v[20:23]
	v_mfma_f32_16x16x32_bf16 v[16:19], v[190:193], v[214:217], v[16:19]
	v_mfma_f32_16x16x32_bf16 v[4:7], v[182:185], v[226:229], v[4:7]
	v_mfma_f32_16x16x32_bf16 v[0:3], v[190:193], v[226:229], v[0:3]
	s_barrier
	s_add_i32 s53, 0, 0x18000
	v_add_u32_e32 v161, s53, v149
	s_add_i32 s55, 0, 0x1c000
	ds_read_b128 v[162:165], v161
	ds_read_b128 v[166:169], v161 offset:1024
	ds_read_b128 v[170:173], v161 offset:2048
	ds_read_b128 v[174:177], v161 offset:3072
	v_add_u32_e32 v161, s55, v149
	ds_read_b128 v[178:181], v161
	ds_read_b128 v[182:185], v161 offset:1024
	ds_read_b128 v[186:189], v161 offset:2048
	ds_read_b128 v[190:193], v161 offset:3072
	s_add_u32 s34, s34, 0x80000
	s_addc_u32 s35, s35, 0
	s_mov_b32 m0, s33
	ds_read_b128 v[194:197], v151 offset:32768
	ds_read_b128 v[198:201], v151 offset:33792
	ds_read_b128 v[202:205], v151 offset:34816
	ds_read_b128 v[206:209], v151 offset:35840
	ds_read_b128 v[210:213], v151 offset:36864
	ds_read_b128 v[214:217], v151 offset:37888
	ds_read_b128 v[222:225], v151 offset:38912
	ds_read_b128 v[226:229], v151 offset:39936
	global_load_lds_dwordx4 v128, s[34:35]
	s_mov_b32 m0, s36
	s_nop 0
	global_load_lds_dwordx4 v132, s[34:35]
	s_waitcnt vmcnt(8)
	s_waitcnt lgkmcnt(0)
	s_waitcnt lgkmcnt(0)
	v_mfma_f32_16x16x32_bf16 v[124:127], v[162:165], v[194:197], v[124:127]
	v_mfma_f32_16x16x32_bf16 v[120:123], v[170:173], v[194:197], v[120:123]
	v_mfma_f32_16x16x32_bf16 v[124:127], v[166:169], v[198:201], v[124:127]
	v_mfma_f32_16x16x32_bf16 v[120:123], v[174:177], v[198:201], v[120:123]
	s_barrier
	v_mfma_f32_16x16x32_bf16 v[108:111], v[162:165], v[202:205], v[108:111]
	v_mfma_f32_16x16x32_bf16 v[104:107], v[170:173], v[202:205], v[104:107]
	v_mfma_f32_16x16x32_bf16 v[92:95], v[162:165], v[210:213], v[92:95]
	v_mfma_f32_16x16x32_bf16 v[88:91], v[170:173], v[210:213], v[88:91]
	v_mfma_f32_16x16x32_bf16 v[76:79], v[162:165], v[222:225], v[76:79]
	v_mfma_f32_16x16x32_bf16 v[72:75], v[170:173], v[222:225], v[72:75]
	v_mfma_f32_16x16x32_bf16 v[116:119], v[178:181], v[194:197], v[116:119]
	v_mfma_f32_16x16x32_bf16 v[112:115], v[186:189], v[194:197], v[112:115]
	v_mfma_f32_16x16x32_bf16 v[100:103], v[178:181], v[202:205], v[100:103]
	v_mfma_f32_16x16x32_bf16 v[96:99], v[186:189], v[202:205], v[96:99]
	v_mfma_f32_16x16x32_bf16 v[84:87], v[178:181], v[210:213], v[84:87]
	v_mfma_f32_16x16x32_bf16 v[80:83], v[186:189], v[210:213], v[80:83]
	v_mfma_f32_16x16x32_bf16 v[68:71], v[178:181], v[222:225], v[68:71]
	v_mfma_f32_16x16x32_bf16 v[64:67], v[186:189], v[222:225], v[64:67]
	v_mfma_f32_16x16x32_bf16 v[108:111], v[166:169], v[206:209], v[108:111]
	v_mfma_f32_16x16x32_bf16 v[104:107], v[174:177], v[206:209], v[104:107]
	v_mfma_f32_16x16x32_bf16 v[92:95], v[166:169], v[214:217], v[92:95]
	v_mfma_f32_16x16x32_bf16 v[88:91], v[174:177], v[214:217], v[88:91]
	v_mfma_f32_16x16x32_bf16 v[76:79], v[166:169], v[226:229], v[76:79]
	v_mfma_f32_16x16x32_bf16 v[72:75], v[174:177], v[226:229], v[72:75]
	v_mfma_f32_16x16x32_bf16 v[116:119], v[182:185], v[198:201], v[116:119]
	v_mfma_f32_16x16x32_bf16 v[112:115], v[190:193], v[198:201], v[112:115]
	v_mfma_f32_16x16x32_bf16 v[100:103], v[182:185], v[206:209], v[100:103]
	v_mfma_f32_16x16x32_bf16 v[96:99], v[190:193], v[206:209], v[96:99]
	v_mfma_f32_16x16x32_bf16 v[84:87], v[182:185], v[214:217], v[84:87]
	v_mfma_f32_16x16x32_bf16 v[80:83], v[190:193], v[214:217], v[80:83]
	v_mfma_f32_16x16x32_bf16 v[68:71], v[182:185], v[226:229], v[68:71]
	v_mfma_f32_16x16x32_bf16 v[64:67], v[190:193], v[226:229], v[64:67]
	s_barrier
	s_add_i32 s34, s53, s2
	v_lshl_add_u64 v[218:219], v[218:219], 0, s[12:13]
	s_mov_b32 m0, s34
	ds_read_b128 v[194:197], v151 offset:49152
	ds_read_b128 v[198:201], v151 offset:50176
	ds_read_b128 v[202:205], v151 offset:51200
	ds_read_b128 v[206:209], v151 offset:52224
	ds_read_b128 v[210:213], v151 offset:53248
	ds_read_b128 v[214:217], v151 offset:54272
	ds_read_b128 v[222:225], v151 offset:55296
	ds_read_b128 v[226:229], v151 offset:56320
	global_load_lds_dwordx4 v[218:219], off
	s_add_i32 m0, s34, 0x2000
	s_add_u32 s30, s30, 0x80080
	v_lshl_add_u64 v[218:219], v[230:231], 0, s[12:13]
	s_addc_u32 s31, s31, 0
	s_add_i32 s34, s55, s2
	global_load_lds_dwordx4 v[218:219], off
	s_mov_b32 m0, s34
	s_nop 0
	global_load_lds_dwordx4 v130, s[30:31]
	s_add_i32 m0, s34, 0x2000
	s_nop 0
	global_load_lds_dwordx4 v134, s[30:31]
	v_lshl_add_u64 v[218:219], v[232:233], 0, s[12:13]
	s_mov_b32 m0, s38
	s_nop 0
	global_load_lds_dwordx4 v[218:219], off
	v_lshl_add_u64 v[218:219], v[234:235], 0, s[12:13]
	s_mov_b32 m0, s39
	s_nop 0
	global_load_lds_dwordx4 v[218:219], off
	s_waitcnt vmcnt(8)
	s_waitcnt lgkmcnt(0)
	s_waitcnt lgkmcnt(0)
	v_mfma_f32_16x16x32_bf16 v[60:63], v[162:165], v[194:197], v[60:63]
	v_mfma_f32_16x16x32_bf16 v[56:59], v[170:173], v[194:197], v[56:59]
	v_mfma_f32_16x16x32_bf16 v[60:63], v[166:169], v[198:201], v[60:63]
	v_mfma_f32_16x16x32_bf16 v[56:59], v[174:177], v[198:201], v[56:59]
	s_barrier
	v_mfma_f32_16x16x32_bf16 v[44:47], v[162:165], v[202:205], v[44:47]
	v_mfma_f32_16x16x32_bf16 v[40:43], v[170:173], v[202:205], v[40:43]
	v_mfma_f32_16x16x32_bf16 v[28:31], v[162:165], v[210:213], v[28:31]
	v_mfma_f32_16x16x32_bf16 v[24:27], v[170:173], v[210:213], v[24:27]
	v_mfma_f32_16x16x32_bf16 v[12:15], v[162:165], v[222:225], v[12:15]
	v_mfma_f32_16x16x32_bf16 v[8:11], v[170:173], v[222:225], v[8:11]
	v_mfma_f32_16x16x32_bf16 v[52:55], v[178:181], v[194:197], v[52:55]
	v_mfma_f32_16x16x32_bf16 v[48:51], v[186:189], v[194:197], v[48:51]
	v_mfma_f32_16x16x32_bf16 v[36:39], v[178:181], v[202:205], v[36:39]
	v_mfma_f32_16x16x32_bf16 v[32:35], v[186:189], v[202:205], v[32:35]
	v_mfma_f32_16x16x32_bf16 v[20:23], v[178:181], v[210:213], v[20:23]
	v_mfma_f32_16x16x32_bf16 v[16:19], v[186:189], v[210:213], v[16:19]
	v_mfma_f32_16x16x32_bf16 v[4:7], v[178:181], v[222:225], v[4:7]
	v_mfma_f32_16x16x32_bf16 v[0:3], v[186:189], v[222:225], v[0:3]
	v_mfma_f32_16x16x32_bf16 v[44:47], v[166:169], v[206:209], v[44:47]
	v_mfma_f32_16x16x32_bf16 v[40:43], v[174:177], v[206:209], v[40:43]
	v_mfma_f32_16x16x32_bf16 v[28:31], v[166:169], v[214:217], v[28:31]
	v_mfma_f32_16x16x32_bf16 v[24:27], v[174:177], v[214:217], v[24:27]
	v_mfma_f32_16x16x32_bf16 v[12:15], v[166:169], v[226:229], v[12:15]
	v_mfma_f32_16x16x32_bf16 v[8:11], v[174:177], v[226:229], v[8:11]
	v_mfma_f32_16x16x32_bf16 v[52:55], v[182:185], v[198:201], v[52:55]
	v_mfma_f32_16x16x32_bf16 v[48:51], v[190:193], v[198:201], v[48:51]
	v_mfma_f32_16x16x32_bf16 v[36:39], v[182:185], v[206:209], v[36:39]
	v_mfma_f32_16x16x32_bf16 v[32:35], v[190:193], v[206:209], v[32:35]
	v_mfma_f32_16x16x32_bf16 v[20:23], v[182:185], v[214:217], v[20:23]
	v_mfma_f32_16x16x32_bf16 v[16:19], v[190:193], v[214:217], v[16:19]
	v_mfma_f32_16x16x32_bf16 v[4:7], v[182:185], v[226:229], v[4:7]
	v_mfma_f32_16x16x32_bf16 v[0:3], v[190:193], v[226:229], v[0:3]
	s_barrier
	s_add_i32 s51, s51, 2
	s_add_u32 s8, s8, 0x100
	s_addc_u32 s9, s9, 0
	s_add_u32 s48, s48, 0x100
	s_addc_u32 s49, s49, 0
	s_cmp_gt_u32 s51, 29
	s_cbranch_scc1 .LBB0_334

.LBB0_657:
	s_ashr_i32 s25, s24, 31
	s_lshl_b64 s[28:29], s[24:25], 20
	s_add_u32 s25, s0, s28
	ds_read_b128 v[0:3], v143
	ds_read_b128 v[4:7], v143 offset:1024
	ds_read_b128 v[8:11], v143 offset:2048
	ds_read_b128 v[12:15], v143 offset:3072
	ds_read_b128 v[16:19], v144
	ds_read_b128 v[20:23], v144 offset:1024
	ds_read_b128 v[24:27], v144 offset:2048
	ds_read_b128 v[28:31], v144 offset:3072
	s_addc_u32 s27, s1, s29
	s_lshl_b32 s28, s26, 9
	s_and_b32 s28, s28, 0xe00
	s_add_u32 s28, s25, s28
	s_addc_u32 s29, s27, 0
	s_and_b64 s[30:31], s[40:41], exec
	s_cselect_b32 s43, s29, s39
	s_cselect_b32 s42, s28, s38
	s_ashr_i32 s27, s26, 31
	s_lshl_b64 s[30:31], s[26:27], 17
	s_add_u32 s30, s10, s30
	s_addc_u32 s31, s11, s31
	s_and_b64 s[40:41], s[40:41], exec
	s_cselect_b32 s41, s31, s9
	s_cselect_b32 s40, s30, s8
	s_add_u32 s64, s38, 0x80080
	s_addc_u32 s65, s39, 0
	s_mov_b32 m0, s48
	v_lshl_add_u64 v[64:65], s[64:65], 0, v[130:131]
	ds_read_b128 v[32:35], v145
	ds_read_b128 v[36:39], v145 offset:1024
	ds_read_b128 v[40:43], v145 offset:2048
	ds_read_b128 v[44:47], v145 offset:3072
	ds_read_b128 v[48:51], v145 offset:4096
	ds_read_b128 v[52:55], v145 offset:5120
	ds_read_b128 v[56:59], v145 offset:6144
	ds_read_b128 v[60:63], v145 offset:7168
	global_load_lds_dwordx4 v[64:65], off
	v_lshl_add_u64 v[64:65], s[64:65], 0, v[132:133]
	s_mov_b32 m0, s49
	s_nop 0
	global_load_lds_dwordx4 v[64:65], off
	s_waitcnt vmcnt(8)
	s_waitcnt lgkmcnt(0)
	s_waitcnt lgkmcnt(0)
	v_mfma_f32_16x16x32_bf16 v[64:67], v[0:3], v[32:35], 0
	v_mfma_f32_16x16x32_bf16 v[68:71], v[8:11], v[32:35], 0
	v_mfma_f32_16x16x32_bf16 v[64:67], v[4:7], v[36:39], v[64:67]
	v_mfma_f32_16x16x32_bf16 v[68:71], v[12:15], v[36:39], v[68:71]
	s_barrier
	v_mfma_f32_16x16x32_bf16 v[96:99], v[16:19], v[32:35], 0
	v_mfma_f32_16x16x32_bf16 v[32:35], v[24:27], v[32:35], 0
	v_mfma_f32_16x16x32_bf16 v[72:75], v[0:3], v[40:43], 0
	v_mfma_f32_16x16x32_bf16 v[76:79], v[8:11], v[40:43], 0
	v_mfma_f32_16x16x32_bf16 v[96:99], v[20:23], v[36:39], v[96:99]
	v_mfma_f32_16x16x32_bf16 v[32:35], v[28:31], v[36:39], v[32:35]
	v_mfma_f32_16x16x32_bf16 v[36:39], v[16:19], v[40:43], 0
	v_mfma_f32_16x16x32_bf16 v[40:43], v[24:27], v[40:43], 0
	v_mfma_f32_16x16x32_bf16 v[80:83], v[0:3], v[48:51], 0
	v_mfma_f32_16x16x32_bf16 v[84:87], v[8:11], v[48:51], 0
	v_mfma_f32_16x16x32_bf16 v[72:75], v[4:7], v[44:47], v[72:75]
	v_mfma_f32_16x16x32_bf16 v[76:79], v[12:15], v[44:47], v[76:79]
	v_mfma_f32_16x16x32_bf16 v[36:39], v[20:23], v[44:47], v[36:39]
	v_mfma_f32_16x16x32_bf16 v[40:43], v[28:31], v[44:47], v[40:43]
	v_mfma_f32_16x16x32_bf16 v[44:47], v[16:19], v[48:51], 0
	v_mfma_f32_16x16x32_bf16 v[48:51], v[24:27], v[48:51], 0
	v_mfma_f32_16x16x32_bf16 v[88:91], v[0:3], v[56:59], 0
	v_mfma_f32_16x16x32_bf16 v[92:95], v[8:11], v[56:59], 0
	v_mfma_f32_16x16x32_bf16 v[80:83], v[4:7], v[52:55], v[80:83]
	v_mfma_f32_16x16x32_bf16 v[84:87], v[12:15], v[52:55], v[84:87]
	v_mfma_f32_16x16x32_bf16 v[44:47], v[20:23], v[52:55], v[44:47]
	v_mfma_f32_16x16x32_bf16 v[48:51], v[28:31], v[52:55], v[48:51]
	v_mfma_f32_16x16x32_bf16 v[52:55], v[16:19], v[56:59], 0
	v_mfma_f32_16x16x32_bf16 v[56:59], v[24:27], v[56:59], 0
	v_mfma_f32_16x16x32_bf16 v[88:91], v[4:7], v[60:63], v[88:91]
	v_mfma_f32_16x16x32_bf16 v[92:95], v[12:15], v[60:63], v[92:95]
	v_mfma_f32_16x16x32_bf16 v[52:55], v[20:23], v[60:63], v[52:55]
	v_mfma_f32_16x16x32_bf16 v[56:59], v[28:31], v[60:63], v[56:59]
	s_barrier
	v_lshl_add_u64 v[208:209], s[8:9], 0, v[128:129]
	s_mov_b32 m0, s51
	v_lshl_add_u64 v[136:137], v[208:209], 0, s[20:21]
	v_lshl_add_u64 v[210:211], s[8:9], 0, v[134:135]
	s_add_u32 s64, s8, 0x10100
	ds_read_b128 v[60:63], v145 offset:16384
	ds_read_b128 v[100:103], v145 offset:17408
	ds_read_b128 v[104:107], v145 offset:18432
	ds_read_b128 v[108:111], v145 offset:19456
	ds_read_b128 v[112:115], v145 offset:20480
	ds_read_b128 v[116:119], v145 offset:21504
	ds_read_b128 v[120:123], v145 offset:22528
	ds_read_b128 v[124:127], v145 offset:23552
	global_load_lds_dwordx4 v[136:137], off
	v_lshl_add_u64 v[136:137], v[210:211], 0, s[20:21]
	s_mov_b32 m0, s53
	s_addc_u32 s65, s9, 0
	global_load_lds_dwordx4 v[136:137], off
	v_lshl_add_u64 v[136:137], s[64:65], 0, v[128:129]
	s_mov_b32 m0, s55
	v_lshl_add_u64 v[212:213], s[38:39], 0, v[130:131]
	global_load_lds_dwordx4 v[136:137], off
	v_lshl_add_u64 v[136:137], s[64:65], 0, v[134:135]
	s_mov_b32 m0, s56
	v_lshl_add_u64 v[214:215], s[38:39], 0, v[132:133]
	global_load_lds_dwordx4 v[136:137], off
	v_lshl_add_u64 v[136:137], v[212:213], 0, s[20:21]
	s_mov_b32 m0, s13
	s_nop 0
	global_load_lds_dwordx4 v[136:137], off
	v_lshl_add_u64 v[136:137], v[214:215], 0, s[20:21]
	s_mov_b32 m0, s35
	s_nop 0
	global_load_lds_dwordx4 v[136:137], off
	s_waitcnt vmcnt(8)
	s_waitcnt lgkmcnt(0)
	s_waitcnt lgkmcnt(0)
	v_mfma_f32_16x16x32_bf16 v[136:139], v[0:3], v[60:63], 0
	v_mfma_f32_16x16x32_bf16 v[148:151], v[8:11], v[60:63], 0
	v_mfma_f32_16x16x32_bf16 v[136:139], v[4:7], v[100:103], v[136:139]
	v_mfma_f32_16x16x32_bf16 v[148:151], v[12:15], v[100:103], v[148:151]
	s_barrier
	v_mfma_f32_16x16x32_bf16 v[152:155], v[0:3], v[104:107], 0
	v_mfma_f32_16x16x32_bf16 v[156:159], v[8:11], v[104:107], 0
	v_mfma_f32_16x16x32_bf16 v[160:163], v[0:3], v[112:115], 0
	v_mfma_f32_16x16x32_bf16 v[164:167], v[8:11], v[112:115], 0
	v_mfma_f32_16x16x32_bf16 v[0:3], v[0:3], v[120:123], 0
	v_mfma_f32_16x16x32_bf16 v[8:11], v[8:11], v[120:123], 0
	v_mfma_f32_16x16x32_bf16 v[152:155], v[4:7], v[108:111], v[152:155]
	v_mfma_f32_16x16x32_bf16 v[156:159], v[12:15], v[108:111], v[156:159]
	v_mfma_f32_16x16x32_bf16 v[160:163], v[4:7], v[116:119], v[160:163]
	v_mfma_f32_16x16x32_bf16 v[164:167], v[12:15], v[116:119], v[164:167]
	v_mfma_f32_16x16x32_bf16 v[0:3], v[4:7], v[124:127], v[0:3]
	v_mfma_f32_16x16x32_bf16 v[4:7], v[12:15], v[124:127], v[8:11]
	v_mfma_f32_16x16x32_bf16 v[8:11], v[16:19], v[60:63], 0
	v_mfma_f32_16x16x32_bf16 v[12:15], v[24:27], v[60:63], 0
	v_mfma_f32_16x16x32_bf16 v[8:11], v[20:23], v[100:103], v[8:11]
	v_mfma_f32_16x16x32_bf16 v[12:15], v[28:31], v[100:103], v[12:15]
	v_mfma_f32_16x16x32_bf16 v[60:63], v[16:19], v[104:107], 0
	v_mfma_f32_16x16x32_bf16 v[100:103], v[24:27], v[104:107], 0
	v_mfma_f32_16x16x32_bf16 v[104:107], v[16:19], v[112:115], 0
	v_mfma_f32_16x16x32_bf16 v[16:19], v[16:19], v[120:123], 0
	v_mfma_f32_16x16x32_bf16 v[60:63], v[20:23], v[108:111], v[60:63]
	v_mfma_f32_16x16x32_bf16 v[100:103], v[28:31], v[108:111], v[100:103]
	v_mfma_f32_16x16x32_bf16 v[104:107], v[20:23], v[116:119], v[104:107]
	v_mfma_f32_16x16x32_bf16 v[108:111], v[24:27], v[112:115], 0
	v_mfma_f32_16x16x32_bf16 v[16:19], v[20:23], v[124:127], v[16:19]
	v_mfma_f32_16x16x32_bf16 v[20:23], v[24:27], v[120:123], 0
	v_mfma_f32_16x16x32_bf16 v[108:111], v[28:31], v[116:119], v[108:111]
	v_mfma_f32_16x16x32_bf16 v[20:23], v[28:31], v[124:127], v[20:23]
	s_barrier
	ds_read_b128 v[24:27], v146
	ds_read_b128 v[28:31], v146 offset:1024
	ds_read_b128 v[112:115], v146 offset:2048
	ds_read_b128 v[116:119], v146 offset:3072
	ds_read_b128 v[120:123], v147
	ds_read_b128 v[124:127], v147 offset:1024
	ds_read_b128 v[168:171], v147 offset:2048
	ds_read_b128 v[172:175], v147 offset:3072
	s_add_u32 s64, s38, 0x80100
	s_addc_u32 s65, s39, 0
	s_mov_b32 m0, s37
	v_lshl_add_u64 v[216:217], s[64:65], 0, v[130:131]
	ds_read_b128 v[176:179], v145 offset:32768
	ds_read_b128 v[180:183], v145 offset:33792
	ds_read_b128 v[184:187], v145 offset:34816
	ds_read_b128 v[188:191], v145 offset:35840
	ds_read_b128 v[192:195], v145 offset:36864
	ds_read_b128 v[196:199], v145 offset:37888
	ds_read_b128 v[200:203], v145 offset:38912
	ds_read_b128 v[204:207], v145 offset:39936
	global_load_lds_dwordx4 v[216:217], off
	v_lshl_add_u64 v[216:217], s[64:65], 0, v[132:133]
	s_mov_b32 m0, s44
	s_nop 0
	global_load_lds_dwordx4 v[216:217], off
	s_waitcnt vmcnt(8)
	s_waitcnt lgkmcnt(0)
	s_waitcnt lgkmcnt(0)
	v_mfma_f32_16x16x32_bf16 v[64:67], v[24:27], v[176:179], v[64:67]
	v_mfma_f32_16x16x32_bf16 v[68:71], v[112:115], v[176:179], v[68:71]
	v_mfma_f32_16x16x32_bf16 v[64:67], v[28:31], v[180:183], v[64:67]
	v_mfma_f32_16x16x32_bf16 v[68:71], v[116:119], v[180:183], v[68:71]
	s_barrier
	v_mfma_f32_16x16x32_bf16 v[72:75], v[24:27], v[184:187], v[72:75]
	v_mfma_f32_16x16x32_bf16 v[76:79], v[112:115], v[184:187], v[76:79]
	v_mfma_f32_16x16x32_bf16 v[80:83], v[24:27], v[192:195], v[80:83]
	v_mfma_f32_16x16x32_bf16 v[84:87], v[112:115], v[192:195], v[84:87]
	v_mfma_f32_16x16x32_bf16 v[88:91], v[24:27], v[200:203], v[88:91]
	v_mfma_f32_16x16x32_bf16 v[92:95], v[112:115], v[200:203], v[92:95]
	v_mfma_f32_16x16x32_bf16 v[96:99], v[120:123], v[176:179], v[96:99]
	v_mfma_f32_16x16x32_bf16 v[32:35], v[168:171], v[176:179], v[32:35]
	v_mfma_f32_16x16x32_bf16 v[36:39], v[120:123], v[184:187], v[36:39]
	v_mfma_f32_16x16x32_bf16 v[40:43], v[168:171], v[184:187], v[40:43]
	v_mfma_f32_16x16x32_bf16 v[44:47], v[120:123], v[192:195], v[44:47]
	v_mfma_f32_16x16x32_bf16 v[48:51], v[168:171], v[192:195], v[48:51]
	v_mfma_f32_16x16x32_bf16 v[52:55], v[120:123], v[200:203], v[52:55]
	v_mfma_f32_16x16x32_bf16 v[56:59], v[168:171], v[200:203], v[56:59]
	v_mfma_f32_16x16x32_bf16 v[72:75], v[28:31], v[188:191], v[72:75]
	v_mfma_f32_16x16x32_bf16 v[76:79], v[116:119], v[188:191], v[76:79]
	v_mfma_f32_16x16x32_bf16 v[80:83], v[28:31], v[196:199], v[80:83]
	v_mfma_f32_16x16x32_bf16 v[84:87], v[116:119], v[196:199], v[84:87]
	v_mfma_f32_16x16x32_bf16 v[88:91], v[28:31], v[204:207], v[88:91]
	v_mfma_f32_16x16x32_bf16 v[92:95], v[116:119], v[204:207], v[92:95]
	v_mfma_f32_16x16x32_bf16 v[96:99], v[124:127], v[180:183], v[96:99]
	v_mfma_f32_16x16x32_bf16 v[32:35], v[172:175], v[180:183], v[32:35]
	v_mfma_f32_16x16x32_bf16 v[36:39], v[124:127], v[188:191], v[36:39]
	v_mfma_f32_16x16x32_bf16 v[40:43], v[172:175], v[188:191], v[40:43]
	v_mfma_f32_16x16x32_bf16 v[44:47], v[124:127], v[196:199], v[44:47]
	v_mfma_f32_16x16x32_bf16 v[48:51], v[172:175], v[196:199], v[48:51]
	v_mfma_f32_16x16x32_bf16 v[52:55], v[124:127], v[204:207], v[52:55]
	v_mfma_f32_16x16x32_bf16 v[56:59], v[172:175], v[204:207], v[56:59]
	s_barrier
	s_mov_b32 m0, s57
	v_lshl_add_u64 v[208:209], v[208:209], 0, s[22:23]
	s_add_u32 s8, s8, 0x10180
	ds_read_b128 v[176:179], v145 offset:49152
	ds_read_b128 v[180:183], v145 offset:50176
	ds_read_b128 v[184:187], v145 offset:51200
	ds_read_b128 v[188:191], v145 offset:52224
	ds_read_b128 v[192:195], v145 offset:53248
	ds_read_b128 v[196:199], v145 offset:54272
	ds_read_b128 v[200:203], v145 offset:55296
	ds_read_b128 v[204:207], v145 offset:56320
	global_load_lds_dwordx4 v[208:209], off
	v_lshl_add_u64 v[208:209], v[210:211], 0, s[22:23]
	s_mov_b32 m0, s59
	s_addc_u32 s9, s9, 0
	global_load_lds_dwordx4 v[208:209], off
	v_lshl_add_u64 v[208:209], s[8:9], 0, v[128:129]
	s_mov_b32 m0, s62
	s_nop 0
	global_load_lds_dwordx4 v[208:209], off
	v_lshl_add_u64 v[208:209], s[8:9], 0, v[134:135]
	s_add_i32 s8, s62, 0x2000
	s_mov_b32 m0, s8
	s_nop 0
	global_load_lds_dwordx4 v[208:209], off
	v_lshl_add_u64 v[208:209], v[212:213], 0, s[22:23]
	s_mov_b32 m0, s45
	s_nop 0
	global_load_lds_dwordx4 v[208:209], off
	v_lshl_add_u64 v[208:209], v[214:215], 0, s[22:23]
	s_mov_b32 m0, s46
	s_nop 0
	global_load_lds_dwordx4 v[208:209], off
	s_waitcnt vmcnt(8)
	s_waitcnt lgkmcnt(0)
	s_waitcnt lgkmcnt(0)
	v_mfma_f32_16x16x32_bf16 v[136:139], v[24:27], v[176:179], v[136:139]
	v_mfma_f32_16x16x32_bf16 v[148:151], v[112:115], v[176:179], v[148:151]
	v_mfma_f32_16x16x32_bf16 v[136:139], v[28:31], v[180:183], v[136:139]
	v_mfma_f32_16x16x32_bf16 v[148:151], v[116:119], v[180:183], v[148:151]
	s_barrier
	v_mfma_f32_16x16x32_bf16 v[152:155], v[24:27], v[184:187], v[152:155]
	v_mfma_f32_16x16x32_bf16 v[160:163], v[24:27], v[192:195], v[160:163]
	v_mfma_f32_16x16x32_bf16 v[0:3], v[24:27], v[200:203], v[0:3]
	v_mfma_f32_16x16x32_bf16 v[156:159], v[112:115], v[184:187], v[156:159]
	v_mfma_f32_16x16x32_bf16 v[4:7], v[112:115], v[200:203], v[4:7]
	v_mfma_f32_16x16x32_bf16 v[24:27], v[28:31], v[188:191], v[152:155]
	v_mfma_f32_16x16x32_bf16 v[152:155], v[28:31], v[196:199], v[160:163]
	v_mfma_f32_16x16x32_bf16 v[0:3], v[28:31], v[204:207], v[0:3]
	v_mfma_f32_16x16x32_bf16 v[8:11], v[120:123], v[176:179], v[8:11]
	v_mfma_f32_16x16x32_bf16 v[12:15], v[168:171], v[176:179], v[12:15]
	v_mfma_f32_16x16x32_bf16 v[28:31], v[120:123], v[184:187], v[60:63]
	v_mfma_f32_16x16x32_bf16 v[60:63], v[168:171], v[184:187], v[100:103]
	v_mfma_f32_16x16x32_bf16 v[100:103], v[120:123], v[192:195], v[104:107]
	v_mfma_f32_16x16x32_bf16 v[104:107], v[168:171], v[192:195], v[108:111]
	v_mfma_f32_16x16x32_bf16 v[16:19], v[120:123], v[200:203], v[16:19]
	v_mfma_f32_16x16x32_bf16 v[20:23], v[168:171], v[200:203], v[20:23]
	v_mfma_f32_16x16x32_bf16 v[164:167], v[112:115], v[192:195], v[164:167]
	v_mfma_f32_16x16x32_bf16 v[112:115], v[116:119], v[188:191], v[156:159]
	v_mfma_f32_16x16x32_bf16 v[4:7], v[116:119], v[204:207], v[4:7]
	v_mfma_f32_16x16x32_bf16 v[8:11], v[124:127], v[180:183], v[8:11]
	v_mfma_f32_16x16x32_bf16 v[12:15], v[172:175], v[180:183], v[12:15]
	v_mfma_f32_16x16x32_bf16 v[28:31], v[124:127], v[188:191], v[28:31]
	v_mfma_f32_16x16x32_bf16 v[60:63], v[172:175], v[188:191], v[60:63]
	v_mfma_f32_16x16x32_bf16 v[100:103], v[124:127], v[196:199], v[100:103]
	v_mfma_f32_16x16x32_bf16 v[104:107], v[172:175], v[196:199], v[104:107]
	v_mfma_f32_16x16x32_bf16 v[16:19], v[124:127], v[204:207], v[16:19]
	v_mfma_f32_16x16x32_bf16 v[20:23], v[172:175], v[204:207], v[20:23]
	v_mfma_f32_16x16x32_bf16 v[156:159], v[116:119], v[196:199], v[164:167]
	s_barrier
	ds_read_b128 v[108:111], v143
	ds_read_b128 v[116:119], v143 offset:1024
	ds_read_b128 v[120:123], v143 offset:2048
	ds_read_b128 v[124:127], v143 offset:3072
	ds_read_b128 v[160:163], v144
	ds_read_b128 v[164:167], v144 offset:1024
	ds_read_b128 v[168:171], v144 offset:2048
	ds_read_b128 v[172:175], v144 offset:3072
	s_add_u32 s38, s38, 0x80180
	s_addc_u32 s39, s39, 0
	s_mov_b32 m0, s48
	v_lshl_add_u64 v[208:209], s[38:39], 0, v[130:131]
	ds_read_b128 v[176:179], v145
	ds_read_b128 v[180:183], v145 offset:1024
	ds_read_b128 v[184:187], v145 offset:2048
	ds_read_b128 v[188:191], v145 offset:3072
	ds_read_b128 v[192:195], v145 offset:4096
	ds_read_b128 v[196:199], v145 offset:5120
	ds_read_b128 v[200:203], v145 offset:6144
	ds_read_b128 v[204:207], v145 offset:7168
	global_load_lds_dwordx4 v[208:209], off
	v_lshl_add_u64 v[208:209], s[38:39], 0, v[132:133]
	s_mov_b32 m0, s49
	s_nop 0
	global_load_lds_dwordx4 v[208:209], off
	s_waitcnt vmcnt(8)
	s_waitcnt lgkmcnt(0)
	s_waitcnt lgkmcnt(0)
	v_mfma_f32_16x16x32_bf16 v[64:67], v[108:111], v[176:179], v[64:67]
	v_mfma_f32_16x16x32_bf16 v[68:71], v[120:123], v[176:179], v[68:71]
	v_mfma_f32_16x16x32_bf16 v[64:67], v[116:119], v[180:183], v[64:67]
	v_mfma_f32_16x16x32_bf16 v[68:71], v[124:127], v[180:183], v[68:71]
	s_barrier
	v_mfma_f32_16x16x32_bf16 v[72:75], v[108:111], v[184:187], v[72:75]
	v_mfma_f32_16x16x32_bf16 v[76:79], v[120:123], v[184:187], v[76:79]
	v_mfma_f32_16x16x32_bf16 v[80:83], v[108:111], v[192:195], v[80:83]
	v_mfma_f32_16x16x32_bf16 v[84:87], v[120:123], v[192:195], v[84:87]
	v_mfma_f32_16x16x32_bf16 v[88:91], v[108:111], v[200:203], v[88:91]
	v_mfma_f32_16x16x32_bf16 v[92:95], v[120:123], v[200:203], v[92:95]
	v_mfma_f32_16x16x32_bf16 v[96:99], v[160:163], v[176:179], v[96:99]
	v_mfma_f32_16x16x32_bf16 v[32:35], v[168:171], v[176:179], v[32:35]
	v_mfma_f32_16x16x32_bf16 v[36:39], v[160:163], v[184:187], v[36:39]
	v_mfma_f32_16x16x32_bf16 v[40:43], v[168:171], v[184:187], v[40:43]
	v_mfma_f32_16x16x32_bf16 v[44:47], v[160:163], v[192:195], v[44:47]
	v_mfma_f32_16x16x32_bf16 v[48:51], v[168:171], v[192:195], v[48:51]
	v_mfma_f32_16x16x32_bf16 v[52:55], v[160:163], v[200:203], v[52:55]
	v_mfma_f32_16x16x32_bf16 v[56:59], v[168:171], v[200:203], v[56:59]
	v_mfma_f32_16x16x32_bf16 v[72:75], v[116:119], v[188:191], v[72:75]
	v_mfma_f32_16x16x32_bf16 v[76:79], v[124:127], v[188:191], v[76:79]
	v_mfma_f32_16x16x32_bf16 v[80:83], v[116:119], v[196:199], v[80:83]
	v_mfma_f32_16x16x32_bf16 v[84:87], v[124:127], v[196:199], v[84:87]
	v_mfma_f32_16x16x32_bf16 v[88:91], v[116:119], v[204:207], v[88:91]
	v_mfma_f32_16x16x32_bf16 v[92:95], v[124:127], v[204:207], v[92:95]
	v_mfma_f32_16x16x32_bf16 v[96:99], v[164:167], v[180:183], v[96:99]
	v_mfma_f32_16x16x32_bf16 v[32:35], v[172:175], v[180:183], v[32:35]
	v_mfma_f32_16x16x32_bf16 v[36:39], v[164:167], v[188:191], v[36:39]
	v_mfma_f32_16x16x32_bf16 v[40:43], v[172:175], v[188:191], v[40:43]
	v_mfma_f32_16x16x32_bf16 v[44:47], v[164:167], v[196:199], v[44:47]
	v_mfma_f32_16x16x32_bf16 v[48:51], v[172:175], v[196:199], v[48:51]
	v_mfma_f32_16x16x32_bf16 v[52:55], v[164:167], v[204:207], v[52:55]
	v_mfma_f32_16x16x32_bf16 v[56:59], v[172:175], v[204:207], v[56:59]
	s_barrier
	s_mov_b32 m0, s51
	v_lshl_add_u64 v[234:235], s[40:41], 0, v[128:129]
	s_add_u32 s38, s40, 0x10000
	ds_read_b128 v[176:179], v145 offset:16384
	ds_read_b128 v[180:183], v145 offset:17408
	ds_read_b128 v[184:187], v145 offset:18432
	ds_read_b128 v[188:191], v145 offset:19456
	ds_read_b128 v[192:195], v145 offset:20480
	ds_read_b128 v[196:199], v145 offset:21504
	ds_read_b128 v[200:203], v145 offset:22528
	ds_read_b128 v[204:207], v145 offset:23552
	global_load_lds_dwordx4 v[234:235], off
	v_lshl_add_u64 v[242:243], s[40:41], 0, v[134:135]
	s_mov_b32 m0, s53
	s_addc_u32 s39, s41, 0
	global_load_lds_dwordx4 v[242:243], off
	v_lshl_add_u64 v[208:209], s[38:39], 0, v[128:129]
	s_mov_b32 m0, s55
	v_lshl_add_u64 v[244:245], s[42:43], 0, v[130:131]
	global_load_lds_dwordx4 v[208:209], off
	v_lshl_add_u64 v[208:209], s[38:39], 0, v[134:135]
	s_mov_b32 m0, s56
	v_lshl_add_u64 v[246:247], s[42:43], 0, v[132:133]
	global_load_lds_dwordx4 v[208:209], off
	s_mov_b32 m0, s13
	s_nop 0
	global_load_lds_dwordx4 v[244:245], off
	s_mov_b32 m0, s35
	s_nop 0
	global_load_lds_dwordx4 v[246:247], off
	s_waitcnt vmcnt(8)
	s_waitcnt lgkmcnt(0)
	s_waitcnt lgkmcnt(0)
	v_mfma_f32_16x16x32_bf16 v[136:139], v[108:111], v[176:179], v[136:139]
	v_mfma_f32_16x16x32_bf16 v[148:151], v[120:123], v[176:179], v[148:151]
	v_mfma_f32_16x16x32_bf16 v[136:139], v[116:119], v[180:183], v[136:139]
	v_mfma_f32_16x16x32_bf16 v[148:151], v[124:127], v[180:183], v[148:151]
	s_barrier
	v_mfma_f32_16x16x32_bf16 v[8:11], v[160:163], v[176:179], v[8:11]
	v_mfma_f32_16x16x32_bf16 v[212:215], v[164:167], v[180:183], v[8:11]
	v_mfma_f32_16x16x32_bf16 v[8:11], v[168:171], v[176:179], v[12:15]
	v_mfma_f32_16x16x32_bf16 v[176:179], v[172:175], v[180:183], v[8:11]
	v_mfma_f32_16x16x32_bf16 v[8:11], v[160:163], v[184:187], v[28:31]
	v_mfma_f32_16x16x32_bf16 v[180:183], v[164:167], v[188:191], v[8:11]
	v_mfma_f32_16x16x32_bf16 v[8:11], v[168:171], v[184:187], v[60:63]
	v_mfma_f32_16x16x32_bf16 v[24:27], v[108:111], v[184:187], v[24:27]
	v_mfma_f32_16x16x32_bf16 v[112:115], v[120:123], v[184:187], v[112:115]
	v_mfma_f32_16x16x32_bf16 v[184:187], v[172:175], v[188:191], v[8:11]
	v_mfma_f32_16x16x32_bf16 v[8:11], v[160:163], v[192:195], v[100:103]
	v_mfma_f32_16x16x32_bf16 v[24:27], v[116:119], v[188:191], v[24:27]
	v_mfma_f32_16x16x32_bf16 v[208:211], v[124:127], v[188:191], v[112:115]
	v_mfma_f32_16x16x32_bf16 v[188:191], v[164:167], v[196:199], v[8:11]
	v_mfma_f32_16x16x32_bf16 v[8:11], v[168:171], v[192:195], v[104:107]
	v_mfma_f32_16x16x32_bf16 v[152:155], v[108:111], v[192:195], v[152:155]
	v_mfma_f32_16x16x32_bf16 v[156:159], v[120:123], v[192:195], v[156:159]
	v_mfma_f32_16x16x32_bf16 v[0:3], v[108:111], v[200:203], v[0:3]
	v_mfma_f32_16x16x32_bf16 v[4:7], v[120:123], v[200:203], v[4:7]
	v_mfma_f32_16x16x32_bf16 v[192:195], v[172:175], v[196:199], v[8:11]
	v_mfma_f32_16x16x32_bf16 v[8:11], v[160:163], v[200:203], v[16:19]
	v_mfma_f32_16x16x32_bf16 v[0:3], v[116:119], v[204:207], v[0:3]
	v_mfma_f32_16x16x32_bf16 v[4:7], v[124:127], v[204:207], v[4:7]
	v_mfma_f32_16x16x32_bf16 v[160:163], v[164:167], v[204:207], v[8:11]
	v_mfma_f32_16x16x32_bf16 v[8:11], v[168:171], v[200:203], v[20:23]
	v_mfma_f32_16x16x32_bf16 v[152:155], v[116:119], v[196:199], v[152:155]
	v_mfma_f32_16x16x32_bf16 v[156:159], v[124:127], v[196:199], v[156:159]
	v_mfma_f32_16x16x32_bf16 v[164:167], v[172:175], v[204:207], v[8:11]
	s_barrier
	s_nop 2
	ds_read_b128 v[8:11], v146
	ds_read_b128 v[12:15], v146 offset:1024
	ds_read_b128 v[16:19], v146 offset:2048
	ds_read_b128 v[20:23], v146 offset:3072
	ds_read_b128 v[168:171], v147
	ds_read_b128 v[172:175], v147 offset:1024
	ds_read_b128 v[196:199], v147 offset:2048
	ds_read_b128 v[200:203], v147 offset:3072
	s_add_u32 s38, s42, 0x80000
	s_addc_u32 s39, s43, 0
	s_mov_b32 m0, s37
	v_lshl_add_u64 v[100:101], s[38:39], 0, v[130:131]
	ds_read_b128 v[28:31], v145 offset:32768
	ds_read_b128 v[60:63], v145 offset:33792
	ds_read_b128 v[204:207], v145 offset:34816
	ds_read_b128 v[216:219], v145 offset:35840
	ds_read_b128 v[222:225], v145 offset:36864
	ds_read_b128 v[226:229], v145 offset:37888
	ds_read_b128 v[230:233], v145 offset:38912
	ds_read_b128 v[238:241], v145 offset:39936
	global_load_lds_dwordx4 v[100:101], off
	v_lshl_add_u64 v[100:101], s[38:39], 0, v[132:133]
	s_mov_b32 m0, s44
	s_nop 0
	global_load_lds_dwordx4 v[100:101], off
	s_waitcnt vmcnt(8)
	s_waitcnt lgkmcnt(0)
	s_waitcnt lgkmcnt(0)
	v_mfma_f32_16x16x32_bf16 v[64:67], v[8:11], v[28:31], v[64:67]
	v_mfma_f32_16x16x32_bf16 v[68:71], v[16:19], v[28:31], v[68:71]
	v_mfma_f32_16x16x32_bf16 v[124:127], v[12:15], v[60:63], v[64:67]
	v_mfma_f32_16x16x32_bf16 v[120:123], v[20:23], v[60:63], v[68:71]
	s_barrier
	v_mfma_f32_16x16x32_bf16 v[64:67], v[8:11], v[204:207], v[72:75]
	v_mfma_f32_16x16x32_bf16 v[108:111], v[12:15], v[216:219], v[64:67]
	v_mfma_f32_16x16x32_bf16 v[64:67], v[168:171], v[28:31], v[96:99]
	v_mfma_f32_16x16x32_bf16 v[28:31], v[196:199], v[28:31], v[32:35]
	v_mfma_f32_16x16x32_bf16 v[112:115], v[200:203], v[60:63], v[28:31]
	v_mfma_f32_16x16x32_bf16 v[28:31], v[168:171], v[204:207], v[36:39]
	v_mfma_f32_16x16x32_bf16 v[100:103], v[172:175], v[216:219], v[28:31]
	v_mfma_f32_16x16x32_bf16 v[28:31], v[196:199], v[204:207], v[40:43]
	v_mfma_f32_16x16x32_bf16 v[68:71], v[16:19], v[204:207], v[76:79]
	v_mfma_f32_16x16x32_bf16 v[72:75], v[8:11], v[222:225], v[80:83]
	v_mfma_f32_16x16x32_bf16 v[76:79], v[16:19], v[222:225], v[84:87]
	v_mfma_f32_16x16x32_bf16 v[84:87], v[16:19], v[230:233], v[92:95]
	v_mfma_f32_16x16x32_bf16 v[96:99], v[200:203], v[216:219], v[28:31]
	v_mfma_f32_16x16x32_bf16 v[28:31], v[168:171], v[222:225], v[44:47]
	v_mfma_f32_16x16x32_bf16 v[80:83], v[8:11], v[230:233], v[88:91]
	v_mfma_f32_16x16x32_bf16 v[92:95], v[12:15], v[226:229], v[72:75]
	v_mfma_f32_16x16x32_bf16 v[72:75], v[20:23], v[238:241], v[84:87]
	v_mfma_f32_16x16x32_bf16 v[84:87], v[172:175], v[226:229], v[28:31]
	v_mfma_f32_16x16x32_bf16 v[28:31], v[196:199], v[222:225], v[48:51]
	v_mfma_f32_16x16x32_bf16 v[88:91], v[20:23], v[226:229], v[76:79]
	v_mfma_f32_16x16x32_bf16 v[76:79], v[12:15], v[238:241], v[80:83]
	v_mfma_f32_16x16x32_bf16 v[80:83], v[200:203], v[226:229], v[28:31]
	v_mfma_f32_16x16x32_bf16 v[28:31], v[168:171], v[230:233], v[52:55]
	v_mfma_f32_16x16x32_bf16 v[104:107], v[20:23], v[216:219], v[68:71]
	v_mfma_f32_16x16x32_bf16 v[68:71], v[172:175], v[238:241], v[28:31]
	v_mfma_f32_16x16x32_bf16 v[28:31], v[196:199], v[230:233], v[56:59]
	v_mfma_f32_16x16x32_bf16 v[116:119], v[172:175], v[60:63], v[64:67]
	v_mfma_f32_16x16x32_bf16 v[64:67], v[200:203], v[238:241], v[28:31]
	s_barrier
	s_mov_b32 m0, s57
	s_nop 2
	v_lshl_add_u64 v[28:29], v[234:235], 0, s[16:17]
	s_add_u32 s38, s40, 0x10080
	ds_read_b128 v[32:35], v145 offset:49152
	ds_read_b128 v[36:39], v145 offset:50176
	ds_read_b128 v[204:207], v145 offset:51200
	ds_read_b128 v[216:219], v145 offset:52224
	ds_read_b128 v[222:225], v145 offset:53248
	ds_read_b128 v[226:229], v145 offset:54272
	ds_read_b128 v[230:233], v145 offset:55296
	ds_read_b128 v[238:241], v145 offset:56320
	global_load_lds_dwordx4 v[28:29], off
	v_lshl_add_u64 v[28:29], v[242:243], 0, s[16:17]
	s_mov_b32 m0, s59
	s_addc_u32 s39, s41, 0
	global_load_lds_dwordx4 v[28:29], off
	v_lshl_add_u64 v[28:29], s[38:39], 0, v[128:129]
	s_mov_b32 m0, s62
	s_nop 0
	global_load_lds_dwordx4 v[28:29], off
	v_lshl_add_u64 v[28:29], s[38:39], 0, v[134:135]
	s_mov_b32 m0, s8
	s_nop 0
	global_load_lds_dwordx4 v[28:29], off
	v_lshl_add_u64 v[28:29], v[244:245], 0, s[16:17]
	s_mov_b32 m0, s45
	s_nop 0
	global_load_lds_dwordx4 v[28:29], off
	v_lshl_add_u64 v[28:29], v[246:247], 0, s[16:17]
	s_mov_b32 m0, s46
	s_nop 0
	global_load_lds_dwordx4 v[28:29], off
	s_waitcnt vmcnt(8)
	s_waitcnt lgkmcnt(0)
	s_waitcnt lgkmcnt(0)
	v_mfma_f32_16x16x32_bf16 v[28:31], v[8:11], v[32:35], v[136:139]
	v_mfma_f32_16x16x32_bf16 v[40:43], v[16:19], v[32:35], v[148:151]
	v_mfma_f32_16x16x32_bf16 v[60:63], v[12:15], v[36:39], v[28:31]
	v_mfma_f32_16x16x32_bf16 v[56:59], v[20:23], v[36:39], v[40:43]
	s_barrier
	v_mfma_f32_16x16x32_bf16 v[24:27], v[8:11], v[204:207], v[24:27]
	v_mfma_f32_16x16x32_bf16 v[28:31], v[16:19], v[204:207], v[208:211]
	v_mfma_f32_16x16x32_bf16 v[48:51], v[8:11], v[222:225], v[152:155]
	v_mfma_f32_16x16x32_bf16 v[0:3], v[8:11], v[230:233], v[0:3]
	v_mfma_f32_16x16x32_bf16 v[52:55], v[16:19], v[222:225], v[156:159]
	v_mfma_f32_16x16x32_bf16 v[44:47], v[12:15], v[216:219], v[24:27]
	v_mfma_f32_16x16x32_bf16 v[40:43], v[20:23], v[216:219], v[28:31]
	v_mfma_f32_16x16x32_bf16 v[28:31], v[12:15], v[226:229], v[48:51]
	v_mfma_f32_16x16x32_bf16 v[12:15], v[12:15], v[238:241], v[0:3]
	v_mfma_f32_16x16x32_bf16 v[0:3], v[168:171], v[32:35], v[212:215]
	v_mfma_f32_16x16x32_bf16 v[24:27], v[20:23], v[226:229], v[52:55]
	v_mfma_f32_16x16x32_bf16 v[52:55], v[172:175], v[36:39], v[0:3]
	v_mfma_f32_16x16x32_bf16 v[0:3], v[196:199], v[32:35], v[176:179]
	v_mfma_f32_16x16x32_bf16 v[48:51], v[200:203], v[36:39], v[0:3]
	v_mfma_f32_16x16x32_bf16 v[0:3], v[168:171], v[204:207], v[180:183]
	v_mfma_f32_16x16x32_bf16 v[36:39], v[172:175], v[216:219], v[0:3]
	v_mfma_f32_16x16x32_bf16 v[0:3], v[196:199], v[204:207], v[184:187]
	v_mfma_f32_16x16x32_bf16 v[4:7], v[16:19], v[230:233], v[4:7]
	v_mfma_f32_16x16x32_bf16 v[32:35], v[200:203], v[216:219], v[0:3]
	v_mfma_f32_16x16x32_bf16 v[0:3], v[168:171], v[222:225], v[188:191]
	v_mfma_f32_16x16x32_bf16 v[8:11], v[20:23], v[238:241], v[4:7]
	v_mfma_f32_16x16x32_bf16 v[20:23], v[172:175], v[226:229], v[0:3]
	v_mfma_f32_16x16x32_bf16 v[0:3], v[196:199], v[222:225], v[192:195]
	v_mfma_f32_16x16x32_bf16 v[16:19], v[200:203], v[226:229], v[0:3]
	v_mfma_f32_16x16x32_bf16 v[0:3], v[168:171], v[230:233], v[160:163]
	v_mfma_f32_16x16x32_bf16 v[4:7], v[172:175], v[238:241], v[0:3]
	v_mfma_f32_16x16x32_bf16 v[0:3], v[196:199], v[230:233], v[164:167]
	v_mfma_f32_16x16x32_bf16 v[0:3], v[200:203], v[238:241], v[0:3]
	s_barrier
	s_andn2_b64 vcc, exec, s[18:19]
	s_cbranch_vccnz .LBB0_675
	s_barrier
	s_cmp_gt_i32 s36, 0x3fffffff
	s_cselect_b64 s[38:39], -1, 0
	s_cmp_lt_i32 s36, 2.0
	s_cbranch_scc0 .LBB0_676

.LBB0_1094:
	ds_read_b128 v[144:147], v151
	ds_read_b128 v[156:159], v151 offset:1024
	ds_read_b128 v[160:163], v151 offset:2048
	ds_read_b128 v[164:167], v151 offset:3072
	ds_read_b128 v[168:171], v152
	ds_read_b128 v[172:175], v152 offset:1024
	ds_read_b128 v[176:179], v152 offset:2048
	ds_read_b128 v[180:183], v152 offset:3072
	s_add_u32 s28, s26, 0xfff80080
	s_addc_u32 s29, s27, -1
	s_cmp_eq_u32 s48, 28
	s_cselect_b32 s31, s17, s29
	s_cselect_b32 s30, s23, s28
	s_cselect_b32 s29, s15, s47
	s_cselect_b32 s28, s45, s46
	s_add_i32 m0, s25, 0xc000
	ds_read_b128 v[184:187], v153
	ds_read_b128 v[188:191], v153 offset:1024
	ds_read_b128 v[192:195], v153 offset:2048
	ds_read_b128 v[196:199], v153 offset:3072
	ds_read_b128 v[200:203], v153 offset:4096
	ds_read_b128 v[204:207], v153 offset:5120
	ds_read_b128 v[208:211], v153 offset:6144
	ds_read_b128 v[212:215], v153 offset:7168
	global_load_lds_dwordx4 v136, s[26:27]
	s_add_i32 m0, s25, 0xe000
	s_nop 0
	global_load_lds_dwordx4 v138, s[26:27]
	s_waitcnt vmcnt(8)
	s_waitcnt lgkmcnt(0)
	s_waitcnt lgkmcnt(0)
	v_mfma_f32_16x16x32_bf16 v[124:127], v[144:147], v[184:187], v[124:127]
	v_mfma_f32_16x16x32_bf16 v[120:123], v[160:163], v[184:187], v[120:123]
	v_mfma_f32_16x16x32_bf16 v[124:127], v[156:159], v[188:191], v[124:127]
	v_mfma_f32_16x16x32_bf16 v[120:123], v[164:167], v[188:191], v[120:123]
	s_barrier
	v_mfma_f32_16x16x32_bf16 v[108:111], v[144:147], v[192:195], v[108:111]
	v_mfma_f32_16x16x32_bf16 v[104:107], v[160:163], v[192:195], v[104:107]
	v_mfma_f32_16x16x32_bf16 v[92:95], v[144:147], v[200:203], v[92:95]
	v_mfma_f32_16x16x32_bf16 v[88:91], v[160:163], v[200:203], v[88:91]
	v_mfma_f32_16x16x32_bf16 v[76:79], v[144:147], v[208:211], v[76:79]
	v_mfma_f32_16x16x32_bf16 v[72:75], v[160:163], v[208:211], v[72:75]
	v_mfma_f32_16x16x32_bf16 v[116:119], v[168:171], v[184:187], v[116:119]
	v_mfma_f32_16x16x32_bf16 v[112:115], v[176:179], v[184:187], v[112:115]
	v_mfma_f32_16x16x32_bf16 v[100:103], v[168:171], v[192:195], v[100:103]
	v_mfma_f32_16x16x32_bf16 v[96:99], v[176:179], v[192:195], v[96:99]
	v_mfma_f32_16x16x32_bf16 v[84:87], v[168:171], v[200:203], v[84:87]
	v_mfma_f32_16x16x32_bf16 v[80:83], v[176:179], v[200:203], v[80:83]
	v_mfma_f32_16x16x32_bf16 v[68:71], v[168:171], v[208:211], v[68:71]
	v_mfma_f32_16x16x32_bf16 v[64:67], v[176:179], v[208:211], v[64:67]
	v_mfma_f32_16x16x32_bf16 v[108:111], v[156:159], v[196:199], v[108:111]
	v_mfma_f32_16x16x32_bf16 v[104:107], v[164:167], v[196:199], v[104:107]
	v_mfma_f32_16x16x32_bf16 v[92:95], v[156:159], v[204:207], v[92:95]
	v_mfma_f32_16x16x32_bf16 v[88:91], v[164:167], v[204:207], v[88:91]
	v_mfma_f32_16x16x32_bf16 v[76:79], v[156:159], v[212:215], v[76:79]
	v_mfma_f32_16x16x32_bf16 v[72:75], v[164:167], v[212:215], v[72:75]
	v_mfma_f32_16x16x32_bf16 v[116:119], v[172:175], v[188:191], v[116:119]
	v_mfma_f32_16x16x32_bf16 v[112:115], v[180:183], v[188:191], v[112:115]
	v_mfma_f32_16x16x32_bf16 v[100:103], v[172:175], v[196:199], v[100:103]
	v_mfma_f32_16x16x32_bf16 v[96:99], v[180:183], v[196:199], v[96:99]
	v_mfma_f32_16x16x32_bf16 v[84:87], v[172:175], v[204:207], v[84:87]
	v_mfma_f32_16x16x32_bf16 v[80:83], v[180:183], v[204:207], v[80:83]
	v_mfma_f32_16x16x32_bf16 v[68:71], v[172:175], v[212:215], v[68:71]
	v_mfma_f32_16x16x32_bf16 v[64:67], v[180:183], v[212:215], v[64:67]
	s_barrier
	s_add_i32 s49, s95, s2
	v_lshl_add_u64 v[216:217], s[28:29], 0, v[130:131]
	s_mov_b32 m0, s49
	ds_read_b128 v[184:187], v153 offset:16384
	ds_read_b128 v[188:191], v153 offset:17408
	ds_read_b128 v[192:195], v153 offset:18432
	ds_read_b128 v[196:199], v153 offset:19456
	ds_read_b128 v[200:203], v153 offset:20480
	ds_read_b128 v[204:207], v153 offset:21504
	ds_read_b128 v[208:211], v153 offset:22528
	ds_read_b128 v[212:215], v153 offset:23552
	global_load_lds_dwordx4 v[216:217], off
	s_add_i32 m0, s49, 0x2000
	s_add_u32 s50, s28, 0x80000
	v_lshl_add_u64 v[218:219], s[28:29], 0, v[134:135]
	s_addc_u32 s51, s29, 0
	s_add_i32 s49, s33, s2
	global_load_lds_dwordx4 v[218:219], off
	s_mov_b32 m0, s49
	v_lshl_add_u64 v[224:225], s[30:31], 0, v[132:133]
	global_load_lds_dwordx4 v130, s[50:51]
	s_add_i32 m0, s49, 0x2000
	s_nop 0
	global_load_lds_dwordx4 v134, s[50:51]
	v_lshl_add_u64 v[222:223], s[30:31], 0, v[128:129]
	s_mov_b32 m0, s25
	s_nop 0
	global_load_lds_dwordx4 v[222:223], off
	s_mov_b32 m0, s36
	s_nop 0
	global_load_lds_dwordx4 v[224:225], off
	s_waitcnt vmcnt(8)
	s_waitcnt lgkmcnt(0)
	s_waitcnt lgkmcnt(0)
	v_mfma_f32_16x16x32_bf16 v[60:63], v[144:147], v[184:187], v[60:63]
	v_mfma_f32_16x16x32_bf16 v[56:59], v[160:163], v[184:187], v[56:59]
	v_mfma_f32_16x16x32_bf16 v[60:63], v[156:159], v[188:191], v[60:63]
	v_mfma_f32_16x16x32_bf16 v[56:59], v[164:167], v[188:191], v[56:59]
	s_barrier
	v_mfma_f32_16x16x32_bf16 v[44:47], v[144:147], v[192:195], v[44:47]
	v_mfma_f32_16x16x32_bf16 v[40:43], v[160:163], v[192:195], v[40:43]
	v_mfma_f32_16x16x32_bf16 v[28:31], v[144:147], v[200:203], v[28:31]
	v_mfma_f32_16x16x32_bf16 v[24:27], v[160:163], v[200:203], v[24:27]
	v_mfma_f32_16x16x32_bf16 v[12:15], v[144:147], v[208:211], v[12:15]
	v_mfma_f32_16x16x32_bf16 v[8:11], v[160:163], v[208:211], v[8:11]
	v_mfma_f32_16x16x32_bf16 v[52:55], v[168:171], v[184:187], v[52:55]
	v_mfma_f32_16x16x32_bf16 v[48:51], v[176:179], v[184:187], v[48:51]
	v_mfma_f32_16x16x32_bf16 v[36:39], v[168:171], v[192:195], v[36:39]
	v_mfma_f32_16x16x32_bf16 v[32:35], v[176:179], v[192:195], v[32:35]
	v_mfma_f32_16x16x32_bf16 v[20:23], v[168:171], v[200:203], v[20:23]
	v_mfma_f32_16x16x32_bf16 v[16:19], v[176:179], v[200:203], v[16:19]
	v_mfma_f32_16x16x32_bf16 v[4:7], v[168:171], v[208:211], v[4:7]
	v_mfma_f32_16x16x32_bf16 v[0:3], v[176:179], v[208:211], v[0:3]
	v_mfma_f32_16x16x32_bf16 v[44:47], v[156:159], v[196:199], v[44:47]
	v_mfma_f32_16x16x32_bf16 v[40:43], v[164:167], v[196:199], v[40:43]
	v_mfma_f32_16x16x32_bf16 v[28:31], v[156:159], v[204:207], v[28:31]
	v_mfma_f32_16x16x32_bf16 v[24:27], v[164:167], v[204:207], v[24:27]
	v_mfma_f32_16x16x32_bf16 v[12:15], v[156:159], v[212:215], v[12:15]
	v_mfma_f32_16x16x32_bf16 v[8:11], v[164:167], v[212:215], v[8:11]
	v_mfma_f32_16x16x32_bf16 v[52:55], v[172:175], v[188:191], v[52:55]
	v_mfma_f32_16x16x32_bf16 v[48:51], v[180:183], v[188:191], v[48:51]
	v_mfma_f32_16x16x32_bf16 v[36:39], v[172:175], v[196:199], v[36:39]
	v_mfma_f32_16x16x32_bf16 v[32:35], v[180:183], v[196:199], v[32:35]
	v_mfma_f32_16x16x32_bf16 v[20:23], v[172:175], v[204:207], v[20:23]
	v_mfma_f32_16x16x32_bf16 v[16:19], v[180:183], v[204:207], v[16:19]
	v_mfma_f32_16x16x32_bf16 v[4:7], v[172:175], v[212:215], v[4:7]
	v_mfma_f32_16x16x32_bf16 v[0:3], v[180:183], v[212:215], v[0:3]
	s_barrier
	v_add_u32_e32 v155, s3, v149
	ds_read_b128 v[144:147], v155
	ds_read_b128 v[156:159], v155 offset:1024
	ds_read_b128 v[160:163], v155 offset:2048
	ds_read_b128 v[164:167], v155 offset:3072
	v_add_u32_e32 v155, s58, v149
	ds_read_b128 v[168:171], v155
	ds_read_b128 v[172:175], v155 offset:1024
	ds_read_b128 v[176:179], v155 offset:2048
	ds_read_b128 v[180:183], v155 offset:3072
	s_add_u32 s30, s30, 0x80000
	s_addc_u32 s31, s31, 0
	s_mov_b32 m0, s37
	ds_read_b128 v[184:187], v153 offset:32768
	ds_read_b128 v[188:191], v153 offset:33792
	ds_read_b128 v[192:195], v153 offset:34816
	ds_read_b128 v[196:199], v153 offset:35840
	ds_read_b128 v[200:203], v153 offset:36864
	ds_read_b128 v[204:207], v153 offset:37888
	ds_read_b128 v[208:211], v153 offset:38912
	ds_read_b128 v[212:215], v153 offset:39936
	global_load_lds_dwordx4 v128, s[30:31]
	s_mov_b32 m0, s38
	s_nop 0
	global_load_lds_dwordx4 v132, s[30:31]
	s_waitcnt vmcnt(8)
	s_waitcnt lgkmcnt(0)
	s_waitcnt lgkmcnt(0)
	v_mfma_f32_16x16x32_bf16 v[124:127], v[144:147], v[184:187], v[124:127]
	v_mfma_f32_16x16x32_bf16 v[120:123], v[160:163], v[184:187], v[120:123]
	v_mfma_f32_16x16x32_bf16 v[124:127], v[156:159], v[188:191], v[124:127]
	v_mfma_f32_16x16x32_bf16 v[120:123], v[164:167], v[188:191], v[120:123]
	s_barrier
	v_mfma_f32_16x16x32_bf16 v[108:111], v[144:147], v[192:195], v[108:111]
	v_mfma_f32_16x16x32_bf16 v[104:107], v[160:163], v[192:195], v[104:107]
	v_mfma_f32_16x16x32_bf16 v[92:95], v[144:147], v[200:203], v[92:95]
	v_mfma_f32_16x16x32_bf16 v[88:91], v[160:163], v[200:203], v[88:91]
	v_mfma_f32_16x16x32_bf16 v[76:79], v[144:147], v[208:211], v[76:79]
	v_mfma_f32_16x16x32_bf16 v[72:75], v[160:163], v[208:211], v[72:75]
	v_mfma_f32_16x16x32_bf16 v[116:119], v[168:171], v[184:187], v[116:119]
	v_mfma_f32_16x16x32_bf16 v[112:115], v[176:179], v[184:187], v[112:115]
	v_mfma_f32_16x16x32_bf16 v[100:103], v[168:171], v[192:195], v[100:103]
	v_mfma_f32_16x16x32_bf16 v[96:99], v[176:179], v[192:195], v[96:99]
	v_mfma_f32_16x16x32_bf16 v[84:87], v[168:171], v[200:203], v[84:87]
	v_mfma_f32_16x16x32_bf16 v[80:83], v[176:179], v[200:203], v[80:83]
	v_mfma_f32_16x16x32_bf16 v[68:71], v[168:171], v[208:211], v[68:71]
	v_mfma_f32_16x16x32_bf16 v[64:67], v[176:179], v[208:211], v[64:67]
	v_mfma_f32_16x16x32_bf16 v[108:111], v[156:159], v[196:199], v[108:111]
	v_mfma_f32_16x16x32_bf16 v[104:107], v[164:167], v[196:199], v[104:107]
	v_mfma_f32_16x16x32_bf16 v[92:95], v[156:159], v[204:207], v[92:95]
	v_mfma_f32_16x16x32_bf16 v[88:91], v[164:167], v[204:207], v[88:91]
	v_mfma_f32_16x16x32_bf16 v[76:79], v[156:159], v[212:215], v[76:79]
	v_mfma_f32_16x16x32_bf16 v[72:75], v[164:167], v[212:215], v[72:75]
	v_mfma_f32_16x16x32_bf16 v[116:119], v[172:175], v[188:191], v[116:119]
	v_mfma_f32_16x16x32_bf16 v[112:115], v[180:183], v[188:191], v[112:115]
	v_mfma_f32_16x16x32_bf16 v[100:103], v[172:175], v[196:199], v[100:103]
	v_mfma_f32_16x16x32_bf16 v[96:99], v[180:183], v[196:199], v[96:99]
	v_mfma_f32_16x16x32_bf16 v[84:87], v[172:175], v[204:207], v[84:87]
	v_mfma_f32_16x16x32_bf16 v[80:83], v[180:183], v[204:207], v[80:83]
	v_mfma_f32_16x16x32_bf16 v[68:71], v[172:175], v[212:215], v[68:71]
	v_mfma_f32_16x16x32_bf16 v[64:67], v[180:183], v[212:215], v[64:67]
	s_barrier
	s_add_i32 s30, s3, s2
	v_lshl_add_u64 v[216:217], v[216:217], 0, s[10:11]
	s_mov_b32 m0, s30
	ds_read_b128 v[184:187], v153 offset:49152
	ds_read_b128 v[188:191], v153 offset:50176
	ds_read_b128 v[192:195], v153 offset:51200
	ds_read_b128 v[196:199], v153 offset:52224
	ds_read_b128 v[200:203], v153 offset:53248
	ds_read_b128 v[204:207], v153 offset:54272
	ds_read_b128 v[208:211], v153 offset:55296
	ds_read_b128 v[212:215], v153 offset:56320
	global_load_lds_dwordx4 v[216:217], off
	s_add_i32 m0, s30, 0x2000
	s_add_u32 s28, s28, 0x80080
	v_lshl_add_u64 v[216:217], v[218:219], 0, s[10:11]
	s_addc_u32 s29, s29, 0
	s_add_i32 s30, s58, s2
	global_load_lds_dwordx4 v[216:217], off
	s_mov_b32 m0, s30
	s_nop 0
	global_load_lds_dwordx4 v130, s[28:29]
	s_add_i32 m0, s30, 0x2000
	s_nop 0
	global_load_lds_dwordx4 v134, s[28:29]
	v_lshl_add_u64 v[216:217], v[222:223], 0, s[10:11]
	s_mov_b32 m0, s40
	s_nop 0
	global_load_lds_dwordx4 v[216:217], off
	v_lshl_add_u64 v[216:217], v[224:225], 0, s[10:11]
	s_mov_b32 m0, s41
	s_nop 0
	global_load_lds_dwordx4 v[216:217], off
	s_waitcnt vmcnt(8)
	s_waitcnt lgkmcnt(0)
	s_waitcnt lgkmcnt(0)
	v_mfma_f32_16x16x32_bf16 v[60:63], v[144:147], v[184:187], v[60:63]
	v_mfma_f32_16x16x32_bf16 v[56:59], v[160:163], v[184:187], v[56:59]
	v_mfma_f32_16x16x32_bf16 v[60:63], v[156:159], v[188:191], v[60:63]
	v_mfma_f32_16x16x32_bf16 v[56:59], v[164:167], v[188:191], v[56:59]
	s_barrier
	v_mfma_f32_16x16x32_bf16 v[44:47], v[144:147], v[192:195], v[44:47]
	v_mfma_f32_16x16x32_bf16 v[40:43], v[160:163], v[192:195], v[40:43]
	v_mfma_f32_16x16x32_bf16 v[28:31], v[144:147], v[200:203], v[28:31]
	v_mfma_f32_16x16x32_bf16 v[24:27], v[160:163], v[200:203], v[24:27]
	v_mfma_f32_16x16x32_bf16 v[12:15], v[144:147], v[208:211], v[12:15]
	v_mfma_f32_16x16x32_bf16 v[8:11], v[160:163], v[208:211], v[8:11]
	v_mfma_f32_16x16x32_bf16 v[52:55], v[168:171], v[184:187], v[52:55]
	v_mfma_f32_16x16x32_bf16 v[48:51], v[176:179], v[184:187], v[48:51]
	v_mfma_f32_16x16x32_bf16 v[36:39], v[168:171], v[192:195], v[36:39]
	v_mfma_f32_16x16x32_bf16 v[32:35], v[176:179], v[192:195], v[32:35]
	v_mfma_f32_16x16x32_bf16 v[20:23], v[168:171], v[200:203], v[20:23]
	v_mfma_f32_16x16x32_bf16 v[16:19], v[176:179], v[200:203], v[16:19]
	v_mfma_f32_16x16x32_bf16 v[4:7], v[168:171], v[208:211], v[4:7]
	v_mfma_f32_16x16x32_bf16 v[0:3], v[176:179], v[208:211], v[0:3]
	v_mfma_f32_16x16x32_bf16 v[44:47], v[156:159], v[196:199], v[44:47]
	v_mfma_f32_16x16x32_bf16 v[40:43], v[164:167], v[196:199], v[40:43]
	v_mfma_f32_16x16x32_bf16 v[28:31], v[156:159], v[204:207], v[28:31]
	v_mfma_f32_16x16x32_bf16 v[24:27], v[164:167], v[204:207], v[24:27]
	v_mfma_f32_16x16x32_bf16 v[12:15], v[156:159], v[212:215], v[12:15]
	v_mfma_f32_16x16x32_bf16 v[8:11], v[164:167], v[212:215], v[8:11]
	v_mfma_f32_16x16x32_bf16 v[52:55], v[172:175], v[188:191], v[52:55]
	v_mfma_f32_16x16x32_bf16 v[48:51], v[180:183], v[188:191], v[48:51]
	v_mfma_f32_16x16x32_bf16 v[36:39], v[172:175], v[196:199], v[36:39]
	v_mfma_f32_16x16x32_bf16 v[32:35], v[180:183], v[196:199], v[32:35]
	v_mfma_f32_16x16x32_bf16 v[20:23], v[172:175], v[204:207], v[20:23]
	v_mfma_f32_16x16x32_bf16 v[16:19], v[180:183], v[204:207], v[16:19]
	v_mfma_f32_16x16x32_bf16 v[4:7], v[172:175], v[212:215], v[4:7]
	v_mfma_f32_16x16x32_bf16 v[0:3], v[180:183], v[212:215], v[0:3]
	s_barrier
	s_add_i32 s48, s48, 2
	s_add_u32 s26, s26, 0x100
	s_addc_u32 s27, s27, 0
	s_add_u32 s46, s46, 0x100
	s_addc_u32 s47, s47, 0
	s_cmp_gt_u32 s48, 29
	s_cbranch_scc0 .LBB0_1094
	s_and_b64 vcc, exec, s[12:13]
	s_cbranch_vccz .LBB0_1097
	s_barrier

.LBB0_1178:
	v_add_u32_e32 v153, s95, v161
	ds_read_b128 v[156:159], v153
	ds_read_b128 v[164:167], v153 offset:1024
	ds_read_b128 v[168:171], v153 offset:2048
	ds_read_b128 v[172:175], v153 offset:3072
	v_add_u32_e32 v153, s33, v161
	ds_read_b128 v[176:179], v153
	ds_read_b128 v[180:183], v153 offset:1024
	ds_read_b128 v[184:187], v153 offset:2048
	ds_read_b128 v[188:191], v153 offset:3072
	s_add_u32 s34, s28, 0xfff80080
	s_addc_u32 s35, s29, -1
	s_and_b64 s[30:31], s[30:31], exec
	s_cselect_b32 s35, s23, s35
	s_cselect_b32 s34, s47, s34
	s_cselect_b32 s31, s21, s50
	s_cselect_b32 s30, s48, s49
	s_add_i32 m0, s19, 0xc000
	ds_read_b128 v[192:195], v163
	ds_read_b128 v[196:199], v163 offset:1024
	ds_read_b128 v[200:203], v163 offset:2048
	ds_read_b128 v[204:207], v163 offset:3072
	ds_read_b128 v[208:211], v163 offset:4096
	ds_read_b128 v[212:215], v163 offset:5120
	ds_read_b128 v[216:219], v163 offset:6144
	ds_read_b128 v[222:225], v163 offset:7168
	global_load_lds_dwordx4 v136, s[28:29]
	s_add_i32 m0, s19, 0xe000
	s_nop 0
	global_load_lds_dwordx4 v138, s[28:29]
	s_waitcnt vmcnt(8)
	s_waitcnt lgkmcnt(0)
	s_waitcnt lgkmcnt(0)
	v_mfma_f32_16x16x32_bf16 v[124:127], v[156:159], v[192:195], v[124:127]
	v_mfma_f32_16x16x32_bf16 v[120:123], v[168:171], v[192:195], v[120:123]
	v_mfma_f32_16x16x32_bf16 v[124:127], v[164:167], v[196:199], v[124:127]
	v_mfma_f32_16x16x32_bf16 v[120:123], v[172:175], v[196:199], v[120:123]
	s_barrier
	v_mfma_f32_16x16x32_bf16 v[108:111], v[156:159], v[200:203], v[108:111]
	v_mfma_f32_16x16x32_bf16 v[104:107], v[168:171], v[200:203], v[104:107]
	v_mfma_f32_16x16x32_bf16 v[92:95], v[156:159], v[208:211], v[92:95]
	v_mfma_f32_16x16x32_bf16 v[88:91], v[168:171], v[208:211], v[88:91]
	v_mfma_f32_16x16x32_bf16 v[76:79], v[156:159], v[216:219], v[76:79]
	v_mfma_f32_16x16x32_bf16 v[72:75], v[168:171], v[216:219], v[72:75]
	v_mfma_f32_16x16x32_bf16 v[116:119], v[176:179], v[192:195], v[116:119]
	v_mfma_f32_16x16x32_bf16 v[112:115], v[184:187], v[192:195], v[112:115]
	v_mfma_f32_16x16x32_bf16 v[100:103], v[176:179], v[200:203], v[100:103]
	v_mfma_f32_16x16x32_bf16 v[96:99], v[184:187], v[200:203], v[96:99]
	v_mfma_f32_16x16x32_bf16 v[84:87], v[176:179], v[208:211], v[84:87]
	v_mfma_f32_16x16x32_bf16 v[80:83], v[184:187], v[208:211], v[80:83]
	v_mfma_f32_16x16x32_bf16 v[68:71], v[176:179], v[216:219], v[68:71]
	v_mfma_f32_16x16x32_bf16 v[64:67], v[184:187], v[216:219], v[64:67]
	v_mfma_f32_16x16x32_bf16 v[108:111], v[164:167], v[204:207], v[108:111]
	v_mfma_f32_16x16x32_bf16 v[104:107], v[172:175], v[204:207], v[104:107]
	v_mfma_f32_16x16x32_bf16 v[92:95], v[164:167], v[212:215], v[92:95]
	v_mfma_f32_16x16x32_bf16 v[88:91], v[172:175], v[212:215], v[88:91]
	v_mfma_f32_16x16x32_bf16 v[76:79], v[164:167], v[222:225], v[76:79]
	v_mfma_f32_16x16x32_bf16 v[72:75], v[172:175], v[222:225], v[72:75]
	v_mfma_f32_16x16x32_bf16 v[116:119], v[180:183], v[196:199], v[116:119]
	v_mfma_f32_16x16x32_bf16 v[112:115], v[188:191], v[196:199], v[112:115]
	v_mfma_f32_16x16x32_bf16 v[100:103], v[180:183], v[204:207], v[100:103]
	v_mfma_f32_16x16x32_bf16 v[96:99], v[188:191], v[204:207], v[96:99]
	v_mfma_f32_16x16x32_bf16 v[84:87], v[180:183], v[212:215], v[84:87]
	v_mfma_f32_16x16x32_bf16 v[80:83], v[188:191], v[212:215], v[80:83]
	v_mfma_f32_16x16x32_bf16 v[68:71], v[180:183], v[222:225], v[68:71]
	v_mfma_f32_16x16x32_bf16 v[64:67], v[188:191], v[222:225], v[64:67]
	s_barrier
	s_add_i32 s53, s95, s7
	v_lshl_add_u64 v[226:227], s[30:31], 0, v[132:133]
	s_mov_b32 m0, s53
	ds_read_b128 v[192:195], v163 offset:16384
	ds_read_b128 v[196:199], v163 offset:17408
	ds_read_b128 v[200:203], v163 offset:18432
	ds_read_b128 v[204:207], v163 offset:19456
	ds_read_b128 v[208:211], v163 offset:20480
	ds_read_b128 v[212:215], v163 offset:21504
	ds_read_b128 v[216:219], v163 offset:22528
	ds_read_b128 v[222:225], v163 offset:23552
	global_load_lds_dwordx4 v[226:227], off
	s_add_i32 m0, s53, 0x2000
	s_add_u32 s54, s30, 0x80000
	v_lshl_add_u64 v[228:229], s[30:31], 0, v[128:129]
	s_addc_u32 s55, s31, 0
	s_add_i32 s53, s33, s7
	global_load_lds_dwordx4 v[228:229], off
	s_mov_b32 m0, s53
	v_lshl_add_u64 v[232:233], s[34:35], 0, v[130:131]
	global_load_lds_dwordx4 v132, s[54:55]
	s_add_i32 m0, s53, 0x2000
	s_nop 0
	global_load_lds_dwordx4 v128, s[54:55]
	v_lshl_add_u64 v[230:231], s[34:35], 0, v[134:135]
	s_mov_b32 m0, s19
	s_nop 0
	global_load_lds_dwordx4 v[230:231], off
	s_mov_b32 m0, s36
	s_nop 0
	global_load_lds_dwordx4 v[232:233], off
	s_waitcnt vmcnt(8)
	s_waitcnt lgkmcnt(0)
	s_waitcnt lgkmcnt(0)
	v_mfma_f32_16x16x32_bf16 v[60:63], v[156:159], v[192:195], v[60:63]
	v_mfma_f32_16x16x32_bf16 v[56:59], v[168:171], v[192:195], v[56:59]
	v_mfma_f32_16x16x32_bf16 v[60:63], v[164:167], v[196:199], v[60:63]
	v_mfma_f32_16x16x32_bf16 v[56:59], v[172:175], v[196:199], v[56:59]
	s_barrier
	v_mfma_f32_16x16x32_bf16 v[44:47], v[156:159], v[200:203], v[44:47]
	v_mfma_f32_16x16x32_bf16 v[40:43], v[168:171], v[200:203], v[40:43]
	v_mfma_f32_16x16x32_bf16 v[28:31], v[156:159], v[208:211], v[28:31]
	v_mfma_f32_16x16x32_bf16 v[24:27], v[168:171], v[208:211], v[24:27]
	v_mfma_f32_16x16x32_bf16 v[12:15], v[156:159], v[216:219], v[12:15]
	v_mfma_f32_16x16x32_bf16 v[8:11], v[168:171], v[216:219], v[8:11]
	v_mfma_f32_16x16x32_bf16 v[52:55], v[176:179], v[192:195], v[52:55]
	v_mfma_f32_16x16x32_bf16 v[48:51], v[184:187], v[192:195], v[48:51]
	v_mfma_f32_16x16x32_bf16 v[36:39], v[176:179], v[200:203], v[36:39]
	v_mfma_f32_16x16x32_bf16 v[32:35], v[184:187], v[200:203], v[32:35]
	v_mfma_f32_16x16x32_bf16 v[20:23], v[176:179], v[208:211], v[20:23]
	v_mfma_f32_16x16x32_bf16 v[16:19], v[184:187], v[208:211], v[16:19]
	v_mfma_f32_16x16x32_bf16 v[4:7], v[176:179], v[216:219], v[4:7]
	v_mfma_f32_16x16x32_bf16 v[0:3], v[184:187], v[216:219], v[0:3]
	v_mfma_f32_16x16x32_bf16 v[44:47], v[164:167], v[204:207], v[44:47]
	v_mfma_f32_16x16x32_bf16 v[40:43], v[172:175], v[204:207], v[40:43]
	v_mfma_f32_16x16x32_bf16 v[28:31], v[164:167], v[212:215], v[28:31]
	v_mfma_f32_16x16x32_bf16 v[24:27], v[172:175], v[212:215], v[24:27]
	v_mfma_f32_16x16x32_bf16 v[12:15], v[164:167], v[222:225], v[12:15]
	v_mfma_f32_16x16x32_bf16 v[8:11], v[172:175], v[222:225], v[8:11]
	v_mfma_f32_16x16x32_bf16 v[52:55], v[180:183], v[196:199], v[52:55]
	v_mfma_f32_16x16x32_bf16 v[48:51], v[188:191], v[196:199], v[48:51]
	v_mfma_f32_16x16x32_bf16 v[36:39], v[180:183], v[204:207], v[36:39]
	v_mfma_f32_16x16x32_bf16 v[32:35], v[188:191], v[204:207], v[32:35]
	v_mfma_f32_16x16x32_bf16 v[20:23], v[180:183], v[212:215], v[20:23]
	v_mfma_f32_16x16x32_bf16 v[16:19], v[188:191], v[212:215], v[16:19]
	v_mfma_f32_16x16x32_bf16 v[4:7], v[180:183], v[222:225], v[4:7]
	v_mfma_f32_16x16x32_bf16 v[0:3], v[188:191], v[222:225], v[0:3]
	s_barrier
	v_add_u32_e32 v153, s3, v161
	ds_read_b128 v[156:159], v153
	ds_read_b128 v[164:167], v153 offset:1024
	ds_read_b128 v[168:171], v153 offset:2048
	ds_read_b128 v[172:175], v153 offset:3072
	v_add_u32_e32 v153, s58, v161
	ds_read_b128 v[176:179], v153
	ds_read_b128 v[180:183], v153 offset:1024
	ds_read_b128 v[184:187], v153 offset:2048
	ds_read_b128 v[188:191], v153 offset:3072
	s_add_u32 s34, s34, 0x80000
	s_addc_u32 s35, s35, 0
	s_mov_b32 m0, s37
	ds_read_b128 v[192:195], v163 offset:32768
	ds_read_b128 v[196:199], v163 offset:33792
	ds_read_b128 v[200:203], v163 offset:34816
	ds_read_b128 v[204:207], v163 offset:35840
	ds_read_b128 v[208:211], v163 offset:36864
	ds_read_b128 v[212:215], v163 offset:37888
	ds_read_b128 v[216:219], v163 offset:38912
	ds_read_b128 v[222:225], v163 offset:39936
	global_load_lds_dwordx4 v134, s[34:35]
	s_mov_b32 m0, s38
	s_nop 0
	global_load_lds_dwordx4 v130, s[34:35]
	s_waitcnt vmcnt(8)
	s_waitcnt lgkmcnt(0)
	s_waitcnt lgkmcnt(0)
	v_mfma_f32_16x16x32_bf16 v[124:127], v[156:159], v[192:195], v[124:127]
	v_mfma_f32_16x16x32_bf16 v[120:123], v[168:171], v[192:195], v[120:123]
	v_mfma_f32_16x16x32_bf16 v[124:127], v[164:167], v[196:199], v[124:127]
	v_mfma_f32_16x16x32_bf16 v[120:123], v[172:175], v[196:199], v[120:123]
	s_barrier
	v_mfma_f32_16x16x32_bf16 v[108:111], v[156:159], v[200:203], v[108:111]
	v_mfma_f32_16x16x32_bf16 v[104:107], v[168:171], v[200:203], v[104:107]
	v_mfma_f32_16x16x32_bf16 v[92:95], v[156:159], v[208:211], v[92:95]
	v_mfma_f32_16x16x32_bf16 v[88:91], v[168:171], v[208:211], v[88:91]
	v_mfma_f32_16x16x32_bf16 v[76:79], v[156:159], v[216:219], v[76:79]
	v_mfma_f32_16x16x32_bf16 v[72:75], v[168:171], v[216:219], v[72:75]
	v_mfma_f32_16x16x32_bf16 v[116:119], v[176:179], v[192:195], v[116:119]
	v_mfma_f32_16x16x32_bf16 v[112:115], v[184:187], v[192:195], v[112:115]
	v_mfma_f32_16x16x32_bf16 v[100:103], v[176:179], v[200:203], v[100:103]
	v_mfma_f32_16x16x32_bf16 v[96:99], v[184:187], v[200:203], v[96:99]
	v_mfma_f32_16x16x32_bf16 v[84:87], v[176:179], v[208:211], v[84:87]
	v_mfma_f32_16x16x32_bf16 v[80:83], v[184:187], v[208:211], v[80:83]
	v_mfma_f32_16x16x32_bf16 v[68:71], v[176:179], v[216:219], v[68:71]
	v_mfma_f32_16x16x32_bf16 v[64:67], v[184:187], v[216:219], v[64:67]
	v_mfma_f32_16x16x32_bf16 v[108:111], v[164:167], v[204:207], v[108:111]
	v_mfma_f32_16x16x32_bf16 v[104:107], v[172:175], v[204:207], v[104:107]
	v_mfma_f32_16x16x32_bf16 v[92:95], v[164:167], v[212:215], v[92:95]
	v_mfma_f32_16x16x32_bf16 v[88:91], v[172:175], v[212:215], v[88:91]
	v_mfma_f32_16x16x32_bf16 v[76:79], v[164:167], v[222:225], v[76:79]
	v_mfma_f32_16x16x32_bf16 v[72:75], v[172:175], v[222:225], v[72:75]
	v_mfma_f32_16x16x32_bf16 v[116:119], v[180:183], v[196:199], v[116:119]
	v_mfma_f32_16x16x32_bf16 v[112:115], v[188:191], v[196:199], v[112:115]
	v_mfma_f32_16x16x32_bf16 v[100:103], v[180:183], v[204:207], v[100:103]
	v_mfma_f32_16x16x32_bf16 v[96:99], v[188:191], v[204:207], v[96:99]
	v_mfma_f32_16x16x32_bf16 v[84:87], v[180:183], v[212:215], v[84:87]
	v_mfma_f32_16x16x32_bf16 v[80:83], v[188:191], v[212:215], v[80:83]
	v_mfma_f32_16x16x32_bf16 v[68:71], v[180:183], v[222:225], v[68:71]
	v_mfma_f32_16x16x32_bf16 v[64:67], v[188:191], v[222:225], v[64:67]
	s_barrier
	s_add_i32 s34, s3, s7
	v_lshl_add_u64 v[226:227], v[226:227], 0, s[10:11]
	s_mov_b32 m0, s34
	ds_read_b128 v[192:195], v163 offset:49152
	ds_read_b128 v[196:199], v163 offset:50176
	ds_read_b128 v[200:203], v163 offset:51200
	ds_read_b128 v[204:207], v163 offset:52224
	ds_read_b128 v[208:211], v163 offset:53248
	ds_read_b128 v[212:215], v163 offset:54272
	ds_read_b128 v[216:219], v163 offset:55296
	ds_read_b128 v[222:225], v163 offset:56320
	global_load_lds_dwordx4 v[226:227], off
	s_add_i32 m0, s34, 0x2000
	s_add_u32 s30, s30, 0x80080
	v_lshl_add_u64 v[226:227], v[228:229], 0, s[10:11]
	s_addc_u32 s31, s31, 0
	s_add_i32 s34, s58, s7
	global_load_lds_dwordx4 v[226:227], off
	s_mov_b32 m0, s34
	s_nop 0
	global_load_lds_dwordx4 v132, s[30:31]
	s_add_i32 m0, s34, 0x2000
	s_nop 0
	global_load_lds_dwordx4 v128, s[30:31]
	v_lshl_add_u64 v[226:227], v[230:231], 0, s[10:11]
	s_mov_b32 m0, s40
	s_nop 0
	global_load_lds_dwordx4 v[226:227], off
	v_lshl_add_u64 v[226:227], v[232:233], 0, s[10:11]
	s_mov_b32 m0, s41
	s_nop 0
	global_load_lds_dwordx4 v[226:227], off
	s_waitcnt vmcnt(8)
	s_waitcnt lgkmcnt(0)
	s_waitcnt lgkmcnt(0)
	v_mfma_f32_16x16x32_bf16 v[60:63], v[156:159], v[192:195], v[60:63]
	v_mfma_f32_16x16x32_bf16 v[56:59], v[168:171], v[192:195], v[56:59]
	v_mfma_f32_16x16x32_bf16 v[60:63], v[164:167], v[196:199], v[60:63]
	v_mfma_f32_16x16x32_bf16 v[56:59], v[172:175], v[196:199], v[56:59]
	s_barrier
	v_mfma_f32_16x16x32_bf16 v[44:47], v[156:159], v[200:203], v[44:47]
	v_mfma_f32_16x16x32_bf16 v[40:43], v[168:171], v[200:203], v[40:43]
	v_mfma_f32_16x16x32_bf16 v[28:31], v[156:159], v[208:211], v[28:31]
	v_mfma_f32_16x16x32_bf16 v[24:27], v[168:171], v[208:211], v[24:27]
	v_mfma_f32_16x16x32_bf16 v[12:15], v[156:159], v[216:219], v[12:15]
	v_mfma_f32_16x16x32_bf16 v[8:11], v[168:171], v[216:219], v[8:11]
	v_mfma_f32_16x16x32_bf16 v[52:55], v[176:179], v[192:195], v[52:55]
	v_mfma_f32_16x16x32_bf16 v[48:51], v[184:187], v[192:195], v[48:51]
	v_mfma_f32_16x16x32_bf16 v[36:39], v[176:179], v[200:203], v[36:39]
	v_mfma_f32_16x16x32_bf16 v[32:35], v[184:187], v[200:203], v[32:35]
	v_mfma_f32_16x16x32_bf16 v[20:23], v[176:179], v[208:211], v[20:23]
	v_mfma_f32_16x16x32_bf16 v[16:19], v[184:187], v[208:211], v[16:19]
	v_mfma_f32_16x16x32_bf16 v[4:7], v[176:179], v[216:219], v[4:7]
	v_mfma_f32_16x16x32_bf16 v[0:3], v[184:187], v[216:219], v[0:3]
	v_mfma_f32_16x16x32_bf16 v[44:47], v[164:167], v[204:207], v[44:47]
	v_mfma_f32_16x16x32_bf16 v[40:43], v[172:175], v[204:207], v[40:43]
	v_mfma_f32_16x16x32_bf16 v[28:31], v[164:167], v[212:215], v[28:31]
	v_mfma_f32_16x16x32_bf16 v[24:27], v[172:175], v[212:215], v[24:27]
	v_mfma_f32_16x16x32_bf16 v[12:15], v[164:167], v[222:225], v[12:15]
	v_mfma_f32_16x16x32_bf16 v[8:11], v[172:175], v[222:225], v[8:11]
	v_mfma_f32_16x16x32_bf16 v[52:55], v[180:183], v[196:199], v[52:55]
	v_mfma_f32_16x16x32_bf16 v[48:51], v[188:191], v[196:199], v[48:51]
	v_mfma_f32_16x16x32_bf16 v[36:39], v[180:183], v[204:207], v[36:39]
	v_mfma_f32_16x16x32_bf16 v[32:35], v[188:191], v[204:207], v[32:35]
	v_mfma_f32_16x16x32_bf16 v[20:23], v[180:183], v[212:215], v[20:23]
	v_mfma_f32_16x16x32_bf16 v[16:19], v[188:191], v[212:215], v[16:19]
	v_mfma_f32_16x16x32_bf16 v[4:7], v[180:183], v[222:225], v[4:7]
	v_mfma_f32_16x16x32_bf16 v[0:3], v[188:191], v[222:225], v[0:3]
	s_barrier
	s_add_i32 s51, s51, 2
	s_add_u32 s28, s28, 0x100
	s_addc_u32 s29, s29, 0
	s_add_u32 s49, s49, 0x100
	s_addc_u32 s50, s50, 0
	s_cmp_gt_u32 s51, 29
	s_cbranch_scc1 .LBB0_1181

.LBB0_1294:
	ds_read_b128 v[144:147], v151
	ds_read_b128 v[156:159], v151 offset:1024
	ds_read_b128 v[160:163], v151 offset:2048
	ds_read_b128 v[164:167], v151 offset:3072
	ds_read_b128 v[168:171], v152
	ds_read_b128 v[172:175], v152 offset:1024
	ds_read_b128 v[176:179], v152 offset:2048
	ds_read_b128 v[180:183], v152 offset:3072
	s_add_u32 s22, s20, 0x100
	s_addc_u32 s23, s21, 0
	s_cmpk_eq_i32 s46, 0x54
	s_cselect_b32 s27, s1, s23
	s_cselect_b32 s26, s0, s22
	s_cselect_b32 s25, s19, s45
	s_cselect_b32 s24, s18, s44
	v_lshl_add_u64 v[216:217], s[20:21], 0, v[136:137]
	s_add_i32 m0, s28, 0xc000
	ds_read_b128 v[184:187], v153
	ds_read_b128 v[188:191], v153 offset:1024
	ds_read_b128 v[192:195], v153 offset:2048
	ds_read_b128 v[196:199], v153 offset:3072
	ds_read_b128 v[200:203], v153 offset:4096
	ds_read_b128 v[204:207], v153 offset:5120
	ds_read_b128 v[208:211], v153 offset:6144
	ds_read_b128 v[212:215], v153 offset:7168
	global_load_lds_dwordx4 v[216:217], off
	v_lshl_add_u64 v[216:217], s[20:21], 0, v[138:139]
	s_add_i32 m0, s28, 0xe000
	s_nop 0
	global_load_lds_dwordx4 v[216:217], off
	s_waitcnt vmcnt(8)
	s_waitcnt lgkmcnt(0)
	s_waitcnt lgkmcnt(0)
	v_mfma_f32_16x16x32_bf16 v[124:127], v[144:147], v[184:187], v[124:127]
	v_mfma_f32_16x16x32_bf16 v[120:123], v[160:163], v[184:187], v[120:123]
	v_mfma_f32_16x16x32_bf16 v[124:127], v[156:159], v[188:191], v[124:127]
	v_mfma_f32_16x16x32_bf16 v[120:123], v[164:167], v[188:191], v[120:123]
	s_barrier
	v_mfma_f32_16x16x32_bf16 v[108:111], v[144:147], v[192:195], v[108:111]
	v_mfma_f32_16x16x32_bf16 v[104:107], v[160:163], v[192:195], v[104:107]
	v_mfma_f32_16x16x32_bf16 v[92:95], v[144:147], v[200:203], v[92:95]
	v_mfma_f32_16x16x32_bf16 v[88:91], v[160:163], v[200:203], v[88:91]
	v_mfma_f32_16x16x32_bf16 v[76:79], v[144:147], v[208:211], v[76:79]
	v_mfma_f32_16x16x32_bf16 v[72:75], v[160:163], v[208:211], v[72:75]
	v_mfma_f32_16x16x32_bf16 v[116:119], v[168:171], v[184:187], v[116:119]
	v_mfma_f32_16x16x32_bf16 v[112:115], v[176:179], v[184:187], v[112:115]
	v_mfma_f32_16x16x32_bf16 v[100:103], v[168:171], v[192:195], v[100:103]
	v_mfma_f32_16x16x32_bf16 v[96:99], v[176:179], v[192:195], v[96:99]
	v_mfma_f32_16x16x32_bf16 v[84:87], v[168:171], v[200:203], v[84:87]
	v_mfma_f32_16x16x32_bf16 v[80:83], v[176:179], v[200:203], v[80:83]
	v_mfma_f32_16x16x32_bf16 v[68:71], v[168:171], v[208:211], v[68:71]
	v_mfma_f32_16x16x32_bf16 v[64:67], v[176:179], v[208:211], v[64:67]
	v_mfma_f32_16x16x32_bf16 v[108:111], v[156:159], v[196:199], v[108:111]
	v_mfma_f32_16x16x32_bf16 v[104:107], v[164:167], v[196:199], v[104:107]
	v_mfma_f32_16x16x32_bf16 v[92:95], v[156:159], v[204:207], v[92:95]
	v_mfma_f32_16x16x32_bf16 v[88:91], v[164:167], v[204:207], v[88:91]
	v_mfma_f32_16x16x32_bf16 v[76:79], v[156:159], v[212:215], v[76:79]
	v_mfma_f32_16x16x32_bf16 v[72:75], v[164:167], v[212:215], v[72:75]
	v_mfma_f32_16x16x32_bf16 v[116:119], v[172:175], v[188:191], v[116:119]
	v_mfma_f32_16x16x32_bf16 v[112:115], v[180:183], v[188:191], v[112:115]
	v_mfma_f32_16x16x32_bf16 v[100:103], v[172:175], v[196:199], v[100:103]
	v_mfma_f32_16x16x32_bf16 v[96:99], v[180:183], v[196:199], v[96:99]
	v_mfma_f32_16x16x32_bf16 v[84:87], v[172:175], v[204:207], v[84:87]
	v_mfma_f32_16x16x32_bf16 v[80:83], v[180:183], v[204:207], v[80:83]
	v_mfma_f32_16x16x32_bf16 v[68:71], v[172:175], v[212:215], v[68:71]
	v_mfma_f32_16x16x32_bf16 v[64:67], v[180:183], v[212:215], v[64:67]
	s_barrier
	s_add_i32 s20, s95, s7
	v_lshl_add_u64 v[216:217], s[24:25], 0, v[130:131]
	s_mov_b32 m0, s20
	ds_read_b128 v[184:187], v153 offset:16384
	ds_read_b128 v[188:191], v153 offset:17408
	ds_read_b128 v[192:195], v153 offset:18432
	ds_read_b128 v[196:199], v153 offset:19456
	ds_read_b128 v[200:203], v153 offset:20480
	ds_read_b128 v[204:207], v153 offset:21504
	ds_read_b128 v[208:211], v153 offset:22528
	ds_read_b128 v[212:215], v153 offset:23552
	global_load_lds_dwordx4 v[216:217], off
	s_add_i32 m0, s20, 0x2000
	s_add_u32 s20, s24, 0x160000
	v_lshl_add_u64 v[218:219], s[24:25], 0, v[134:135]
	s_addc_u32 s21, s25, 0
	s_add_i32 s47, s33, s7
	global_load_lds_dwordx4 v[218:219], off
	s_mov_b32 m0, s47
	v_lshl_add_u64 v[224:225], s[26:27], 0, v[132:133]
	global_load_lds_dwordx4 v130, s[20:21]
	s_add_i32 m0, s47, 0x2000
	s_nop 0
	global_load_lds_dwordx4 v134, s[20:21]
	v_lshl_add_u64 v[222:223], s[26:27], 0, v[128:129]
	s_mov_b32 m0, s28
	s_nop 0
	global_load_lds_dwordx4 v[222:223], off
	s_mov_b32 m0, s29
	s_nop 0
	global_load_lds_dwordx4 v[224:225], off
	s_waitcnt vmcnt(8)
	s_waitcnt lgkmcnt(0)
	s_waitcnt lgkmcnt(0)
	v_mfma_f32_16x16x32_bf16 v[60:63], v[144:147], v[184:187], v[60:63]
	v_mfma_f32_16x16x32_bf16 v[56:59], v[160:163], v[184:187], v[56:59]
	v_mfma_f32_16x16x32_bf16 v[60:63], v[156:159], v[188:191], v[60:63]
	v_mfma_f32_16x16x32_bf16 v[56:59], v[164:167], v[188:191], v[56:59]
	s_barrier
	v_mfma_f32_16x16x32_bf16 v[44:47], v[144:147], v[192:195], v[44:47]
	v_mfma_f32_16x16x32_bf16 v[40:43], v[160:163], v[192:195], v[40:43]
	v_mfma_f32_16x16x32_bf16 v[28:31], v[144:147], v[200:203], v[28:31]
	v_mfma_f32_16x16x32_bf16 v[24:27], v[160:163], v[200:203], v[24:27]
	v_mfma_f32_16x16x32_bf16 v[12:15], v[144:147], v[208:211], v[12:15]
	v_mfma_f32_16x16x32_bf16 v[8:11], v[160:163], v[208:211], v[8:11]
	v_mfma_f32_16x16x32_bf16 v[52:55], v[168:171], v[184:187], v[52:55]
	v_mfma_f32_16x16x32_bf16 v[48:51], v[176:179], v[184:187], v[48:51]
	v_mfma_f32_16x16x32_bf16 v[36:39], v[168:171], v[192:195], v[36:39]
	v_mfma_f32_16x16x32_bf16 v[32:35], v[176:179], v[192:195], v[32:35]
	v_mfma_f32_16x16x32_bf16 v[20:23], v[168:171], v[200:203], v[20:23]
	v_mfma_f32_16x16x32_bf16 v[16:19], v[176:179], v[200:203], v[16:19]
	v_mfma_f32_16x16x32_bf16 v[4:7], v[168:171], v[208:211], v[4:7]
	v_mfma_f32_16x16x32_bf16 v[0:3], v[176:179], v[208:211], v[0:3]
	v_mfma_f32_16x16x32_bf16 v[44:47], v[156:159], v[196:199], v[44:47]
	v_mfma_f32_16x16x32_bf16 v[40:43], v[164:167], v[196:199], v[40:43]
	v_mfma_f32_16x16x32_bf16 v[28:31], v[156:159], v[204:207], v[28:31]
	v_mfma_f32_16x16x32_bf16 v[24:27], v[164:167], v[204:207], v[24:27]
	v_mfma_f32_16x16x32_bf16 v[12:15], v[156:159], v[212:215], v[12:15]
	v_mfma_f32_16x16x32_bf16 v[8:11], v[164:167], v[212:215], v[8:11]
	v_mfma_f32_16x16x32_bf16 v[52:55], v[172:175], v[188:191], v[52:55]
	v_mfma_f32_16x16x32_bf16 v[48:51], v[180:183], v[188:191], v[48:51]
	v_mfma_f32_16x16x32_bf16 v[36:39], v[172:175], v[196:199], v[36:39]
	v_mfma_f32_16x16x32_bf16 v[32:35], v[180:183], v[196:199], v[32:35]
	v_mfma_f32_16x16x32_bf16 v[20:23], v[172:175], v[204:207], v[20:23]
	v_mfma_f32_16x16x32_bf16 v[16:19], v[180:183], v[204:207], v[16:19]
	v_mfma_f32_16x16x32_bf16 v[4:7], v[172:175], v[212:215], v[4:7]
	v_mfma_f32_16x16x32_bf16 v[0:3], v[180:183], v[212:215], v[0:3]
	s_barrier
	v_add_u32_e32 v155, s3, v149
	ds_read_b128 v[144:147], v155
	ds_read_b128 v[156:159], v155 offset:1024
	ds_read_b128 v[160:163], v155 offset:2048
	ds_read_b128 v[164:167], v155 offset:3072
	v_add_u32_e32 v155, s58, v149
	ds_read_b128 v[168:171], v155
	ds_read_b128 v[172:175], v155 offset:1024
	ds_read_b128 v[176:179], v155 offset:2048
	ds_read_b128 v[180:183], v155 offset:3072
	s_add_u32 s20, s26, 0x160000
	s_addc_u32 s21, s27, 0
	s_mov_b32 m0, s30
	ds_read_b128 v[184:187], v153 offset:32768
	ds_read_b128 v[188:191], v153 offset:33792
	ds_read_b128 v[192:195], v153 offset:34816
	ds_read_b128 v[196:199], v153 offset:35840
	ds_read_b128 v[200:203], v153 offset:36864
	ds_read_b128 v[204:207], v153 offset:37888
	ds_read_b128 v[208:211], v153 offset:38912
	ds_read_b128 v[212:215], v153 offset:39936
	global_load_lds_dwordx4 v128, s[20:21]
	s_mov_b32 m0, s31
	s_nop 0
	global_load_lds_dwordx4 v132, s[20:21]
	s_waitcnt vmcnt(8)
	s_waitcnt lgkmcnt(0)
	s_waitcnt lgkmcnt(0)
	v_mfma_f32_16x16x32_bf16 v[124:127], v[144:147], v[184:187], v[124:127]
	v_mfma_f32_16x16x32_bf16 v[120:123], v[160:163], v[184:187], v[120:123]
	v_mfma_f32_16x16x32_bf16 v[124:127], v[156:159], v[188:191], v[124:127]
	v_mfma_f32_16x16x32_bf16 v[120:123], v[164:167], v[188:191], v[120:123]
	s_barrier
	v_mfma_f32_16x16x32_bf16 v[108:111], v[144:147], v[192:195], v[108:111]
	v_mfma_f32_16x16x32_bf16 v[104:107], v[160:163], v[192:195], v[104:107]
	v_mfma_f32_16x16x32_bf16 v[92:95], v[144:147], v[200:203], v[92:95]
	v_mfma_f32_16x16x32_bf16 v[88:91], v[160:163], v[200:203], v[88:91]
	v_mfma_f32_16x16x32_bf16 v[76:79], v[144:147], v[208:211], v[76:79]
	v_mfma_f32_16x16x32_bf16 v[72:75], v[160:163], v[208:211], v[72:75]
	v_mfma_f32_16x16x32_bf16 v[116:119], v[168:171], v[184:187], v[116:119]
	v_mfma_f32_16x16x32_bf16 v[112:115], v[176:179], v[184:187], v[112:115]
	v_mfma_f32_16x16x32_bf16 v[100:103], v[168:171], v[192:195], v[100:103]
	v_mfma_f32_16x16x32_bf16 v[96:99], v[176:179], v[192:195], v[96:99]
	v_mfma_f32_16x16x32_bf16 v[84:87], v[168:171], v[200:203], v[84:87]
	v_mfma_f32_16x16x32_bf16 v[80:83], v[176:179], v[200:203], v[80:83]
	v_mfma_f32_16x16x32_bf16 v[68:71], v[168:171], v[208:211], v[68:71]
	v_mfma_f32_16x16x32_bf16 v[64:67], v[176:179], v[208:211], v[64:67]
	v_mfma_f32_16x16x32_bf16 v[108:111], v[156:159], v[196:199], v[108:111]
	v_mfma_f32_16x16x32_bf16 v[104:107], v[164:167], v[196:199], v[104:107]
	v_mfma_f32_16x16x32_bf16 v[92:95], v[156:159], v[204:207], v[92:95]
	v_mfma_f32_16x16x32_bf16 v[88:91], v[164:167], v[204:207], v[88:91]
	v_mfma_f32_16x16x32_bf16 v[76:79], v[156:159], v[212:215], v[76:79]
	v_mfma_f32_16x16x32_bf16 v[72:75], v[164:167], v[212:215], v[72:75]
	v_mfma_f32_16x16x32_bf16 v[116:119], v[172:175], v[188:191], v[116:119]
	v_mfma_f32_16x16x32_bf16 v[112:115], v[180:183], v[188:191], v[112:115]
	v_mfma_f32_16x16x32_bf16 v[100:103], v[172:175], v[196:199], v[100:103]
	v_mfma_f32_16x16x32_bf16 v[96:99], v[180:183], v[196:199], v[96:99]
	v_mfma_f32_16x16x32_bf16 v[84:87], v[172:175], v[204:207], v[84:87]
	v_mfma_f32_16x16x32_bf16 v[80:83], v[180:183], v[204:207], v[80:83]
	v_mfma_f32_16x16x32_bf16 v[68:71], v[172:175], v[212:215], v[68:71]
	v_mfma_f32_16x16x32_bf16 v[64:67], v[180:183], v[212:215], v[64:67]
	s_barrier
	s_add_i32 s20, s3, s7
	v_lshl_add_u64 v[216:217], v[216:217], 0, s[14:15]
	s_mov_b32 m0, s20
	ds_read_b128 v[184:187], v153 offset:49152
	ds_read_b128 v[188:191], v153 offset:50176
	ds_read_b128 v[192:195], v153 offset:51200
	ds_read_b128 v[196:199], v153 offset:52224
	ds_read_b128 v[200:203], v153 offset:53248
	ds_read_b128 v[204:207], v153 offset:54272
	ds_read_b128 v[208:211], v153 offset:55296
	ds_read_b128 v[212:215], v153 offset:56320
	global_load_lds_dwordx4 v[216:217], off
	s_add_i32 m0, s20, 0x2000
	s_add_u32 s20, s24, 0x160080
	v_lshl_add_u64 v[216:217], v[218:219], 0, s[14:15]
	s_addc_u32 s21, s25, 0
	s_add_i32 s24, s58, s7
	global_load_lds_dwordx4 v[216:217], off
	s_mov_b32 m0, s24
	s_nop 0
	global_load_lds_dwordx4 v130, s[20:21]
	s_add_i32 m0, s24, 0x2000
	s_nop 0
	global_load_lds_dwordx4 v134, s[20:21]
	v_lshl_add_u64 v[216:217], v[222:223], 0, s[14:15]
	s_mov_b32 m0, s35
	s_nop 0
	global_load_lds_dwordx4 v[216:217], off
	v_lshl_add_u64 v[216:217], v[224:225], 0, s[14:15]
	s_mov_b32 m0, s36
	s_nop 0
	global_load_lds_dwordx4 v[216:217], off
	s_waitcnt vmcnt(8)
	s_waitcnt lgkmcnt(0)
	s_waitcnt lgkmcnt(0)
	v_mfma_f32_16x16x32_bf16 v[60:63], v[144:147], v[184:187], v[60:63]
	v_mfma_f32_16x16x32_bf16 v[56:59], v[160:163], v[184:187], v[56:59]
	v_mfma_f32_16x16x32_bf16 v[60:63], v[156:159], v[188:191], v[60:63]
	v_mfma_f32_16x16x32_bf16 v[56:59], v[164:167], v[188:191], v[56:59]
	s_barrier
	v_mfma_f32_16x16x32_bf16 v[44:47], v[144:147], v[192:195], v[44:47]
	v_mfma_f32_16x16x32_bf16 v[40:43], v[160:163], v[192:195], v[40:43]
	v_mfma_f32_16x16x32_bf16 v[28:31], v[144:147], v[200:203], v[28:31]
	v_mfma_f32_16x16x32_bf16 v[24:27], v[160:163], v[200:203], v[24:27]
	v_mfma_f32_16x16x32_bf16 v[12:15], v[144:147], v[208:211], v[12:15]
	v_mfma_f32_16x16x32_bf16 v[8:11], v[160:163], v[208:211], v[8:11]
	v_mfma_f32_16x16x32_bf16 v[52:55], v[168:171], v[184:187], v[52:55]
	v_mfma_f32_16x16x32_bf16 v[48:51], v[176:179], v[184:187], v[48:51]
	v_mfma_f32_16x16x32_bf16 v[36:39], v[168:171], v[192:195], v[36:39]
	v_mfma_f32_16x16x32_bf16 v[32:35], v[176:179], v[192:195], v[32:35]
	v_mfma_f32_16x16x32_bf16 v[20:23], v[168:171], v[200:203], v[20:23]
	v_mfma_f32_16x16x32_bf16 v[16:19], v[176:179], v[200:203], v[16:19]
	v_mfma_f32_16x16x32_bf16 v[4:7], v[168:171], v[208:211], v[4:7]
	v_mfma_f32_16x16x32_bf16 v[0:3], v[176:179], v[208:211], v[0:3]
	v_mfma_f32_16x16x32_bf16 v[44:47], v[156:159], v[196:199], v[44:47]
	v_mfma_f32_16x16x32_bf16 v[40:43], v[164:167], v[196:199], v[40:43]
	v_mfma_f32_16x16x32_bf16 v[28:31], v[156:159], v[204:207], v[28:31]
	v_mfma_f32_16x16x32_bf16 v[24:27], v[164:167], v[204:207], v[24:27]
	v_mfma_f32_16x16x32_bf16 v[12:15], v[156:159], v[212:215], v[12:15]
	v_mfma_f32_16x16x32_bf16 v[8:11], v[164:167], v[212:215], v[8:11]
	v_mfma_f32_16x16x32_bf16 v[52:55], v[172:175], v[188:191], v[52:55]
	v_mfma_f32_16x16x32_bf16 v[48:51], v[180:183], v[188:191], v[48:51]
	v_mfma_f32_16x16x32_bf16 v[36:39], v[172:175], v[196:199], v[36:39]
	v_mfma_f32_16x16x32_bf16 v[32:35], v[180:183], v[196:199], v[32:35]
	v_mfma_f32_16x16x32_bf16 v[20:23], v[172:175], v[204:207], v[20:23]
	v_mfma_f32_16x16x32_bf16 v[16:19], v[180:183], v[204:207], v[16:19]
	v_mfma_f32_16x16x32_bf16 v[4:7], v[172:175], v[212:215], v[4:7]
	v_mfma_f32_16x16x32_bf16 v[0:3], v[180:183], v[212:215], v[0:3]
	s_barrier
	s_add_i32 s46, s46, 2
	s_add_u32 s44, s44, 0x100
	s_addc_u32 s45, s45, 0
	s_cmpk_gt_u32 s46, 0x55
	s_mov_b64 s[20:21], s[22:23]
	s_cbranch_scc0 .LBB0_1294
	s_and_b64 vcc, exec, s[16:17]
	s_cbranch_vccz .LBB0_1297
	s_barrier

.LBB0_1386:
	v_add_u32_e32 v156, s95, v159
	ds_read_b128 v[162:165], v156
	ds_read_b128 v[166:169], v156 offset:1024
	ds_read_b128 v[170:173], v156 offset:2048
	ds_read_b128 v[174:177], v156 offset:3072
	v_add_u32_e32 v156, s33, v159
	ds_read_b128 v[178:181], v156
	ds_read_b128 v[182:185], v156 offset:1024
	ds_read_b128 v[186:189], v156 offset:2048
	ds_read_b128 v[190:193], v156 offset:3072
	s_add_u32 s38, s34, 0xfff80080
	s_addc_u32 s39, s35, -1
	s_and_b64 s[36:37], s[36:37], exec
	s_cselect_b32 s39, s27, s39
	s_cselect_b32 s38, s53, s38
	s_cselect_b32 s37, s25, s56
	s_cselect_b32 s36, s54, s55
	s_add_i32 m0, s7, 0xc000
	ds_read_b128 v[194:197], v161
	ds_read_b128 v[198:201], v161 offset:1024
	ds_read_b128 v[202:205], v161 offset:2048
	ds_read_b128 v[206:209], v161 offset:3072
	ds_read_b128 v[210:213], v161 offset:4096
	ds_read_b128 v[214:217], v161 offset:5120
	ds_read_b128 v[222:225], v161 offset:6144
	ds_read_b128 v[226:229], v161 offset:7168
	global_load_lds_dwordx4 v136, s[34:35]
	s_add_i32 m0, s7, 0xe000
	s_nop 0
	global_load_lds_dwordx4 v138, s[34:35]
	s_waitcnt vmcnt(8)
	s_waitcnt lgkmcnt(0)
	s_waitcnt lgkmcnt(0)
	v_mfma_f32_16x16x32_bf16 v[124:127], v[162:165], v[194:197], v[124:127]
	v_mfma_f32_16x16x32_bf16 v[120:123], v[170:173], v[194:197], v[120:123]
	v_mfma_f32_16x16x32_bf16 v[124:127], v[166:169], v[198:201], v[124:127]
	v_mfma_f32_16x16x32_bf16 v[120:123], v[174:177], v[198:201], v[120:123]
	s_barrier
	v_mfma_f32_16x16x32_bf16 v[116:119], v[162:165], v[202:205], v[116:119]
	v_mfma_f32_16x16x32_bf16 v[104:107], v[170:173], v[202:205], v[104:107]
	v_mfma_f32_16x16x32_bf16 v[92:95], v[162:165], v[210:213], v[92:95]
	v_mfma_f32_16x16x32_bf16 v[88:91], v[170:173], v[210:213], v[88:91]
	v_mfma_f32_16x16x32_bf16 v[84:87], v[162:165], v[222:225], v[84:87]
	v_mfma_f32_16x16x32_bf16 v[72:75], v[170:173], v[222:225], v[72:75]
	v_mfma_f32_16x16x32_bf16 v[112:115], v[178:181], v[194:197], v[112:115]
	v_mfma_f32_16x16x32_bf16 v[108:111], v[186:189], v[194:197], v[108:111]
	v_mfma_f32_16x16x32_bf16 v[100:103], v[178:181], v[202:205], v[100:103]
	v_mfma_f32_16x16x32_bf16 v[96:99], v[186:189], v[202:205], v[96:99]
	v_mfma_f32_16x16x32_bf16 v[80:83], v[178:181], v[210:213], v[80:83]
	v_mfma_f32_16x16x32_bf16 v[76:79], v[186:189], v[210:213], v[76:79]
	v_mfma_f32_16x16x32_bf16 v[68:71], v[178:181], v[222:225], v[68:71]
	v_mfma_f32_16x16x32_bf16 v[64:67], v[186:189], v[222:225], v[64:67]
	v_mfma_f32_16x16x32_bf16 v[116:119], v[166:169], v[206:209], v[116:119]
	v_mfma_f32_16x16x32_bf16 v[104:107], v[174:177], v[206:209], v[104:107]
	v_mfma_f32_16x16x32_bf16 v[92:95], v[166:169], v[214:217], v[92:95]
	v_mfma_f32_16x16x32_bf16 v[88:91], v[174:177], v[214:217], v[88:91]
	v_mfma_f32_16x16x32_bf16 v[84:87], v[166:169], v[226:229], v[84:87]
	v_mfma_f32_16x16x32_bf16 v[72:75], v[174:177], v[226:229], v[72:75]
	v_mfma_f32_16x16x32_bf16 v[112:115], v[182:185], v[198:201], v[112:115]
	v_mfma_f32_16x16x32_bf16 v[108:111], v[190:193], v[198:201], v[108:111]
	v_mfma_f32_16x16x32_bf16 v[100:103], v[182:185], v[206:209], v[100:103]
	v_mfma_f32_16x16x32_bf16 v[96:99], v[190:193], v[206:209], v[96:99]
	v_mfma_f32_16x16x32_bf16 v[80:83], v[182:185], v[214:217], v[80:83]
	v_mfma_f32_16x16x32_bf16 v[76:79], v[190:193], v[214:217], v[76:79]
	v_mfma_f32_16x16x32_bf16 v[68:71], v[182:185], v[226:229], v[68:71]
	v_mfma_f32_16x16x32_bf16 v[64:67], v[190:193], v[226:229], v[64:67]
	s_barrier
	s_add_i32 s59, s95, s6
	v_lshl_add_u64 v[156:157], s[36:37], 0, v[130:131]
	s_mov_b32 m0, s59
	ds_read_b128 v[194:197], v161 offset:16384
	ds_read_b128 v[198:201], v161 offset:17408
	ds_read_b128 v[202:205], v161 offset:18432
	ds_read_b128 v[206:209], v161 offset:19456
	ds_read_b128 v[210:213], v161 offset:20480
	ds_read_b128 v[214:217], v161 offset:21504
	ds_read_b128 v[222:225], v161 offset:22528
	ds_read_b128 v[226:229], v161 offset:23552
	global_load_lds_dwordx4 v[156:157], off
	s_add_i32 m0, s59, 0x2000
	s_add_u32 s62, s36, 0x80000
	v_lshl_add_u64 v[218:219], s[36:37], 0, v[134:135]
	s_addc_u32 s63, s37, 0
	s_add_i32 s59, s33, s6
	global_load_lds_dwordx4 v[218:219], off
	s_mov_b32 m0, s59
	v_lshl_add_u64 v[232:233], s[38:39], 0, v[132:133]
	global_load_lds_dwordx4 v130, s[62:63]
	s_add_i32 m0, s59, 0x2000
	s_nop 0
	global_load_lds_dwordx4 v134, s[62:63]
	v_lshl_add_u64 v[230:231], s[38:39], 0, v[128:129]
	s_mov_b32 m0, s7
	s_nop 0
	global_load_lds_dwordx4 v[230:231], off
	s_mov_b32 m0, s17
	s_nop 0
	global_load_lds_dwordx4 v[232:233], off
	s_waitcnt vmcnt(8)
	s_waitcnt lgkmcnt(0)
	s_waitcnt lgkmcnt(0)
	v_mfma_f32_16x16x32_bf16 v[60:63], v[162:165], v[194:197], v[60:63]
	v_mfma_f32_16x16x32_bf16 v[56:59], v[170:173], v[194:197], v[56:59]
	v_mfma_f32_16x16x32_bf16 v[60:63], v[166:169], v[198:201], v[60:63]
	v_mfma_f32_16x16x32_bf16 v[56:59], v[174:177], v[198:201], v[56:59]
	s_barrier
	v_mfma_f32_16x16x32_bf16 v[52:55], v[162:165], v[202:205], v[52:55]
	v_mfma_f32_16x16x32_bf16 v[44:47], v[170:173], v[202:205], v[44:47]
	v_mfma_f32_16x16x32_bf16 v[32:35], v[162:165], v[210:213], v[32:35]
	v_mfma_f32_16x16x32_bf16 v[24:27], v[170:173], v[210:213], v[24:27]
	v_mfma_f32_16x16x32_bf16 v[20:23], v[162:165], v[222:225], v[20:23]
	v_mfma_f32_16x16x32_bf16 v[12:15], v[170:173], v[222:225], v[12:15]
	v_mfma_f32_16x16x32_bf16 v[48:51], v[178:181], v[194:197], v[48:51]
	v_mfma_f32_16x16x32_bf16 v[40:43], v[186:189], v[194:197], v[40:43]
	v_mfma_f32_16x16x32_bf16 v[36:39], v[178:181], v[202:205], v[36:39]
	v_mfma_f32_16x16x32_bf16 v[28:31], v[186:189], v[202:205], v[28:31]
	v_mfma_f32_16x16x32_bf16 v[16:19], v[178:181], v[210:213], v[16:19]
	v_mfma_f32_16x16x32_bf16 v[8:11], v[186:189], v[210:213], v[8:11]
	v_mfma_f32_16x16x32_bf16 v[4:7], v[178:181], v[222:225], v[4:7]
	v_mfma_f32_16x16x32_bf16 v[0:3], v[186:189], v[222:225], v[0:3]
	v_mfma_f32_16x16x32_bf16 v[52:55], v[166:169], v[206:209], v[52:55]
	v_mfma_f32_16x16x32_bf16 v[44:47], v[174:177], v[206:209], v[44:47]
	v_mfma_f32_16x16x32_bf16 v[32:35], v[166:169], v[214:217], v[32:35]
	v_mfma_f32_16x16x32_bf16 v[24:27], v[174:177], v[214:217], v[24:27]
	v_mfma_f32_16x16x32_bf16 v[20:23], v[166:169], v[226:229], v[20:23]
	v_mfma_f32_16x16x32_bf16 v[12:15], v[174:177], v[226:229], v[12:15]
	v_mfma_f32_16x16x32_bf16 v[48:51], v[182:185], v[198:201], v[48:51]
	v_mfma_f32_16x16x32_bf16 v[40:43], v[190:193], v[198:201], v[40:43]
	v_mfma_f32_16x16x32_bf16 v[36:39], v[182:185], v[206:209], v[36:39]
	v_mfma_f32_16x16x32_bf16 v[28:31], v[190:193], v[206:209], v[28:31]
	v_mfma_f32_16x16x32_bf16 v[16:19], v[182:185], v[214:217], v[16:19]
	v_mfma_f32_16x16x32_bf16 v[8:11], v[190:193], v[214:217], v[8:11]
	v_mfma_f32_16x16x32_bf16 v[4:7], v[182:185], v[226:229], v[4:7]
	v_mfma_f32_16x16x32_bf16 v[0:3], v[190:193], v[226:229], v[0:3]
	s_barrier
	v_add_u32_e32 v174, s3, v159
	v_add_u32_e32 v190, s58, v159
	ds_read_b128 v[162:165], v174
	ds_read_b128 v[166:169], v174 offset:1024
	ds_read_b128 v[170:173], v174 offset:2048
	ds_read_b128 v[174:177], v174 offset:3072
	ds_read_b128 v[178:181], v190
	ds_read_b128 v[182:185], v190 offset:1024
	ds_read_b128 v[186:189], v190 offset:2048
	ds_read_b128 v[190:193], v190 offset:3072
	s_add_u32 s38, s38, 0x80000
	s_addc_u32 s39, s39, 0
	s_mov_b32 m0, s19
	ds_read_b128 v[194:197], v161 offset:32768
	ds_read_b128 v[198:201], v161 offset:33792
	ds_read_b128 v[202:205], v161 offset:34816
	ds_read_b128 v[206:209], v161 offset:35840
	ds_read_b128 v[210:213], v161 offset:36864
	ds_read_b128 v[214:217], v161 offset:37888
	ds_read_b128 v[222:225], v161 offset:38912
	ds_read_b128 v[226:229], v161 offset:39936
	global_load_lds_dwordx4 v128, s[38:39]
	s_mov_b32 m0, s40
	s_nop 0
	global_load_lds_dwordx4 v132, s[38:39]
	s_waitcnt vmcnt(8)
	s_waitcnt lgkmcnt(0)
	s_waitcnt lgkmcnt(0)
	v_mfma_f32_16x16x32_bf16 v[124:127], v[162:165], v[194:197], v[124:127]
	v_mfma_f32_16x16x32_bf16 v[120:123], v[170:173], v[194:197], v[120:123]
	v_mfma_f32_16x16x32_bf16 v[124:127], v[166:169], v[198:201], v[124:127]
	v_mfma_f32_16x16x32_bf16 v[120:123], v[174:177], v[198:201], v[120:123]
	s_barrier
	v_mfma_f32_16x16x32_bf16 v[116:119], v[162:165], v[202:205], v[116:119]
	v_mfma_f32_16x16x32_bf16 v[104:107], v[170:173], v[202:205], v[104:107]
	v_mfma_f32_16x16x32_bf16 v[92:95], v[162:165], v[210:213], v[92:95]
	v_mfma_f32_16x16x32_bf16 v[88:91], v[170:173], v[210:213], v[88:91]
	v_mfma_f32_16x16x32_bf16 v[84:87], v[162:165], v[222:225], v[84:87]
	v_mfma_f32_16x16x32_bf16 v[72:75], v[170:173], v[222:225], v[72:75]
	v_mfma_f32_16x16x32_bf16 v[112:115], v[178:181], v[194:197], v[112:115]
	v_mfma_f32_16x16x32_bf16 v[108:111], v[186:189], v[194:197], v[108:111]
	v_mfma_f32_16x16x32_bf16 v[100:103], v[178:181], v[202:205], v[100:103]
	v_mfma_f32_16x16x32_bf16 v[96:99], v[186:189], v[202:205], v[96:99]
	v_mfma_f32_16x16x32_bf16 v[80:83], v[178:181], v[210:213], v[80:83]
	v_mfma_f32_16x16x32_bf16 v[76:79], v[186:189], v[210:213], v[76:79]
	v_mfma_f32_16x16x32_bf16 v[68:71], v[178:181], v[222:225], v[68:71]
	v_mfma_f32_16x16x32_bf16 v[64:67], v[186:189], v[222:225], v[64:67]
	v_mfma_f32_16x16x32_bf16 v[116:119], v[166:169], v[206:209], v[116:119]
	v_mfma_f32_16x16x32_bf16 v[104:107], v[174:177], v[206:209], v[104:107]
	v_mfma_f32_16x16x32_bf16 v[92:95], v[166:169], v[214:217], v[92:95]
	v_mfma_f32_16x16x32_bf16 v[88:91], v[174:177], v[214:217], v[88:91]
	v_mfma_f32_16x16x32_bf16 v[84:87], v[166:169], v[226:229], v[84:87]
	v_mfma_f32_16x16x32_bf16 v[72:75], v[174:177], v[226:229], v[72:75]
	v_mfma_f32_16x16x32_bf16 v[112:115], v[182:185], v[198:201], v[112:115]
	v_mfma_f32_16x16x32_bf16 v[108:111], v[190:193], v[198:201], v[108:111]
	v_mfma_f32_16x16x32_bf16 v[100:103], v[182:185], v[206:209], v[100:103]
	v_mfma_f32_16x16x32_bf16 v[96:99], v[190:193], v[206:209], v[96:99]
	v_mfma_f32_16x16x32_bf16 v[80:83], v[182:185], v[214:217], v[80:83]
	v_mfma_f32_16x16x32_bf16 v[76:79], v[190:193], v[214:217], v[76:79]
	v_mfma_f32_16x16x32_bf16 v[68:71], v[182:185], v[226:229], v[68:71]
	v_mfma_f32_16x16x32_bf16 v[64:67], v[190:193], v[226:229], v[64:67]
	s_barrier
	s_add_i32 s38, s3, s6
	v_lshl_add_u64 v[156:157], v[156:157], 0, s[12:13]
	s_mov_b32 m0, s38
	ds_read_b128 v[194:197], v161 offset:49152
	ds_read_b128 v[198:201], v161 offset:50176
	ds_read_b128 v[202:205], v161 offset:51200
	ds_read_b128 v[206:209], v161 offset:52224
	ds_read_b128 v[210:213], v161 offset:53248
	ds_read_b128 v[214:217], v161 offset:54272
	ds_read_b128 v[222:225], v161 offset:55296
	ds_read_b128 v[226:229], v161 offset:56320
	global_load_lds_dwordx4 v[156:157], off
	s_add_i32 m0, s38, 0x2000
	s_add_u32 s36, s36, 0x80080
	v_lshl_add_u64 v[156:157], v[218:219], 0, s[12:13]
	s_addc_u32 s37, s37, 0
	s_add_i32 s38, s58, s6
	global_load_lds_dwordx4 v[156:157], off
	s_mov_b32 m0, s38
	s_nop 0
	global_load_lds_dwordx4 v130, s[36:37]
	s_add_i32 m0, s38, 0x2000
	s_nop 0
	global_load_lds_dwordx4 v134, s[36:37]
	v_lshl_add_u64 v[156:157], v[230:231], 0, s[12:13]
	s_mov_b32 m0, s42
	s_nop 0
	global_load_lds_dwordx4 v[156:157], off
	v_lshl_add_u64 v[156:157], v[232:233], 0, s[12:13]
	s_mov_b32 m0, s43
	s_nop 0
	global_load_lds_dwordx4 v[156:157], off
	s_waitcnt vmcnt(8)
	s_waitcnt lgkmcnt(0)
	s_waitcnt lgkmcnt(0)
	v_mfma_f32_16x16x32_bf16 v[60:63], v[162:165], v[194:197], v[60:63]
	v_mfma_f32_16x16x32_bf16 v[56:59], v[170:173], v[194:197], v[56:59]
	v_mfma_f32_16x16x32_bf16 v[60:63], v[166:169], v[198:201], v[60:63]
	v_mfma_f32_16x16x32_bf16 v[56:59], v[174:177], v[198:201], v[56:59]
	s_barrier
	v_mfma_f32_16x16x32_bf16 v[52:55], v[162:165], v[202:205], v[52:55]
	v_mfma_f32_16x16x32_bf16 v[44:47], v[170:173], v[202:205], v[44:47]
	v_mfma_f32_16x16x32_bf16 v[32:35], v[162:165], v[210:213], v[32:35]
	v_mfma_f32_16x16x32_bf16 v[24:27], v[170:173], v[210:213], v[24:27]
	v_mfma_f32_16x16x32_bf16 v[20:23], v[162:165], v[222:225], v[20:23]
	v_mfma_f32_16x16x32_bf16 v[12:15], v[170:173], v[222:225], v[12:15]
	v_mfma_f32_16x16x32_bf16 v[48:51], v[178:181], v[194:197], v[48:51]
	v_mfma_f32_16x16x32_bf16 v[40:43], v[186:189], v[194:197], v[40:43]
	v_mfma_f32_16x16x32_bf16 v[36:39], v[178:181], v[202:205], v[36:39]
	v_mfma_f32_16x16x32_bf16 v[28:31], v[186:189], v[202:205], v[28:31]
	v_mfma_f32_16x16x32_bf16 v[16:19], v[178:181], v[210:213], v[16:19]
	v_mfma_f32_16x16x32_bf16 v[8:11], v[186:189], v[210:213], v[8:11]
	v_mfma_f32_16x16x32_bf16 v[4:7], v[178:181], v[222:225], v[4:7]
	v_mfma_f32_16x16x32_bf16 v[0:3], v[186:189], v[222:225], v[0:3]
	v_mfma_f32_16x16x32_bf16 v[52:55], v[166:169], v[206:209], v[52:55]
	v_mfma_f32_16x16x32_bf16 v[44:47], v[174:177], v[206:209], v[44:47]
	v_mfma_f32_16x16x32_bf16 v[32:35], v[166:169], v[214:217], v[32:35]
	v_mfma_f32_16x16x32_bf16 v[24:27], v[174:177], v[214:217], v[24:27]
	v_mfma_f32_16x16x32_bf16 v[20:23], v[166:169], v[226:229], v[20:23]
	v_mfma_f32_16x16x32_bf16 v[12:15], v[174:177], v[226:229], v[12:15]
	v_mfma_f32_16x16x32_bf16 v[48:51], v[182:185], v[198:201], v[48:51]
	v_mfma_f32_16x16x32_bf16 v[40:43], v[190:193], v[198:201], v[40:43]
	v_mfma_f32_16x16x32_bf16 v[36:39], v[182:185], v[206:209], v[36:39]
	v_mfma_f32_16x16x32_bf16 v[28:31], v[190:193], v[206:209], v[28:31]
	v_mfma_f32_16x16x32_bf16 v[16:19], v[182:185], v[214:217], v[16:19]
	v_mfma_f32_16x16x32_bf16 v[8:11], v[190:193], v[214:217], v[8:11]
	v_mfma_f32_16x16x32_bf16 v[4:7], v[182:185], v[226:229], v[4:7]
	v_mfma_f32_16x16x32_bf16 v[0:3], v[190:193], v[226:229], v[0:3]
	s_barrier
	s_add_i32 s57, s57, 2
	s_add_u32 s34, s34, 0x100
	s_addc_u32 s35, s35, 0
	s_add_u32 s55, s55, 0x100
	s_addc_u32 s56, s56, 0
	s_cmp_gt_u32 s57, 29
	s_cbranch_scc1 .LBB0_1389

.LBB0_1404:
	v_add_u32_e32 v153, s95, v161
	ds_read_b128 v[156:159], v153
	ds_read_b128 v[164:167], v153 offset:1024
	ds_read_b128 v[168:171], v153 offset:2048
	ds_read_b128 v[172:175], v153 offset:3072
	v_add_u32_e32 v153, s33, v161
	ds_read_b128 v[176:179], v153
	ds_read_b128 v[180:183], v153 offset:1024
	ds_read_b128 v[184:187], v153 offset:2048
	ds_read_b128 v[188:191], v153 offset:3072
	s_add_u32 s36, s30, 0xfff80080
	s_addc_u32 s37, s31, -1
	s_and_b64 s[34:35], s[34:35], exec
	s_cselect_b32 s37, s25, s37
	s_cselect_b32 s36, s49, s36
	s_cselect_b32 s35, s23, s53
	s_cselect_b32 s34, s50, s51
	s_add_i32 m0, s21, 0xc000
	ds_read_b128 v[192:195], v163
	ds_read_b128 v[196:199], v163 offset:1024
	ds_read_b128 v[200:203], v163 offset:2048
	ds_read_b128 v[204:207], v163 offset:3072
	ds_read_b128 v[208:211], v163 offset:4096
	ds_read_b128 v[212:215], v163 offset:5120
	ds_read_b128 v[216:219], v163 offset:6144
	ds_read_b128 v[222:225], v163 offset:7168
	global_load_lds_dwordx4 v136, s[30:31]
	s_add_i32 m0, s21, 0xe000
	s_nop 0
	global_load_lds_dwordx4 v138, s[30:31]
	s_waitcnt vmcnt(8)
	s_waitcnt lgkmcnt(0)
	s_waitcnt lgkmcnt(0)
	v_mfma_f32_16x16x32_bf16 v[124:127], v[156:159], v[192:195], v[124:127]
	v_mfma_f32_16x16x32_bf16 v[120:123], v[168:171], v[192:195], v[120:123]
	v_mfma_f32_16x16x32_bf16 v[124:127], v[164:167], v[196:199], v[124:127]
	v_mfma_f32_16x16x32_bf16 v[120:123], v[172:175], v[196:199], v[120:123]
	s_barrier
	v_mfma_f32_16x16x32_bf16 v[108:111], v[156:159], v[200:203], v[108:111]
	v_mfma_f32_16x16x32_bf16 v[104:107], v[168:171], v[200:203], v[104:107]
	v_mfma_f32_16x16x32_bf16 v[92:95], v[156:159], v[208:211], v[92:95]
	v_mfma_f32_16x16x32_bf16 v[88:91], v[168:171], v[208:211], v[88:91]
	v_mfma_f32_16x16x32_bf16 v[76:79], v[156:159], v[216:219], v[76:79]
	v_mfma_f32_16x16x32_bf16 v[72:75], v[168:171], v[216:219], v[72:75]
	v_mfma_f32_16x16x32_bf16 v[116:119], v[176:179], v[192:195], v[116:119]
	v_mfma_f32_16x16x32_bf16 v[112:115], v[184:187], v[192:195], v[112:115]
	v_mfma_f32_16x16x32_bf16 v[100:103], v[176:179], v[200:203], v[100:103]
	v_mfma_f32_16x16x32_bf16 v[96:99], v[184:187], v[200:203], v[96:99]
	v_mfma_f32_16x16x32_bf16 v[84:87], v[176:179], v[208:211], v[84:87]
	v_mfma_f32_16x16x32_bf16 v[80:83], v[184:187], v[208:211], v[80:83]
	v_mfma_f32_16x16x32_bf16 v[68:71], v[176:179], v[216:219], v[68:71]
	v_mfma_f32_16x16x32_bf16 v[64:67], v[184:187], v[216:219], v[64:67]
	v_mfma_f32_16x16x32_bf16 v[108:111], v[164:167], v[204:207], v[108:111]
	v_mfma_f32_16x16x32_bf16 v[104:107], v[172:175], v[204:207], v[104:107]
	v_mfma_f32_16x16x32_bf16 v[92:95], v[164:167], v[212:215], v[92:95]
	v_mfma_f32_16x16x32_bf16 v[88:91], v[172:175], v[212:215], v[88:91]
	v_mfma_f32_16x16x32_bf16 v[76:79], v[164:167], v[222:225], v[76:79]
	v_mfma_f32_16x16x32_bf16 v[72:75], v[172:175], v[222:225], v[72:75]
	v_mfma_f32_16x16x32_bf16 v[116:119], v[180:183], v[196:199], v[116:119]
	v_mfma_f32_16x16x32_bf16 v[112:115], v[188:191], v[196:199], v[112:115]
	v_mfma_f32_16x16x32_bf16 v[100:103], v[180:183], v[204:207], v[100:103]
	v_mfma_f32_16x16x32_bf16 v[96:99], v[188:191], v[204:207], v[96:99]
	v_mfma_f32_16x16x32_bf16 v[84:87], v[180:183], v[212:215], v[84:87]
	v_mfma_f32_16x16x32_bf16 v[80:83], v[188:191], v[212:215], v[80:83]
	v_mfma_f32_16x16x32_bf16 v[68:71], v[180:183], v[222:225], v[68:71]
	v_mfma_f32_16x16x32_bf16 v[64:67], v[188:191], v[222:225], v[64:67]
	s_barrier
	s_add_i32 s55, s95, s7
	v_lshl_add_u64 v[226:227], s[34:35], 0, v[132:133]
	s_mov_b32 m0, s55
	ds_read_b128 v[192:195], v163 offset:16384
	ds_read_b128 v[196:199], v163 offset:17408
	ds_read_b128 v[200:203], v163 offset:18432
	ds_read_b128 v[204:207], v163 offset:19456
	ds_read_b128 v[208:211], v163 offset:20480
	ds_read_b128 v[212:215], v163 offset:21504
	ds_read_b128 v[216:219], v163 offset:22528
	ds_read_b128 v[222:225], v163 offset:23552
	global_load_lds_dwordx4 v[226:227], off
	s_add_i32 m0, s55, 0x2000
	s_add_u32 s56, s34, 0x80000
	v_lshl_add_u64 v[228:229], s[34:35], 0, v[128:129]
	s_addc_u32 s57, s35, 0
	s_add_i32 s55, s33, s7
	global_load_lds_dwordx4 v[228:229], off
	s_mov_b32 m0, s55
	v_lshl_add_u64 v[232:233], s[36:37], 0, v[130:131]
	global_load_lds_dwordx4 v132, s[56:57]
	s_add_i32 m0, s55, 0x2000
	s_nop 0
	global_load_lds_dwordx4 v128, s[56:57]
	v_lshl_add_u64 v[230:231], s[36:37], 0, v[134:135]
	s_mov_b32 m0, s21
	s_nop 0
	global_load_lds_dwordx4 v[230:231], off
	s_mov_b32 m0, s38
	s_nop 0
	global_load_lds_dwordx4 v[232:233], off
	s_waitcnt vmcnt(8)
	s_waitcnt lgkmcnt(0)
	s_waitcnt lgkmcnt(0)
	v_mfma_f32_16x16x32_bf16 v[60:63], v[156:159], v[192:195], v[60:63]
	v_mfma_f32_16x16x32_bf16 v[56:59], v[168:171], v[192:195], v[56:59]
	v_mfma_f32_16x16x32_bf16 v[60:63], v[164:167], v[196:199], v[60:63]
	v_mfma_f32_16x16x32_bf16 v[56:59], v[172:175], v[196:199], v[56:59]
	s_barrier
	v_mfma_f32_16x16x32_bf16 v[44:47], v[156:159], v[200:203], v[44:47]
	v_mfma_f32_16x16x32_bf16 v[40:43], v[168:171], v[200:203], v[40:43]
	v_mfma_f32_16x16x32_bf16 v[28:31], v[156:159], v[208:211], v[28:31]
	v_mfma_f32_16x16x32_bf16 v[24:27], v[168:171], v[208:211], v[24:27]
	v_mfma_f32_16x16x32_bf16 v[12:15], v[156:159], v[216:219], v[12:15]
	v_mfma_f32_16x16x32_bf16 v[8:11], v[168:171], v[216:219], v[8:11]
	v_mfma_f32_16x16x32_bf16 v[52:55], v[176:179], v[192:195], v[52:55]
	v_mfma_f32_16x16x32_bf16 v[48:51], v[184:187], v[192:195], v[48:51]
	v_mfma_f32_16x16x32_bf16 v[36:39], v[176:179], v[200:203], v[36:39]
	v_mfma_f32_16x16x32_bf16 v[32:35], v[184:187], v[200:203], v[32:35]
	v_mfma_f32_16x16x32_bf16 v[20:23], v[176:179], v[208:211], v[20:23]
	v_mfma_f32_16x16x32_bf16 v[16:19], v[184:187], v[208:211], v[16:19]
	v_mfma_f32_16x16x32_bf16 v[4:7], v[176:179], v[216:219], v[4:7]
	v_mfma_f32_16x16x32_bf16 v[0:3], v[184:187], v[216:219], v[0:3]
	v_mfma_f32_16x16x32_bf16 v[44:47], v[164:167], v[204:207], v[44:47]
	v_mfma_f32_16x16x32_bf16 v[40:43], v[172:175], v[204:207], v[40:43]
	v_mfma_f32_16x16x32_bf16 v[28:31], v[164:167], v[212:215], v[28:31]
	v_mfma_f32_16x16x32_bf16 v[24:27], v[172:175], v[212:215], v[24:27]
	v_mfma_f32_16x16x32_bf16 v[12:15], v[164:167], v[222:225], v[12:15]
	v_mfma_f32_16x16x32_bf16 v[8:11], v[172:175], v[222:225], v[8:11]
	v_mfma_f32_16x16x32_bf16 v[52:55], v[180:183], v[196:199], v[52:55]
	v_mfma_f32_16x16x32_bf16 v[48:51], v[188:191], v[196:199], v[48:51]
	v_mfma_f32_16x16x32_bf16 v[36:39], v[180:183], v[204:207], v[36:39]
	v_mfma_f32_16x16x32_bf16 v[32:35], v[188:191], v[204:207], v[32:35]
	v_mfma_f32_16x16x32_bf16 v[20:23], v[180:183], v[212:215], v[20:23]
	v_mfma_f32_16x16x32_bf16 v[16:19], v[188:191], v[212:215], v[16:19]
	v_mfma_f32_16x16x32_bf16 v[4:7], v[180:183], v[222:225], v[4:7]
	v_mfma_f32_16x16x32_bf16 v[0:3], v[188:191], v[222:225], v[0:3]
	s_barrier
	v_add_u32_e32 v153, s3, v161
	ds_read_b128 v[156:159], v153
	ds_read_b128 v[164:167], v153 offset:1024
	ds_read_b128 v[168:171], v153 offset:2048
	ds_read_b128 v[172:175], v153 offset:3072
	v_add_u32_e32 v153, s58, v161
	ds_read_b128 v[176:179], v153
	ds_read_b128 v[180:183], v153 offset:1024
	ds_read_b128 v[184:187], v153 offset:2048
	ds_read_b128 v[188:191], v153 offset:3072
	s_add_u32 s36, s36, 0x80000
	s_addc_u32 s37, s37, 0
	s_mov_b32 m0, s39
	ds_read_b128 v[192:195], v163 offset:32768
	ds_read_b128 v[196:199], v163 offset:33792
	ds_read_b128 v[200:203], v163 offset:34816
	ds_read_b128 v[204:207], v163 offset:35840
	ds_read_b128 v[208:211], v163 offset:36864
	ds_read_b128 v[212:215], v163 offset:37888
	ds_read_b128 v[216:219], v163 offset:38912
	ds_read_b128 v[222:225], v163 offset:39936
	global_load_lds_dwordx4 v134, s[36:37]
	s_mov_b32 m0, s40
	s_nop 0
	global_load_lds_dwordx4 v130, s[36:37]
	s_waitcnt vmcnt(8)
	s_waitcnt lgkmcnt(0)
	s_waitcnt lgkmcnt(0)
	v_mfma_f32_16x16x32_bf16 v[124:127], v[156:159], v[192:195], v[124:127]
	v_mfma_f32_16x16x32_bf16 v[120:123], v[168:171], v[192:195], v[120:123]
	v_mfma_f32_16x16x32_bf16 v[124:127], v[164:167], v[196:199], v[124:127]
	v_mfma_f32_16x16x32_bf16 v[120:123], v[172:175], v[196:199], v[120:123]
	s_barrier
	v_mfma_f32_16x16x32_bf16 v[108:111], v[156:159], v[200:203], v[108:111]
	v_mfma_f32_16x16x32_bf16 v[104:107], v[168:171], v[200:203], v[104:107]
	v_mfma_f32_16x16x32_bf16 v[92:95], v[156:159], v[208:211], v[92:95]
	v_mfma_f32_16x16x32_bf16 v[88:91], v[168:171], v[208:211], v[88:91]
	v_mfma_f32_16x16x32_bf16 v[76:79], v[156:159], v[216:219], v[76:79]
	v_mfma_f32_16x16x32_bf16 v[72:75], v[168:171], v[216:219], v[72:75]
	v_mfma_f32_16x16x32_bf16 v[116:119], v[176:179], v[192:195], v[116:119]
	v_mfma_f32_16x16x32_bf16 v[112:115], v[184:187], v[192:195], v[112:115]
	v_mfma_f32_16x16x32_bf16 v[100:103], v[176:179], v[200:203], v[100:103]
	v_mfma_f32_16x16x32_bf16 v[96:99], v[184:187], v[200:203], v[96:99]
	v_mfma_f32_16x16x32_bf16 v[84:87], v[176:179], v[208:211], v[84:87]
	v_mfma_f32_16x16x32_bf16 v[80:83], v[184:187], v[208:211], v[80:83]
	v_mfma_f32_16x16x32_bf16 v[68:71], v[176:179], v[216:219], v[68:71]
	v_mfma_f32_16x16x32_bf16 v[64:67], v[184:187], v[216:219], v[64:67]
	v_mfma_f32_16x16x32_bf16 v[108:111], v[164:167], v[204:207], v[108:111]
	v_mfma_f32_16x16x32_bf16 v[104:107], v[172:175], v[204:207], v[104:107]
	v_mfma_f32_16x16x32_bf16 v[92:95], v[164:167], v[212:215], v[92:95]
	v_mfma_f32_16x16x32_bf16 v[88:91], v[172:175], v[212:215], v[88:91]
	v_mfma_f32_16x16x32_bf16 v[76:79], v[164:167], v[222:225], v[76:79]
	v_mfma_f32_16x16x32_bf16 v[72:75], v[172:175], v[222:225], v[72:75]
	v_mfma_f32_16x16x32_bf16 v[116:119], v[180:183], v[196:199], v[116:119]
	v_mfma_f32_16x16x32_bf16 v[112:115], v[188:191], v[196:199], v[112:115]
	v_mfma_f32_16x16x32_bf16 v[100:103], v[180:183], v[204:207], v[100:103]
	v_mfma_f32_16x16x32_bf16 v[96:99], v[188:191], v[204:207], v[96:99]
	v_mfma_f32_16x16x32_bf16 v[84:87], v[180:183], v[212:215], v[84:87]
	v_mfma_f32_16x16x32_bf16 v[80:83], v[188:191], v[212:215], v[80:83]
	v_mfma_f32_16x16x32_bf16 v[68:71], v[180:183], v[222:225], v[68:71]
	v_mfma_f32_16x16x32_bf16 v[64:67], v[188:191], v[222:225], v[64:67]
	s_barrier
	s_add_i32 s36, s3, s7
	v_lshl_add_u64 v[226:227], v[226:227], 0, s[12:13]
	s_mov_b32 m0, s36
	ds_read_b128 v[192:195], v163 offset:49152
	ds_read_b128 v[196:199], v163 offset:50176
	ds_read_b128 v[200:203], v163 offset:51200
	ds_read_b128 v[204:207], v163 offset:52224
	ds_read_b128 v[208:211], v163 offset:53248
	ds_read_b128 v[212:215], v163 offset:54272
	ds_read_b128 v[216:219], v163 offset:55296
	ds_read_b128 v[222:225], v163 offset:56320
	global_load_lds_dwordx4 v[226:227], off
	s_add_i32 m0, s36, 0x2000
	s_add_u32 s34, s34, 0x80080
	v_lshl_add_u64 v[226:227], v[228:229], 0, s[12:13]
	s_addc_u32 s35, s35, 0
	s_add_i32 s36, s58, s7
	global_load_lds_dwordx4 v[226:227], off
	s_mov_b32 m0, s36
	s_nop 0
	global_load_lds_dwordx4 v132, s[34:35]
	s_add_i32 m0, s36, 0x2000
	s_nop 0
	global_load_lds_dwordx4 v128, s[34:35]
	v_lshl_add_u64 v[226:227], v[230:231], 0, s[12:13]
	s_mov_b32 m0, s42
	s_nop 0
	global_load_lds_dwordx4 v[226:227], off
	v_lshl_add_u64 v[226:227], v[232:233], 0, s[12:13]
	s_mov_b32 m0, s43
	s_nop 0
	global_load_lds_dwordx4 v[226:227], off
	s_waitcnt vmcnt(8)
	s_waitcnt lgkmcnt(0)
	s_waitcnt lgkmcnt(0)
	v_mfma_f32_16x16x32_bf16 v[60:63], v[156:159], v[192:195], v[60:63]
	v_mfma_f32_16x16x32_bf16 v[56:59], v[168:171], v[192:195], v[56:59]
	v_mfma_f32_16x16x32_bf16 v[60:63], v[164:167], v[196:199], v[60:63]
	v_mfma_f32_16x16x32_bf16 v[56:59], v[172:175], v[196:199], v[56:59]
	s_barrier
	v_mfma_f32_16x16x32_bf16 v[44:47], v[156:159], v[200:203], v[44:47]
	v_mfma_f32_16x16x32_bf16 v[40:43], v[168:171], v[200:203], v[40:43]
	v_mfma_f32_16x16x32_bf16 v[28:31], v[156:159], v[208:211], v[28:31]
	v_mfma_f32_16x16x32_bf16 v[24:27], v[168:171], v[208:211], v[24:27]
	v_mfma_f32_16x16x32_bf16 v[12:15], v[156:159], v[216:219], v[12:15]
	v_mfma_f32_16x16x32_bf16 v[8:11], v[168:171], v[216:219], v[8:11]
	v_mfma_f32_16x16x32_bf16 v[52:55], v[176:179], v[192:195], v[52:55]
	v_mfma_f32_16x16x32_bf16 v[48:51], v[184:187], v[192:195], v[48:51]
	v_mfma_f32_16x16x32_bf16 v[36:39], v[176:179], v[200:203], v[36:39]
	v_mfma_f32_16x16x32_bf16 v[32:35], v[184:187], v[200:203], v[32:35]
	v_mfma_f32_16x16x32_bf16 v[20:23], v[176:179], v[208:211], v[20:23]
	v_mfma_f32_16x16x32_bf16 v[16:19], v[184:187], v[208:211], v[16:19]
	v_mfma_f32_16x16x32_bf16 v[4:7], v[176:179], v[216:219], v[4:7]
	v_mfma_f32_16x16x32_bf16 v[0:3], v[184:187], v[216:219], v[0:3]
	v_mfma_f32_16x16x32_bf16 v[44:47], v[164:167], v[204:207], v[44:47]
	v_mfma_f32_16x16x32_bf16 v[40:43], v[172:175], v[204:207], v[40:43]
	v_mfma_f32_16x16x32_bf16 v[28:31], v[164:167], v[212:215], v[28:31]
	v_mfma_f32_16x16x32_bf16 v[24:27], v[172:175], v[212:215], v[24:27]
	v_mfma_f32_16x16x32_bf16 v[12:15], v[164:167], v[222:225], v[12:15]
	v_mfma_f32_16x16x32_bf16 v[8:11], v[172:175], v[222:225], v[8:11]
	v_mfma_f32_16x16x32_bf16 v[52:55], v[180:183], v[196:199], v[52:55]
	v_mfma_f32_16x16x32_bf16 v[48:51], v[188:191], v[196:199], v[48:51]
	v_mfma_f32_16x16x32_bf16 v[36:39], v[180:183], v[204:207], v[36:39]
	v_mfma_f32_16x16x32_bf16 v[32:35], v[188:191], v[204:207], v[32:35]
	v_mfma_f32_16x16x32_bf16 v[20:23], v[180:183], v[212:215], v[20:23]
	v_mfma_f32_16x16x32_bf16 v[16:19], v[188:191], v[212:215], v[16:19]
	v_mfma_f32_16x16x32_bf16 v[4:7], v[180:183], v[222:225], v[4:7]
	v_mfma_f32_16x16x32_bf16 v[0:3], v[188:191], v[222:225], v[0:3]
	s_barrier
	s_add_i32 s54, s54, 2
	s_add_u32 s30, s30, 0x100
	s_addc_u32 s31, s31, 0
	s_add_u32 s51, s51, 0x100
	s_addc_u32 s53, s53, 0
	s_cmp_gt_u32 s54, 29
	s_cbranch_scc1 .LBB0_1407

.LBB0_1555:
	ds_read_b128 v[144:147], v151
	ds_read_b128 v[156:159], v151 offset:1024
	ds_read_b128 v[160:163], v151 offset:2048
	ds_read_b128 v[164:167], v151 offset:3072
	ds_read_b128 v[168:171], v152
	ds_read_b128 v[172:175], v152 offset:1024
	ds_read_b128 v[176:179], v152 offset:2048
	ds_read_b128 v[180:183], v152 offset:3072
	s_add_u32 s22, s20, 0x100
	s_addc_u32 s23, s21, 0
	s_cmpk_eq_i32 s48, 0x54
	s_cselect_b32 s27, s1, s23
	s_cselect_b32 s26, s0, s22
	s_cselect_b32 s25, s19, s47
	s_cselect_b32 s24, s18, s46
	v_lshl_add_u64 v[216:217], s[20:21], 0, v[136:137]
	s_add_i32 m0, s28, 0xc000
	ds_read_b128 v[184:187], v153
	ds_read_b128 v[188:191], v153 offset:1024
	ds_read_b128 v[192:195], v153 offset:2048
	ds_read_b128 v[196:199], v153 offset:3072
	ds_read_b128 v[200:203], v153 offset:4096
	ds_read_b128 v[204:207], v153 offset:5120
	ds_read_b128 v[208:211], v153 offset:6144
	ds_read_b128 v[212:215], v153 offset:7168
	global_load_lds_dwordx4 v[216:217], off
	v_lshl_add_u64 v[216:217], s[20:21], 0, v[138:139]
	s_add_i32 m0, s28, 0xe000
	s_nop 0
	global_load_lds_dwordx4 v[216:217], off
	s_waitcnt vmcnt(8)
	s_waitcnt lgkmcnt(0)
	s_waitcnt lgkmcnt(0)
	v_mfma_f32_16x16x32_bf16 v[124:127], v[144:147], v[184:187], v[124:127]
	v_mfma_f32_16x16x32_bf16 v[120:123], v[160:163], v[184:187], v[120:123]
	v_mfma_f32_16x16x32_bf16 v[124:127], v[156:159], v[188:191], v[124:127]
	v_mfma_f32_16x16x32_bf16 v[120:123], v[164:167], v[188:191], v[120:123]
	s_barrier
	v_mfma_f32_16x16x32_bf16 v[108:111], v[144:147], v[192:195], v[108:111]
	v_mfma_f32_16x16x32_bf16 v[104:107], v[160:163], v[192:195], v[104:107]
	v_mfma_f32_16x16x32_bf16 v[92:95], v[144:147], v[200:203], v[92:95]
	v_mfma_f32_16x16x32_bf16 v[88:91], v[160:163], v[200:203], v[88:91]
	v_mfma_f32_16x16x32_bf16 v[76:79], v[144:147], v[208:211], v[76:79]
	v_mfma_f32_16x16x32_bf16 v[72:75], v[160:163], v[208:211], v[72:75]
	v_mfma_f32_16x16x32_bf16 v[116:119], v[168:171], v[184:187], v[116:119]
	v_mfma_f32_16x16x32_bf16 v[112:115], v[176:179], v[184:187], v[112:115]
	v_mfma_f32_16x16x32_bf16 v[100:103], v[168:171], v[192:195], v[100:103]
	v_mfma_f32_16x16x32_bf16 v[96:99], v[176:179], v[192:195], v[96:99]
	v_mfma_f32_16x16x32_bf16 v[84:87], v[168:171], v[200:203], v[84:87]
	v_mfma_f32_16x16x32_bf16 v[80:83], v[176:179], v[200:203], v[80:83]
	v_mfma_f32_16x16x32_bf16 v[68:71], v[168:171], v[208:211], v[68:71]
	v_mfma_f32_16x16x32_bf16 v[64:67], v[176:179], v[208:211], v[64:67]
	v_mfma_f32_16x16x32_bf16 v[108:111], v[156:159], v[196:199], v[108:111]
	v_mfma_f32_16x16x32_bf16 v[104:107], v[164:167], v[196:199], v[104:107]
	v_mfma_f32_16x16x32_bf16 v[92:95], v[156:159], v[204:207], v[92:95]
	v_mfma_f32_16x16x32_bf16 v[88:91], v[164:167], v[204:207], v[88:91]
	v_mfma_f32_16x16x32_bf16 v[76:79], v[156:159], v[212:215], v[76:79]
	v_mfma_f32_16x16x32_bf16 v[72:75], v[164:167], v[212:215], v[72:75]
	v_mfma_f32_16x16x32_bf16 v[116:119], v[172:175], v[188:191], v[116:119]
	v_mfma_f32_16x16x32_bf16 v[112:115], v[180:183], v[188:191], v[112:115]
	v_mfma_f32_16x16x32_bf16 v[100:103], v[172:175], v[196:199], v[100:103]
	v_mfma_f32_16x16x32_bf16 v[96:99], v[180:183], v[196:199], v[96:99]
	v_mfma_f32_16x16x32_bf16 v[84:87], v[172:175], v[204:207], v[84:87]
	v_mfma_f32_16x16x32_bf16 v[80:83], v[180:183], v[204:207], v[80:83]
	v_mfma_f32_16x16x32_bf16 v[68:71], v[172:175], v[212:215], v[68:71]
	v_mfma_f32_16x16x32_bf16 v[64:67], v[180:183], v[212:215], v[64:67]
	s_barrier
	s_add_i32 s20, s95, s7
	v_lshl_add_u64 v[216:217], s[24:25], 0, v[130:131]
	s_mov_b32 m0, s20
	ds_read_b128 v[184:187], v153 offset:16384
	ds_read_b128 v[188:191], v153 offset:17408
	ds_read_b128 v[192:195], v153 offset:18432
	ds_read_b128 v[196:199], v153 offset:19456
	ds_read_b128 v[200:203], v153 offset:20480
	ds_read_b128 v[204:207], v153 offset:21504
	ds_read_b128 v[208:211], v153 offset:22528
	ds_read_b128 v[212:215], v153 offset:23552
	global_load_lds_dwordx4 v[216:217], off
	s_add_i32 m0, s20, 0x2000
	s_add_u32 s20, s24, 0x160000
	v_lshl_add_u64 v[218:219], s[24:25], 0, v[134:135]
	s_addc_u32 s21, s25, 0
	s_add_i32 s49, s33, s7
	global_load_lds_dwordx4 v[218:219], off
	s_mov_b32 m0, s49
	v_lshl_add_u64 v[224:225], s[26:27], 0, v[132:133]
	global_load_lds_dwordx4 v130, s[20:21]
	s_add_i32 m0, s49, 0x2000
	s_nop 0
	global_load_lds_dwordx4 v134, s[20:21]
	v_lshl_add_u64 v[222:223], s[26:27], 0, v[128:129]
	s_mov_b32 m0, s28
	s_nop 0
	global_load_lds_dwordx4 v[222:223], off
	s_mov_b32 m0, s29
	s_nop 0
	global_load_lds_dwordx4 v[224:225], off
	s_waitcnt vmcnt(8)
	s_waitcnt lgkmcnt(0)
	s_waitcnt lgkmcnt(0)
	v_mfma_f32_16x16x32_bf16 v[60:63], v[144:147], v[184:187], v[60:63]
	v_mfma_f32_16x16x32_bf16 v[56:59], v[160:163], v[184:187], v[56:59]
	v_mfma_f32_16x16x32_bf16 v[60:63], v[156:159], v[188:191], v[60:63]
	v_mfma_f32_16x16x32_bf16 v[56:59], v[164:167], v[188:191], v[56:59]
	s_barrier
	v_mfma_f32_16x16x32_bf16 v[44:47], v[144:147], v[192:195], v[44:47]
	v_mfma_f32_16x16x32_bf16 v[40:43], v[160:163], v[192:195], v[40:43]
	v_mfma_f32_16x16x32_bf16 v[28:31], v[144:147], v[200:203], v[28:31]
	v_mfma_f32_16x16x32_bf16 v[24:27], v[160:163], v[200:203], v[24:27]
	v_mfma_f32_16x16x32_bf16 v[12:15], v[144:147], v[208:211], v[12:15]
	v_mfma_f32_16x16x32_bf16 v[8:11], v[160:163], v[208:211], v[8:11]
	v_mfma_f32_16x16x32_bf16 v[52:55], v[168:171], v[184:187], v[52:55]
	v_mfma_f32_16x16x32_bf16 v[48:51], v[176:179], v[184:187], v[48:51]
	v_mfma_f32_16x16x32_bf16 v[36:39], v[168:171], v[192:195], v[36:39]
	v_mfma_f32_16x16x32_bf16 v[32:35], v[176:179], v[192:195], v[32:35]
	v_mfma_f32_16x16x32_bf16 v[20:23], v[168:171], v[200:203], v[20:23]
	v_mfma_f32_16x16x32_bf16 v[16:19], v[176:179], v[200:203], v[16:19]
	v_mfma_f32_16x16x32_bf16 v[4:7], v[168:171], v[208:211], v[4:7]
	v_mfma_f32_16x16x32_bf16 v[0:3], v[176:179], v[208:211], v[0:3]
	v_mfma_f32_16x16x32_bf16 v[44:47], v[156:159], v[196:199], v[44:47]
	v_mfma_f32_16x16x32_bf16 v[40:43], v[164:167], v[196:199], v[40:43]
	v_mfma_f32_16x16x32_bf16 v[28:31], v[156:159], v[204:207], v[28:31]
	v_mfma_f32_16x16x32_bf16 v[24:27], v[164:167], v[204:207], v[24:27]
	v_mfma_f32_16x16x32_bf16 v[12:15], v[156:159], v[212:215], v[12:15]
	v_mfma_f32_16x16x32_bf16 v[8:11], v[164:167], v[212:215], v[8:11]
	v_mfma_f32_16x16x32_bf16 v[52:55], v[172:175], v[188:191], v[52:55]
	v_mfma_f32_16x16x32_bf16 v[48:51], v[180:183], v[188:191], v[48:51]
	v_mfma_f32_16x16x32_bf16 v[36:39], v[172:175], v[196:199], v[36:39]
	v_mfma_f32_16x16x32_bf16 v[32:35], v[180:183], v[196:199], v[32:35]
	v_mfma_f32_16x16x32_bf16 v[20:23], v[172:175], v[204:207], v[20:23]
	v_mfma_f32_16x16x32_bf16 v[16:19], v[180:183], v[204:207], v[16:19]
	v_mfma_f32_16x16x32_bf16 v[4:7], v[172:175], v[212:215], v[4:7]
	v_mfma_f32_16x16x32_bf16 v[0:3], v[180:183], v[212:215], v[0:3]
	s_barrier
	v_add_u32_e32 v155, s3, v149
	ds_read_b128 v[144:147], v155
	ds_read_b128 v[156:159], v155 offset:1024
	ds_read_b128 v[160:163], v155 offset:2048
	ds_read_b128 v[164:167], v155 offset:3072
	v_add_u32_e32 v155, s58, v149
	ds_read_b128 v[168:171], v155
	ds_read_b128 v[172:175], v155 offset:1024
	ds_read_b128 v[176:179], v155 offset:2048
	ds_read_b128 v[180:183], v155 offset:3072
	s_add_u32 s20, s26, 0x160000
	s_addc_u32 s21, s27, 0
	s_mov_b32 m0, s30
	ds_read_b128 v[184:187], v153 offset:32768
	ds_read_b128 v[188:191], v153 offset:33792
	ds_read_b128 v[192:195], v153 offset:34816
	ds_read_b128 v[196:199], v153 offset:35840
	ds_read_b128 v[200:203], v153 offset:36864
	ds_read_b128 v[204:207], v153 offset:37888
	ds_read_b128 v[208:211], v153 offset:38912
	ds_read_b128 v[212:215], v153 offset:39936
	global_load_lds_dwordx4 v128, s[20:21]
	s_mov_b32 m0, s31
	s_nop 0
	global_load_lds_dwordx4 v132, s[20:21]
	s_waitcnt vmcnt(8)
	s_waitcnt lgkmcnt(0)
	s_waitcnt lgkmcnt(0)
	v_mfma_f32_16x16x32_bf16 v[124:127], v[144:147], v[184:187], v[124:127]
	v_mfma_f32_16x16x32_bf16 v[120:123], v[160:163], v[184:187], v[120:123]
	v_mfma_f32_16x16x32_bf16 v[124:127], v[156:159], v[188:191], v[124:127]
	v_mfma_f32_16x16x32_bf16 v[120:123], v[164:167], v[188:191], v[120:123]
	s_barrier
	v_mfma_f32_16x16x32_bf16 v[108:111], v[144:147], v[192:195], v[108:111]
	v_mfma_f32_16x16x32_bf16 v[104:107], v[160:163], v[192:195], v[104:107]
	v_mfma_f32_16x16x32_bf16 v[92:95], v[144:147], v[200:203], v[92:95]
	v_mfma_f32_16x16x32_bf16 v[88:91], v[160:163], v[200:203], v[88:91]
	v_mfma_f32_16x16x32_bf16 v[76:79], v[144:147], v[208:211], v[76:79]
	v_mfma_f32_16x16x32_bf16 v[72:75], v[160:163], v[208:211], v[72:75]
	v_mfma_f32_16x16x32_bf16 v[116:119], v[168:171], v[184:187], v[116:119]
	v_mfma_f32_16x16x32_bf16 v[112:115], v[176:179], v[184:187], v[112:115]
	v_mfma_f32_16x16x32_bf16 v[100:103], v[168:171], v[192:195], v[100:103]
	v_mfma_f32_16x16x32_bf16 v[96:99], v[176:179], v[192:195], v[96:99]
	v_mfma_f32_16x16x32_bf16 v[84:87], v[168:171], v[200:203], v[84:87]
	v_mfma_f32_16x16x32_bf16 v[80:83], v[176:179], v[200:203], v[80:83]
	v_mfma_f32_16x16x32_bf16 v[68:71], v[168:171], v[208:211], v[68:71]
	v_mfma_f32_16x16x32_bf16 v[64:67], v[176:179], v[208:211], v[64:67]
	v_mfma_f32_16x16x32_bf16 v[108:111], v[156:159], v[196:199], v[108:111]
	v_mfma_f32_16x16x32_bf16 v[104:107], v[164:167], v[196:199], v[104:107]
	v_mfma_f32_16x16x32_bf16 v[92:95], v[156:159], v[204:207], v[92:95]
	v_mfma_f32_16x16x32_bf16 v[88:91], v[164:167], v[204:207], v[88:91]
	v_mfma_f32_16x16x32_bf16 v[76:79], v[156:159], v[212:215], v[76:79]
	v_mfma_f32_16x16x32_bf16 v[72:75], v[164:167], v[212:215], v[72:75]
	v_mfma_f32_16x16x32_bf16 v[116:119], v[172:175], v[188:191], v[116:119]
	v_mfma_f32_16x16x32_bf16 v[112:115], v[180:183], v[188:191], v[112:115]
	v_mfma_f32_16x16x32_bf16 v[100:103], v[172:175], v[196:199], v[100:103]
	v_mfma_f32_16x16x32_bf16 v[96:99], v[180:183], v[196:199], v[96:99]
	v_mfma_f32_16x16x32_bf16 v[84:87], v[172:175], v[204:207], v[84:87]
	v_mfma_f32_16x16x32_bf16 v[80:83], v[180:183], v[204:207], v[80:83]
	v_mfma_f32_16x16x32_bf16 v[68:71], v[172:175], v[212:215], v[68:71]
	v_mfma_f32_16x16x32_bf16 v[64:67], v[180:183], v[212:215], v[64:67]
	s_barrier
	s_add_i32 s20, s3, s7
	v_lshl_add_u64 v[216:217], v[216:217], 0, s[14:15]
	s_mov_b32 m0, s20
	ds_read_b128 v[184:187], v153 offset:49152
	ds_read_b128 v[188:191], v153 offset:50176
	ds_read_b128 v[192:195], v153 offset:51200
	ds_read_b128 v[196:199], v153 offset:52224
	ds_read_b128 v[200:203], v153 offset:53248
	ds_read_b128 v[204:207], v153 offset:54272
	ds_read_b128 v[208:211], v153 offset:55296
	ds_read_b128 v[212:215], v153 offset:56320
	global_load_lds_dwordx4 v[216:217], off
	s_add_i32 m0, s20, 0x2000
	s_add_u32 s20, s24, 0x160080
	v_lshl_add_u64 v[216:217], v[218:219], 0, s[14:15]
	s_addc_u32 s21, s25, 0
	s_add_i32 s24, s58, s7
	global_load_lds_dwordx4 v[216:217], off
	s_mov_b32 m0, s24
	s_nop 0
	global_load_lds_dwordx4 v130, s[20:21]
	s_add_i32 m0, s24, 0x2000
	s_nop 0
	global_load_lds_dwordx4 v134, s[20:21]
	v_lshl_add_u64 v[216:217], v[222:223], 0, s[14:15]
	s_mov_b32 m0, s35
	s_nop 0
	global_load_lds_dwordx4 v[216:217], off
	v_lshl_add_u64 v[216:217], v[224:225], 0, s[14:15]
	s_mov_b32 m0, s38
	s_nop 0
	global_load_lds_dwordx4 v[216:217], off
	s_waitcnt vmcnt(8)
	s_waitcnt lgkmcnt(0)
	s_waitcnt lgkmcnt(0)
	v_mfma_f32_16x16x32_bf16 v[60:63], v[144:147], v[184:187], v[60:63]
	v_mfma_f32_16x16x32_bf16 v[56:59], v[160:163], v[184:187], v[56:59]
	v_mfma_f32_16x16x32_bf16 v[60:63], v[156:159], v[188:191], v[60:63]
	v_mfma_f32_16x16x32_bf16 v[56:59], v[164:167], v[188:191], v[56:59]
	s_barrier
	v_mfma_f32_16x16x32_bf16 v[44:47], v[144:147], v[192:195], v[44:47]
	v_mfma_f32_16x16x32_bf16 v[40:43], v[160:163], v[192:195], v[40:43]
	v_mfma_f32_16x16x32_bf16 v[28:31], v[144:147], v[200:203], v[28:31]
	v_mfma_f32_16x16x32_bf16 v[24:27], v[160:163], v[200:203], v[24:27]
	v_mfma_f32_16x16x32_bf16 v[12:15], v[144:147], v[208:211], v[12:15]
	v_mfma_f32_16x16x32_bf16 v[8:11], v[160:163], v[208:211], v[8:11]
	v_mfma_f32_16x16x32_bf16 v[52:55], v[168:171], v[184:187], v[52:55]
	v_mfma_f32_16x16x32_bf16 v[48:51], v[176:179], v[184:187], v[48:51]
	v_mfma_f32_16x16x32_bf16 v[36:39], v[168:171], v[192:195], v[36:39]
	v_mfma_f32_16x16x32_bf16 v[32:35], v[176:179], v[192:195], v[32:35]
	v_mfma_f32_16x16x32_bf16 v[20:23], v[168:171], v[200:203], v[20:23]
	v_mfma_f32_16x16x32_bf16 v[16:19], v[176:179], v[200:203], v[16:19]
	v_mfma_f32_16x16x32_bf16 v[4:7], v[168:171], v[208:211], v[4:7]
	v_mfma_f32_16x16x32_bf16 v[0:3], v[176:179], v[208:211], v[0:3]
	v_mfma_f32_16x16x32_bf16 v[44:47], v[156:159], v[196:199], v[44:47]
	v_mfma_f32_16x16x32_bf16 v[40:43], v[164:167], v[196:199], v[40:43]
	v_mfma_f32_16x16x32_bf16 v[28:31], v[156:159], v[204:207], v[28:31]
	v_mfma_f32_16x16x32_bf16 v[24:27], v[164:167], v[204:207], v[24:27]
	v_mfma_f32_16x16x32_bf16 v[12:15], v[156:159], v[212:215], v[12:15]
	v_mfma_f32_16x16x32_bf16 v[8:11], v[164:167], v[212:215], v[8:11]
	v_mfma_f32_16x16x32_bf16 v[52:55], v[172:175], v[188:191], v[52:55]
	v_mfma_f32_16x16x32_bf16 v[48:51], v[180:183], v[188:191], v[48:51]
	v_mfma_f32_16x16x32_bf16 v[36:39], v[172:175], v[196:199], v[36:39]
	v_mfma_f32_16x16x32_bf16 v[32:35], v[180:183], v[196:199], v[32:35]
	v_mfma_f32_16x16x32_bf16 v[20:23], v[172:175], v[204:207], v[20:23]
	v_mfma_f32_16x16x32_bf16 v[16:19], v[180:183], v[204:207], v[16:19]
	v_mfma_f32_16x16x32_bf16 v[4:7], v[172:175], v[212:215], v[4:7]
	v_mfma_f32_16x16x32_bf16 v[0:3], v[180:183], v[212:215], v[0:3]
	s_barrier
	s_add_i32 s48, s48, 2
	s_add_u32 s46, s46, 0x100
	s_addc_u32 s47, s47, 0
	s_cmpk_gt_u32 s48, 0x55
	s_mov_b64 s[20:21], s[22:23]
	s_cbranch_scc0 .LBB0_1555
	s_and_b64 vcc, exec, s[16:17]
	s_cbranch_vccz .LBB0_1558
	s_barrier

.LBB0_1647:
	v_add_u32_e32 v156, s95, v159
	ds_read_b128 v[162:165], v156
	ds_read_b128 v[166:169], v156 offset:1024
	ds_read_b128 v[170:173], v156 offset:2048
	ds_read_b128 v[174:177], v156 offset:3072
	v_add_u32_e32 v156, s33, v159
	ds_read_b128 v[178:181], v156
	ds_read_b128 v[182:185], v156 offset:1024
	ds_read_b128 v[186:189], v156 offset:2048
	ds_read_b128 v[190:193], v156 offset:3072
	s_add_u32 s44, s40, 0xfff80080
	s_addc_u32 s45, s41, -1
	s_and_b64 s[42:43], s[42:43], exec
	s_cselect_b32 s45, s29, s45
	s_cselect_b32 s44, s63, s44
	s_cselect_b32 s43, s27, s66
	s_cselect_b32 s42, s64, s65
	s_add_i32 m0, s17, 0xc000
	ds_read_b128 v[194:197], v161
	ds_read_b128 v[198:201], v161 offset:1024
	ds_read_b128 v[202:205], v161 offset:2048
	ds_read_b128 v[206:209], v161 offset:3072
	ds_read_b128 v[210:213], v161 offset:4096
	ds_read_b128 v[214:217], v161 offset:5120
	ds_read_b128 v[222:225], v161 offset:6144
	ds_read_b128 v[226:229], v161 offset:7168
	global_load_lds_dwordx4 v136, s[40:41]
	s_add_i32 m0, s17, 0xe000
	s_nop 0
	global_load_lds_dwordx4 v138, s[40:41]
	s_waitcnt vmcnt(8)
	s_waitcnt lgkmcnt(0)
	s_waitcnt lgkmcnt(0)
	v_mfma_f32_16x16x32_bf16 v[124:127], v[162:165], v[194:197], v[124:127]
	v_mfma_f32_16x16x32_bf16 v[120:123], v[170:173], v[194:197], v[120:123]
	v_mfma_f32_16x16x32_bf16 v[124:127], v[166:169], v[198:201], v[124:127]
	v_mfma_f32_16x16x32_bf16 v[120:123], v[174:177], v[198:201], v[120:123]
	s_barrier
	v_mfma_f32_16x16x32_bf16 v[116:119], v[162:165], v[202:205], v[116:119]
	v_mfma_f32_16x16x32_bf16 v[104:107], v[170:173], v[202:205], v[104:107]
	v_mfma_f32_16x16x32_bf16 v[92:95], v[162:165], v[210:213], v[92:95]
	v_mfma_f32_16x16x32_bf16 v[88:91], v[170:173], v[210:213], v[88:91]
	v_mfma_f32_16x16x32_bf16 v[84:87], v[162:165], v[222:225], v[84:87]
	v_mfma_f32_16x16x32_bf16 v[72:75], v[170:173], v[222:225], v[72:75]
	v_mfma_f32_16x16x32_bf16 v[112:115], v[178:181], v[194:197], v[112:115]
	v_mfma_f32_16x16x32_bf16 v[108:111], v[186:189], v[194:197], v[108:111]
	v_mfma_f32_16x16x32_bf16 v[100:103], v[178:181], v[202:205], v[100:103]
	v_mfma_f32_16x16x32_bf16 v[96:99], v[186:189], v[202:205], v[96:99]
	v_mfma_f32_16x16x32_bf16 v[80:83], v[178:181], v[210:213], v[80:83]
	v_mfma_f32_16x16x32_bf16 v[76:79], v[186:189], v[210:213], v[76:79]
	v_mfma_f32_16x16x32_bf16 v[68:71], v[178:181], v[222:225], v[68:71]
	v_mfma_f32_16x16x32_bf16 v[64:67], v[186:189], v[222:225], v[64:67]
	v_mfma_f32_16x16x32_bf16 v[116:119], v[166:169], v[206:209], v[116:119]
	v_mfma_f32_16x16x32_bf16 v[104:107], v[174:177], v[206:209], v[104:107]
	v_mfma_f32_16x16x32_bf16 v[92:95], v[166:169], v[214:217], v[92:95]
	v_mfma_f32_16x16x32_bf16 v[88:91], v[174:177], v[214:217], v[88:91]
	v_mfma_f32_16x16x32_bf16 v[84:87], v[166:169], v[226:229], v[84:87]
	v_mfma_f32_16x16x32_bf16 v[72:75], v[174:177], v[226:229], v[72:75]
	v_mfma_f32_16x16x32_bf16 v[112:115], v[182:185], v[198:201], v[112:115]
	v_mfma_f32_16x16x32_bf16 v[108:111], v[190:193], v[198:201], v[108:111]
	v_mfma_f32_16x16x32_bf16 v[100:103], v[182:185], v[206:209], v[100:103]
	v_mfma_f32_16x16x32_bf16 v[96:99], v[190:193], v[206:209], v[96:99]
	v_mfma_f32_16x16x32_bf16 v[80:83], v[182:185], v[214:217], v[80:83]
	v_mfma_f32_16x16x32_bf16 v[76:79], v[190:193], v[214:217], v[76:79]
	v_mfma_f32_16x16x32_bf16 v[68:71], v[182:185], v[226:229], v[68:71]
	v_mfma_f32_16x16x32_bf16 v[64:67], v[190:193], v[226:229], v[64:67]
	s_barrier
	s_add_i32 s68, s95, s6
	v_lshl_add_u64 v[156:157], s[42:43], 0, v[130:131]
	s_mov_b32 m0, s68
	ds_read_b128 v[194:197], v161 offset:16384
	ds_read_b128 v[198:201], v161 offset:17408
	ds_read_b128 v[202:205], v161 offset:18432
	ds_read_b128 v[206:209], v161 offset:19456
	ds_read_b128 v[210:213], v161 offset:20480
	ds_read_b128 v[214:217], v161 offset:21504
	ds_read_b128 v[222:225], v161 offset:22528
	ds_read_b128 v[226:229], v161 offset:23552
	global_load_lds_dwordx4 v[156:157], off
	s_add_i32 m0, s68, 0x2000
	s_add_u32 s68, s42, 0x80000
	v_lshl_add_u64 v[218:219], s[42:43], 0, v[134:135]
	s_addc_u32 s69, s43, 0
	s_add_i32 s70, s33, s6
	global_load_lds_dwordx4 v[218:219], off
	s_mov_b32 m0, s70
	v_lshl_add_u64 v[232:233], s[44:45], 0, v[132:133]
	global_load_lds_dwordx4 v130, s[68:69]
	s_add_i32 m0, s70, 0x2000
	s_nop 0
	global_load_lds_dwordx4 v134, s[68:69]
	v_lshl_add_u64 v[230:231], s[44:45], 0, v[128:129]
	s_mov_b32 m0, s17
	s_nop 0
	global_load_lds_dwordx4 v[230:231], off
	s_mov_b32 m0, s19
	s_nop 0
	global_load_lds_dwordx4 v[232:233], off
	s_waitcnt vmcnt(8)
	s_waitcnt lgkmcnt(0)
	s_waitcnt lgkmcnt(0)
	v_mfma_f32_16x16x32_bf16 v[60:63], v[162:165], v[194:197], v[60:63]
	v_mfma_f32_16x16x32_bf16 v[56:59], v[170:173], v[194:197], v[56:59]
	v_mfma_f32_16x16x32_bf16 v[60:63], v[166:169], v[198:201], v[60:63]
	v_mfma_f32_16x16x32_bf16 v[56:59], v[174:177], v[198:201], v[56:59]
	s_barrier
	v_mfma_f32_16x16x32_bf16 v[52:55], v[162:165], v[202:205], v[52:55]
	v_mfma_f32_16x16x32_bf16 v[44:47], v[170:173], v[202:205], v[44:47]
	v_mfma_f32_16x16x32_bf16 v[32:35], v[162:165], v[210:213], v[32:35]
	v_mfma_f32_16x16x32_bf16 v[24:27], v[170:173], v[210:213], v[24:27]
	v_mfma_f32_16x16x32_bf16 v[20:23], v[162:165], v[222:225], v[20:23]
	v_mfma_f32_16x16x32_bf16 v[12:15], v[170:173], v[222:225], v[12:15]
	v_mfma_f32_16x16x32_bf16 v[48:51], v[178:181], v[194:197], v[48:51]
	v_mfma_f32_16x16x32_bf16 v[40:43], v[186:189], v[194:197], v[40:43]
	v_mfma_f32_16x16x32_bf16 v[36:39], v[178:181], v[202:205], v[36:39]
	v_mfma_f32_16x16x32_bf16 v[28:31], v[186:189], v[202:205], v[28:31]
	v_mfma_f32_16x16x32_bf16 v[16:19], v[178:181], v[210:213], v[16:19]
	v_mfma_f32_16x16x32_bf16 v[8:11], v[186:189], v[210:213], v[8:11]
	v_mfma_f32_16x16x32_bf16 v[4:7], v[178:181], v[222:225], v[4:7]
	v_mfma_f32_16x16x32_bf16 v[0:3], v[186:189], v[222:225], v[0:3]
	v_mfma_f32_16x16x32_bf16 v[52:55], v[166:169], v[206:209], v[52:55]
	v_mfma_f32_16x16x32_bf16 v[44:47], v[174:177], v[206:209], v[44:47]
	v_mfma_f32_16x16x32_bf16 v[32:35], v[166:169], v[214:217], v[32:35]
	v_mfma_f32_16x16x32_bf16 v[24:27], v[174:177], v[214:217], v[24:27]
	v_mfma_f32_16x16x32_bf16 v[20:23], v[166:169], v[226:229], v[20:23]
	v_mfma_f32_16x16x32_bf16 v[12:15], v[174:177], v[226:229], v[12:15]
	v_mfma_f32_16x16x32_bf16 v[48:51], v[182:185], v[198:201], v[48:51]
	v_mfma_f32_16x16x32_bf16 v[40:43], v[190:193], v[198:201], v[40:43]
	v_mfma_f32_16x16x32_bf16 v[36:39], v[182:185], v[206:209], v[36:39]
	v_mfma_f32_16x16x32_bf16 v[28:31], v[190:193], v[206:209], v[28:31]
	v_mfma_f32_16x16x32_bf16 v[16:19], v[182:185], v[214:217], v[16:19]
	v_mfma_f32_16x16x32_bf16 v[8:11], v[190:193], v[214:217], v[8:11]
	v_mfma_f32_16x16x32_bf16 v[4:7], v[182:185], v[226:229], v[4:7]
	v_mfma_f32_16x16x32_bf16 v[0:3], v[190:193], v[226:229], v[0:3]
	s_barrier
	v_add_u32_e32 v174, s3, v159
	v_add_u32_e32 v190, s58, v159
	ds_read_b128 v[162:165], v174
	ds_read_b128 v[166:169], v174 offset:1024
	ds_read_b128 v[170:173], v174 offset:2048
	ds_read_b128 v[174:177], v174 offset:3072
	ds_read_b128 v[178:181], v190
	ds_read_b128 v[182:185], v190 offset:1024
	ds_read_b128 v[186:189], v190 offset:2048
	ds_read_b128 v[190:193], v190 offset:3072
	s_add_u32 s44, s44, 0x80000
	s_addc_u32 s45, s45, 0
	s_mov_b32 m0, s46
	ds_read_b128 v[194:197], v161 offset:32768
	ds_read_b128 v[198:201], v161 offset:33792
	ds_read_b128 v[202:205], v161 offset:34816
	ds_read_b128 v[206:209], v161 offset:35840
	ds_read_b128 v[210:213], v161 offset:36864
	ds_read_b128 v[214:217], v161 offset:37888
	ds_read_b128 v[222:225], v161 offset:38912
	ds_read_b128 v[226:229], v161 offset:39936
	global_load_lds_dwordx4 v128, s[44:45]
	s_mov_b32 m0, s47
	s_nop 0
	global_load_lds_dwordx4 v132, s[44:45]
	s_waitcnt vmcnt(8)
	s_waitcnt lgkmcnt(0)
	s_waitcnt lgkmcnt(0)
	v_mfma_f32_16x16x32_bf16 v[124:127], v[162:165], v[194:197], v[124:127]
	v_mfma_f32_16x16x32_bf16 v[120:123], v[170:173], v[194:197], v[120:123]
	v_mfma_f32_16x16x32_bf16 v[124:127], v[166:169], v[198:201], v[124:127]
	v_mfma_f32_16x16x32_bf16 v[120:123], v[174:177], v[198:201], v[120:123]
	s_barrier
	v_mfma_f32_16x16x32_bf16 v[116:119], v[162:165], v[202:205], v[116:119]
	v_mfma_f32_16x16x32_bf16 v[104:107], v[170:173], v[202:205], v[104:107]
	v_mfma_f32_16x16x32_bf16 v[92:95], v[162:165], v[210:213], v[92:95]
	v_mfma_f32_16x16x32_bf16 v[88:91], v[170:173], v[210:213], v[88:91]
	v_mfma_f32_16x16x32_bf16 v[84:87], v[162:165], v[222:225], v[84:87]
	v_mfma_f32_16x16x32_bf16 v[72:75], v[170:173], v[222:225], v[72:75]
	v_mfma_f32_16x16x32_bf16 v[112:115], v[178:181], v[194:197], v[112:115]
	v_mfma_f32_16x16x32_bf16 v[108:111], v[186:189], v[194:197], v[108:111]
	v_mfma_f32_16x16x32_bf16 v[100:103], v[178:181], v[202:205], v[100:103]
	v_mfma_f32_16x16x32_bf16 v[96:99], v[186:189], v[202:205], v[96:99]
	v_mfma_f32_16x16x32_bf16 v[80:83], v[178:181], v[210:213], v[80:83]
	v_mfma_f32_16x16x32_bf16 v[76:79], v[186:189], v[210:213], v[76:79]
	v_mfma_f32_16x16x32_bf16 v[68:71], v[178:181], v[222:225], v[68:71]
	v_mfma_f32_16x16x32_bf16 v[64:67], v[186:189], v[222:225], v[64:67]
	v_mfma_f32_16x16x32_bf16 v[116:119], v[166:169], v[206:209], v[116:119]
	v_mfma_f32_16x16x32_bf16 v[104:107], v[174:177], v[206:209], v[104:107]
	v_mfma_f32_16x16x32_bf16 v[92:95], v[166:169], v[214:217], v[92:95]
	v_mfma_f32_16x16x32_bf16 v[88:91], v[174:177], v[214:217], v[88:91]
	v_mfma_f32_16x16x32_bf16 v[84:87], v[166:169], v[226:229], v[84:87]
	v_mfma_f32_16x16x32_bf16 v[72:75], v[174:177], v[226:229], v[72:75]
	v_mfma_f32_16x16x32_bf16 v[112:115], v[182:185], v[198:201], v[112:115]
	v_mfma_f32_16x16x32_bf16 v[108:111], v[190:193], v[198:201], v[108:111]
	v_mfma_f32_16x16x32_bf16 v[100:103], v[182:185], v[206:209], v[100:103]
	v_mfma_f32_16x16x32_bf16 v[96:99], v[190:193], v[206:209], v[96:99]
	v_mfma_f32_16x16x32_bf16 v[80:83], v[182:185], v[214:217], v[80:83]
	v_mfma_f32_16x16x32_bf16 v[76:79], v[190:193], v[214:217], v[76:79]
	v_mfma_f32_16x16x32_bf16 v[68:71], v[182:185], v[226:229], v[68:71]
	v_mfma_f32_16x16x32_bf16 v[64:67], v[190:193], v[226:229], v[64:67]
	s_barrier
	s_add_i32 s44, s3, s6
	v_lshl_add_u64 v[156:157], v[156:157], 0, s[8:9]
	s_mov_b32 m0, s44
	ds_read_b128 v[194:197], v161 offset:49152
	ds_read_b128 v[198:201], v161 offset:50176
	ds_read_b128 v[202:205], v161 offset:51200
	ds_read_b128 v[206:209], v161 offset:52224
	ds_read_b128 v[210:213], v161 offset:53248
	ds_read_b128 v[214:217], v161 offset:54272
	ds_read_b128 v[222:225], v161 offset:55296
	ds_read_b128 v[226:229], v161 offset:56320
	global_load_lds_dwordx4 v[156:157], off
	s_add_i32 m0, s44, 0x2000
	s_add_u32 s42, s42, 0x80080
	v_lshl_add_u64 v[156:157], v[218:219], 0, s[8:9]
	s_addc_u32 s43, s43, 0
	s_add_i32 s44, s58, s6
	global_load_lds_dwordx4 v[156:157], off
	s_mov_b32 m0, s44
	s_nop 0
	global_load_lds_dwordx4 v130, s[42:43]
	s_add_i32 m0, s44, 0x2000
	s_nop 0
	global_load_lds_dwordx4 v134, s[42:43]
	v_lshl_add_u64 v[156:157], v[230:231], 0, s[8:9]
	s_mov_b32 m0, s49
	s_nop 0
	global_load_lds_dwordx4 v[156:157], off
	v_lshl_add_u64 v[156:157], v[232:233], 0, s[8:9]
	s_mov_b32 m0, s50
	s_nop 0
	global_load_lds_dwordx4 v[156:157], off
	s_waitcnt vmcnt(8)
	s_waitcnt lgkmcnt(0)
	s_waitcnt lgkmcnt(0)
	v_mfma_f32_16x16x32_bf16 v[60:63], v[162:165], v[194:197], v[60:63]
	v_mfma_f32_16x16x32_bf16 v[56:59], v[170:173], v[194:197], v[56:59]
	v_mfma_f32_16x16x32_bf16 v[60:63], v[166:169], v[198:201], v[60:63]
	v_mfma_f32_16x16x32_bf16 v[56:59], v[174:177], v[198:201], v[56:59]
	s_barrier
	v_mfma_f32_16x16x32_bf16 v[52:55], v[162:165], v[202:205], v[52:55]
	v_mfma_f32_16x16x32_bf16 v[44:47], v[170:173], v[202:205], v[44:47]
	v_mfma_f32_16x16x32_bf16 v[32:35], v[162:165], v[210:213], v[32:35]
	v_mfma_f32_16x16x32_bf16 v[24:27], v[170:173], v[210:213], v[24:27]
	v_mfma_f32_16x16x32_bf16 v[20:23], v[162:165], v[222:225], v[20:23]
	v_mfma_f32_16x16x32_bf16 v[12:15], v[170:173], v[222:225], v[12:15]
	v_mfma_f32_16x16x32_bf16 v[48:51], v[178:181], v[194:197], v[48:51]
	v_mfma_f32_16x16x32_bf16 v[40:43], v[186:189], v[194:197], v[40:43]
	v_mfma_f32_16x16x32_bf16 v[36:39], v[178:181], v[202:205], v[36:39]
	v_mfma_f32_16x16x32_bf16 v[28:31], v[186:189], v[202:205], v[28:31]
	v_mfma_f32_16x16x32_bf16 v[16:19], v[178:181], v[210:213], v[16:19]
	v_mfma_f32_16x16x32_bf16 v[8:11], v[186:189], v[210:213], v[8:11]
	v_mfma_f32_16x16x32_bf16 v[4:7], v[178:181], v[222:225], v[4:7]
	v_mfma_f32_16x16x32_bf16 v[0:3], v[186:189], v[222:225], v[0:3]
	v_mfma_f32_16x16x32_bf16 v[52:55], v[166:169], v[206:209], v[52:55]
	v_mfma_f32_16x16x32_bf16 v[44:47], v[174:177], v[206:209], v[44:47]
	v_mfma_f32_16x16x32_bf16 v[32:35], v[166:169], v[214:217], v[32:35]
	v_mfma_f32_16x16x32_bf16 v[24:27], v[174:177], v[214:217], v[24:27]
	v_mfma_f32_16x16x32_bf16 v[20:23], v[166:169], v[226:229], v[20:23]
	v_mfma_f32_16x16x32_bf16 v[12:15], v[174:177], v[226:229], v[12:15]
	v_mfma_f32_16x16x32_bf16 v[48:51], v[182:185], v[198:201], v[48:51]
	v_mfma_f32_16x16x32_bf16 v[40:43], v[190:193], v[198:201], v[40:43]
	v_mfma_f32_16x16x32_bf16 v[36:39], v[182:185], v[206:209], v[36:39]
	v_mfma_f32_16x16x32_bf16 v[28:31], v[190:193], v[206:209], v[28:31]
	v_mfma_f32_16x16x32_bf16 v[16:19], v[182:185], v[214:217], v[16:19]
	v_mfma_f32_16x16x32_bf16 v[8:11], v[190:193], v[214:217], v[8:11]
	v_mfma_f32_16x16x32_bf16 v[4:7], v[182:185], v[226:229], v[4:7]
	v_mfma_f32_16x16x32_bf16 v[0:3], v[190:193], v[226:229], v[0:3]
	s_barrier
	s_add_i32 s67, s67, 2
	s_add_u32 s40, s40, 0x100
	s_addc_u32 s41, s41, 0
	s_add_u32 s65, s65, 0x100
	s_addc_u32 s66, s66, 0
	s_cmp_gt_u32 s67, 29
	s_cbranch_scc1 .LBB0_1650

.LBB0_1865:
	ds_read_b128 v[144:147], v151
	ds_read_b128 v[156:159], v151 offset:1024
	ds_read_b128 v[160:163], v151 offset:2048
	ds_read_b128 v[164:167], v151 offset:3072
	ds_read_b128 v[168:171], v152
	ds_read_b128 v[172:175], v152 offset:1024
	ds_read_b128 v[176:179], v152 offset:2048
	ds_read_b128 v[180:183], v152 offset:3072
	s_add_u32 s30, s28, 0xfff80080
	s_addc_u32 s31, s29, -1
	s_cmp_eq_u32 s50, 28
	s_cselect_b32 s35, s19, s31
	s_cselect_b32 s34, s25, s30
	s_cselect_b32 s31, s17, s49
	s_cselect_b32 s30, s47, s48
	s_add_i32 m0, s27, 0xc000
	ds_read_b128 v[184:187], v153
	ds_read_b128 v[188:191], v153 offset:1024
	ds_read_b128 v[192:195], v153 offset:2048
	ds_read_b128 v[196:199], v153 offset:3072
	ds_read_b128 v[200:203], v153 offset:4096
	ds_read_b128 v[204:207], v153 offset:5120
	ds_read_b128 v[208:211], v153 offset:6144
	ds_read_b128 v[212:215], v153 offset:7168
	global_load_lds_dwordx4 v136, s[28:29]
	s_add_i32 m0, s27, 0xe000
	s_nop 0
	global_load_lds_dwordx4 v138, s[28:29]
	s_waitcnt vmcnt(8)
	s_waitcnt lgkmcnt(0)
	s_waitcnt lgkmcnt(0)
	v_mfma_f32_16x16x32_bf16 v[124:127], v[144:147], v[184:187], v[124:127]
	v_mfma_f32_16x16x32_bf16 v[120:123], v[160:163], v[184:187], v[120:123]
	v_mfma_f32_16x16x32_bf16 v[124:127], v[156:159], v[188:191], v[124:127]
	v_mfma_f32_16x16x32_bf16 v[120:123], v[164:167], v[188:191], v[120:123]
	s_barrier
	v_mfma_f32_16x16x32_bf16 v[108:111], v[144:147], v[192:195], v[108:111]
	v_mfma_f32_16x16x32_bf16 v[104:107], v[160:163], v[192:195], v[104:107]
	v_mfma_f32_16x16x32_bf16 v[92:95], v[144:147], v[200:203], v[92:95]
	v_mfma_f32_16x16x32_bf16 v[88:91], v[160:163], v[200:203], v[88:91]
	v_mfma_f32_16x16x32_bf16 v[76:79], v[144:147], v[208:211], v[76:79]
	v_mfma_f32_16x16x32_bf16 v[72:75], v[160:163], v[208:211], v[72:75]
	v_mfma_f32_16x16x32_bf16 v[116:119], v[168:171], v[184:187], v[116:119]
	v_mfma_f32_16x16x32_bf16 v[112:115], v[176:179], v[184:187], v[112:115]
	v_mfma_f32_16x16x32_bf16 v[100:103], v[168:171], v[192:195], v[100:103]
	v_mfma_f32_16x16x32_bf16 v[96:99], v[176:179], v[192:195], v[96:99]
	v_mfma_f32_16x16x32_bf16 v[84:87], v[168:171], v[200:203], v[84:87]
	v_mfma_f32_16x16x32_bf16 v[80:83], v[176:179], v[200:203], v[80:83]
	v_mfma_f32_16x16x32_bf16 v[68:71], v[168:171], v[208:211], v[68:71]
	v_mfma_f32_16x16x32_bf16 v[64:67], v[176:179], v[208:211], v[64:67]
	v_mfma_f32_16x16x32_bf16 v[108:111], v[156:159], v[196:199], v[108:111]
	v_mfma_f32_16x16x32_bf16 v[104:107], v[164:167], v[196:199], v[104:107]
	v_mfma_f32_16x16x32_bf16 v[92:95], v[156:159], v[204:207], v[92:95]
	v_mfma_f32_16x16x32_bf16 v[88:91], v[164:167], v[204:207], v[88:91]
	v_mfma_f32_16x16x32_bf16 v[76:79], v[156:159], v[212:215], v[76:79]
	v_mfma_f32_16x16x32_bf16 v[72:75], v[164:167], v[212:215], v[72:75]
	v_mfma_f32_16x16x32_bf16 v[116:119], v[172:175], v[188:191], v[116:119]
	v_mfma_f32_16x16x32_bf16 v[112:115], v[180:183], v[188:191], v[112:115]
	v_mfma_f32_16x16x32_bf16 v[100:103], v[172:175], v[196:199], v[100:103]
	v_mfma_f32_16x16x32_bf16 v[96:99], v[180:183], v[196:199], v[96:99]
	v_mfma_f32_16x16x32_bf16 v[84:87], v[172:175], v[204:207], v[84:87]
	v_mfma_f32_16x16x32_bf16 v[80:83], v[180:183], v[204:207], v[80:83]
	v_mfma_f32_16x16x32_bf16 v[68:71], v[172:175], v[212:215], v[68:71]
	v_mfma_f32_16x16x32_bf16 v[64:67], v[180:183], v[212:215], v[64:67]
	s_barrier
	s_add_i32 s51, s95, s7
	v_lshl_add_u64 v[216:217], s[30:31], 0, v[130:131]
	s_mov_b32 m0, s51
	ds_read_b128 v[184:187], v153 offset:16384
	ds_read_b128 v[188:191], v153 offset:17408
	ds_read_b128 v[192:195], v153 offset:18432
	ds_read_b128 v[196:199], v153 offset:19456
	ds_read_b128 v[200:203], v153 offset:20480
	ds_read_b128 v[204:207], v153 offset:21504
	ds_read_b128 v[208:211], v153 offset:22528
	ds_read_b128 v[212:215], v153 offset:23552
	global_load_lds_dwordx4 v[216:217], off
	s_add_i32 m0, s51, 0x2000
	s_add_u32 s54, s30, 0x80000
	v_lshl_add_u64 v[218:219], s[30:31], 0, v[134:135]
	s_addc_u32 s55, s31, 0
	s_add_i32 s51, s33, s7
	global_load_lds_dwordx4 v[218:219], off
	s_mov_b32 m0, s51
	v_lshl_add_u64 v[224:225], s[34:35], 0, v[132:133]
	global_load_lds_dwordx4 v130, s[54:55]
	s_add_i32 m0, s51, 0x2000
	s_nop 0
	global_load_lds_dwordx4 v134, s[54:55]
	v_lshl_add_u64 v[222:223], s[34:35], 0, v[128:129]
	s_mov_b32 m0, s27
	s_nop 0
	global_load_lds_dwordx4 v[222:223], off
	s_mov_b32 m0, s38
	s_nop 0
	global_load_lds_dwordx4 v[224:225], off
	s_waitcnt vmcnt(8)
	s_waitcnt lgkmcnt(0)
	s_waitcnt lgkmcnt(0)
	v_mfma_f32_16x16x32_bf16 v[60:63], v[144:147], v[184:187], v[60:63]
	v_mfma_f32_16x16x32_bf16 v[56:59], v[160:163], v[184:187], v[56:59]
	v_mfma_f32_16x16x32_bf16 v[60:63], v[156:159], v[188:191], v[60:63]
	v_mfma_f32_16x16x32_bf16 v[56:59], v[164:167], v[188:191], v[56:59]
	s_barrier
	v_mfma_f32_16x16x32_bf16 v[44:47], v[144:147], v[192:195], v[44:47]
	v_mfma_f32_16x16x32_bf16 v[40:43], v[160:163], v[192:195], v[40:43]
	v_mfma_f32_16x16x32_bf16 v[28:31], v[144:147], v[200:203], v[28:31]
	v_mfma_f32_16x16x32_bf16 v[24:27], v[160:163], v[200:203], v[24:27]
	v_mfma_f32_16x16x32_bf16 v[12:15], v[144:147], v[208:211], v[12:15]
	v_mfma_f32_16x16x32_bf16 v[8:11], v[160:163], v[208:211], v[8:11]
	v_mfma_f32_16x16x32_bf16 v[52:55], v[168:171], v[184:187], v[52:55]
	v_mfma_f32_16x16x32_bf16 v[48:51], v[176:179], v[184:187], v[48:51]
	v_mfma_f32_16x16x32_bf16 v[36:39], v[168:171], v[192:195], v[36:39]
	v_mfma_f32_16x16x32_bf16 v[32:35], v[176:179], v[192:195], v[32:35]
	v_mfma_f32_16x16x32_bf16 v[20:23], v[168:171], v[200:203], v[20:23]
	v_mfma_f32_16x16x32_bf16 v[16:19], v[176:179], v[200:203], v[16:19]
	v_mfma_f32_16x16x32_bf16 v[4:7], v[168:171], v[208:211], v[4:7]
	v_mfma_f32_16x16x32_bf16 v[0:3], v[176:179], v[208:211], v[0:3]
	v_mfma_f32_16x16x32_bf16 v[44:47], v[156:159], v[196:199], v[44:47]
	v_mfma_f32_16x16x32_bf16 v[40:43], v[164:167], v[196:199], v[40:43]
	v_mfma_f32_16x16x32_bf16 v[28:31], v[156:159], v[204:207], v[28:31]
	v_mfma_f32_16x16x32_bf16 v[24:27], v[164:167], v[204:207], v[24:27]
	v_mfma_f32_16x16x32_bf16 v[12:15], v[156:159], v[212:215], v[12:15]
	v_mfma_f32_16x16x32_bf16 v[8:11], v[164:167], v[212:215], v[8:11]
	v_mfma_f32_16x16x32_bf16 v[52:55], v[172:175], v[188:191], v[52:55]
	v_mfma_f32_16x16x32_bf16 v[48:51], v[180:183], v[188:191], v[48:51]
	v_mfma_f32_16x16x32_bf16 v[36:39], v[172:175], v[196:199], v[36:39]
	v_mfma_f32_16x16x32_bf16 v[32:35], v[180:183], v[196:199], v[32:35]
	v_mfma_f32_16x16x32_bf16 v[20:23], v[172:175], v[204:207], v[20:23]
	v_mfma_f32_16x16x32_bf16 v[16:19], v[180:183], v[204:207], v[16:19]
	v_mfma_f32_16x16x32_bf16 v[4:7], v[172:175], v[212:215], v[4:7]
	v_mfma_f32_16x16x32_bf16 v[0:3], v[180:183], v[212:215], v[0:3]
	s_barrier
	v_add_u32_e32 v155, s3, v149
	ds_read_b128 v[144:147], v155
	ds_read_b128 v[156:159], v155 offset:1024
	ds_read_b128 v[160:163], v155 offset:2048
	ds_read_b128 v[164:167], v155 offset:3072
	v_add_u32_e32 v155, s58, v149
	ds_read_b128 v[168:171], v155
	ds_read_b128 v[172:175], v155 offset:1024
	ds_read_b128 v[176:179], v155 offset:2048
	ds_read_b128 v[180:183], v155 offset:3072
	s_add_u32 s34, s34, 0x80000
	s_addc_u32 s35, s35, 0
	s_mov_b32 m0, s39
	ds_read_b128 v[184:187], v153 offset:32768
	ds_read_b128 v[188:191], v153 offset:33792
	ds_read_b128 v[192:195], v153 offset:34816
	ds_read_b128 v[196:199], v153 offset:35840
	ds_read_b128 v[200:203], v153 offset:36864
	ds_read_b128 v[204:207], v153 offset:37888
	ds_read_b128 v[208:211], v153 offset:38912
	ds_read_b128 v[212:215], v153 offset:39936
	global_load_lds_dwordx4 v128, s[34:35]
	s_mov_b32 m0, s40
	s_nop 0
	global_load_lds_dwordx4 v132, s[34:35]
	s_waitcnt vmcnt(8)
	s_waitcnt lgkmcnt(0)
	s_waitcnt lgkmcnt(0)
	v_mfma_f32_16x16x32_bf16 v[124:127], v[144:147], v[184:187], v[124:127]
	v_mfma_f32_16x16x32_bf16 v[120:123], v[160:163], v[184:187], v[120:123]
	v_mfma_f32_16x16x32_bf16 v[124:127], v[156:159], v[188:191], v[124:127]
	v_mfma_f32_16x16x32_bf16 v[120:123], v[164:167], v[188:191], v[120:123]
	s_barrier
	v_mfma_f32_16x16x32_bf16 v[108:111], v[144:147], v[192:195], v[108:111]
	v_mfma_f32_16x16x32_bf16 v[104:107], v[160:163], v[192:195], v[104:107]
	v_mfma_f32_16x16x32_bf16 v[92:95], v[144:147], v[200:203], v[92:95]
	v_mfma_f32_16x16x32_bf16 v[88:91], v[160:163], v[200:203], v[88:91]
	v_mfma_f32_16x16x32_bf16 v[76:79], v[144:147], v[208:211], v[76:79]
	v_mfma_f32_16x16x32_bf16 v[72:75], v[160:163], v[208:211], v[72:75]
	v_mfma_f32_16x16x32_bf16 v[116:119], v[168:171], v[184:187], v[116:119]
	v_mfma_f32_16x16x32_bf16 v[112:115], v[176:179], v[184:187], v[112:115]
	v_mfma_f32_16x16x32_bf16 v[100:103], v[168:171], v[192:195], v[100:103]
	v_mfma_f32_16x16x32_bf16 v[96:99], v[176:179], v[192:195], v[96:99]
	v_mfma_f32_16x16x32_bf16 v[84:87], v[168:171], v[200:203], v[84:87]
	v_mfma_f32_16x16x32_bf16 v[80:83], v[176:179], v[200:203], v[80:83]
	v_mfma_f32_16x16x32_bf16 v[68:71], v[168:171], v[208:211], v[68:71]
	v_mfma_f32_16x16x32_bf16 v[64:67], v[176:179], v[208:211], v[64:67]
	v_mfma_f32_16x16x32_bf16 v[108:111], v[156:159], v[196:199], v[108:111]
	v_mfma_f32_16x16x32_bf16 v[104:107], v[164:167], v[196:199], v[104:107]
	v_mfma_f32_16x16x32_bf16 v[92:95], v[156:159], v[204:207], v[92:95]
	v_mfma_f32_16x16x32_bf16 v[88:91], v[164:167], v[204:207], v[88:91]
	v_mfma_f32_16x16x32_bf16 v[76:79], v[156:159], v[212:215], v[76:79]
	v_mfma_f32_16x16x32_bf16 v[72:75], v[164:167], v[212:215], v[72:75]
	v_mfma_f32_16x16x32_bf16 v[116:119], v[172:175], v[188:191], v[116:119]
	v_mfma_f32_16x16x32_bf16 v[112:115], v[180:183], v[188:191], v[112:115]
	v_mfma_f32_16x16x32_bf16 v[100:103], v[172:175], v[196:199], v[100:103]
	v_mfma_f32_16x16x32_bf16 v[96:99], v[180:183], v[196:199], v[96:99]
	v_mfma_f32_16x16x32_bf16 v[84:87], v[172:175], v[204:207], v[84:87]
	v_mfma_f32_16x16x32_bf16 v[80:83], v[180:183], v[204:207], v[80:83]
	v_mfma_f32_16x16x32_bf16 v[68:71], v[172:175], v[212:215], v[68:71]
	v_mfma_f32_16x16x32_bf16 v[64:67], v[180:183], v[212:215], v[64:67]
	s_barrier
	s_add_i32 s34, s3, s7
	v_lshl_add_u64 v[216:217], v[216:217], 0, s[12:13]
	s_mov_b32 m0, s34
	ds_read_b128 v[184:187], v153 offset:49152
	ds_read_b128 v[188:191], v153 offset:50176
	ds_read_b128 v[192:195], v153 offset:51200
	ds_read_b128 v[196:199], v153 offset:52224
	ds_read_b128 v[200:203], v153 offset:53248
	ds_read_b128 v[204:207], v153 offset:54272
	ds_read_b128 v[208:211], v153 offset:55296
	ds_read_b128 v[212:215], v153 offset:56320
	global_load_lds_dwordx4 v[216:217], off
	s_add_i32 m0, s34, 0x2000
	s_add_u32 s30, s30, 0x80080
	v_lshl_add_u64 v[216:217], v[218:219], 0, s[12:13]
	s_addc_u32 s31, s31, 0
	s_add_i32 s34, s58, s7
	global_load_lds_dwordx4 v[216:217], off
	s_mov_b32 m0, s34
	s_nop 0
	global_load_lds_dwordx4 v130, s[30:31]
	s_add_i32 m0, s34, 0x2000
	s_nop 0
	global_load_lds_dwordx4 v134, s[30:31]
	v_lshl_add_u64 v[216:217], v[222:223], 0, s[12:13]
	s_mov_b32 m0, s42
	s_nop 0
	global_load_lds_dwordx4 v[216:217], off
	v_lshl_add_u64 v[216:217], v[224:225], 0, s[12:13]
	s_mov_b32 m0, s43
	s_nop 0
	global_load_lds_dwordx4 v[216:217], off
	s_waitcnt vmcnt(8)
	s_waitcnt lgkmcnt(0)
	s_waitcnt lgkmcnt(0)
	v_mfma_f32_16x16x32_bf16 v[60:63], v[144:147], v[184:187], v[60:63]
	v_mfma_f32_16x16x32_bf16 v[56:59], v[160:163], v[184:187], v[56:59]
	v_mfma_f32_16x16x32_bf16 v[60:63], v[156:159], v[188:191], v[60:63]
	v_mfma_f32_16x16x32_bf16 v[56:59], v[164:167], v[188:191], v[56:59]
	s_barrier
	v_mfma_f32_16x16x32_bf16 v[44:47], v[144:147], v[192:195], v[44:47]
	v_mfma_f32_16x16x32_bf16 v[40:43], v[160:163], v[192:195], v[40:43]
	v_mfma_f32_16x16x32_bf16 v[28:31], v[144:147], v[200:203], v[28:31]
	v_mfma_f32_16x16x32_bf16 v[24:27], v[160:163], v[200:203], v[24:27]
	v_mfma_f32_16x16x32_bf16 v[12:15], v[144:147], v[208:211], v[12:15]
	v_mfma_f32_16x16x32_bf16 v[8:11], v[160:163], v[208:211], v[8:11]
	v_mfma_f32_16x16x32_bf16 v[52:55], v[168:171], v[184:187], v[52:55]
	v_mfma_f32_16x16x32_bf16 v[48:51], v[176:179], v[184:187], v[48:51]
	v_mfma_f32_16x16x32_bf16 v[36:39], v[168:171], v[192:195], v[36:39]
	v_mfma_f32_16x16x32_bf16 v[32:35], v[176:179], v[192:195], v[32:35]
	v_mfma_f32_16x16x32_bf16 v[20:23], v[168:171], v[200:203], v[20:23]
	v_mfma_f32_16x16x32_bf16 v[16:19], v[176:179], v[200:203], v[16:19]
	v_mfma_f32_16x16x32_bf16 v[4:7], v[168:171], v[208:211], v[4:7]
	v_mfma_f32_16x16x32_bf16 v[0:3], v[176:179], v[208:211], v[0:3]
	v_mfma_f32_16x16x32_bf16 v[44:47], v[156:159], v[196:199], v[44:47]
	v_mfma_f32_16x16x32_bf16 v[40:43], v[164:167], v[196:199], v[40:43]
	v_mfma_f32_16x16x32_bf16 v[28:31], v[156:159], v[204:207], v[28:31]
	v_mfma_f32_16x16x32_bf16 v[24:27], v[164:167], v[204:207], v[24:27]
	v_mfma_f32_16x16x32_bf16 v[12:15], v[156:159], v[212:215], v[12:15]
	v_mfma_f32_16x16x32_bf16 v[8:11], v[164:167], v[212:215], v[8:11]
	v_mfma_f32_16x16x32_bf16 v[52:55], v[172:175], v[188:191], v[52:55]
	v_mfma_f32_16x16x32_bf16 v[48:51], v[180:183], v[188:191], v[48:51]
	v_mfma_f32_16x16x32_bf16 v[36:39], v[172:175], v[196:199], v[36:39]
	v_mfma_f32_16x16x32_bf16 v[32:35], v[180:183], v[196:199], v[32:35]
	v_mfma_f32_16x16x32_bf16 v[20:23], v[172:175], v[204:207], v[20:23]
	v_mfma_f32_16x16x32_bf16 v[16:19], v[180:183], v[204:207], v[16:19]
	v_mfma_f32_16x16x32_bf16 v[4:7], v[172:175], v[212:215], v[4:7]
	v_mfma_f32_16x16x32_bf16 v[0:3], v[180:183], v[212:215], v[0:3]
	s_barrier
	s_add_i32 s50, s50, 2
	s_add_u32 s28, s28, 0x100
	s_addc_u32 s29, s29, 0
	s_add_u32 s48, s48, 0x100
	s_addc_u32 s49, s49, 0
	s_cmp_gt_u32 s50, 29
	s_cbranch_scc0 .LBB0_1865
	s_and_b64 vcc, exec, s[14:15]
	s_cbranch_vccz .LBB0_1868
	s_barrier

.LBB0_1949:
	v_add_u32_e32 v153, s95, v161
	ds_read_b128 v[156:159], v153
	ds_read_b128 v[164:167], v153 offset:1024
	ds_read_b128 v[168:171], v153 offset:2048
	ds_read_b128 v[172:175], v153 offset:3072
	v_add_u32_e32 v153, s33, v161
	ds_read_b128 v[176:179], v153
	ds_read_b128 v[180:183], v153 offset:1024
	ds_read_b128 v[184:187], v153 offset:2048
	ds_read_b128 v[188:191], v153 offset:3072
	s_add_u32 s30, s26, 0xfff80080
	s_addc_u32 s31, s27, -1
	s_and_b64 s[28:29], s[28:29], exec
	s_cselect_b32 s31, s21, s31
	s_cselect_b32 s30, s47, s30
	s_cselect_b32 s29, s19, s50
	s_cselect_b32 s28, s48, s49
	s_add_i32 m0, s35, 0xc000
	ds_read_b128 v[192:195], v163
	ds_read_b128 v[196:199], v163 offset:1024
	ds_read_b128 v[200:203], v163 offset:2048
	ds_read_b128 v[204:207], v163 offset:3072
	ds_read_b128 v[208:211], v163 offset:4096
	ds_read_b128 v[212:215], v163 offset:5120
	ds_read_b128 v[216:219], v163 offset:6144
	ds_read_b128 v[222:225], v163 offset:7168
	global_load_lds_dwordx4 v136, s[26:27]
	s_add_i32 m0, s35, 0xe000
	s_nop 0
	global_load_lds_dwordx4 v138, s[26:27]
	s_waitcnt vmcnt(8)
	s_waitcnt lgkmcnt(0)
	s_waitcnt lgkmcnt(0)
	v_mfma_f32_16x16x32_bf16 v[124:127], v[156:159], v[192:195], v[124:127]
	v_mfma_f32_16x16x32_bf16 v[120:123], v[168:171], v[192:195], v[120:123]
	v_mfma_f32_16x16x32_bf16 v[124:127], v[164:167], v[196:199], v[124:127]
	v_mfma_f32_16x16x32_bf16 v[120:123], v[172:175], v[196:199], v[120:123]
	s_barrier
	v_mfma_f32_16x16x32_bf16 v[108:111], v[156:159], v[200:203], v[108:111]
	v_mfma_f32_16x16x32_bf16 v[104:107], v[168:171], v[200:203], v[104:107]
	v_mfma_f32_16x16x32_bf16 v[92:95], v[156:159], v[208:211], v[92:95]
	v_mfma_f32_16x16x32_bf16 v[88:91], v[168:171], v[208:211], v[88:91]
	v_mfma_f32_16x16x32_bf16 v[76:79], v[156:159], v[216:219], v[76:79]
	v_mfma_f32_16x16x32_bf16 v[72:75], v[168:171], v[216:219], v[72:75]
	v_mfma_f32_16x16x32_bf16 v[116:119], v[176:179], v[192:195], v[116:119]
	v_mfma_f32_16x16x32_bf16 v[112:115], v[184:187], v[192:195], v[112:115]
	v_mfma_f32_16x16x32_bf16 v[100:103], v[176:179], v[200:203], v[100:103]
	v_mfma_f32_16x16x32_bf16 v[96:99], v[184:187], v[200:203], v[96:99]
	v_mfma_f32_16x16x32_bf16 v[84:87], v[176:179], v[208:211], v[84:87]
	v_mfma_f32_16x16x32_bf16 v[80:83], v[184:187], v[208:211], v[80:83]
	v_mfma_f32_16x16x32_bf16 v[68:71], v[176:179], v[216:219], v[68:71]
	v_mfma_f32_16x16x32_bf16 v[64:67], v[184:187], v[216:219], v[64:67]
	v_mfma_f32_16x16x32_bf16 v[108:111], v[164:167], v[204:207], v[108:111]
	v_mfma_f32_16x16x32_bf16 v[104:107], v[172:175], v[204:207], v[104:107]
	v_mfma_f32_16x16x32_bf16 v[92:95], v[164:167], v[212:215], v[92:95]
	v_mfma_f32_16x16x32_bf16 v[88:91], v[172:175], v[212:215], v[88:91]
	v_mfma_f32_16x16x32_bf16 v[76:79], v[164:167], v[222:225], v[76:79]
	v_mfma_f32_16x16x32_bf16 v[72:75], v[172:175], v[222:225], v[72:75]
	v_mfma_f32_16x16x32_bf16 v[116:119], v[180:183], v[196:199], v[116:119]
	v_mfma_f32_16x16x32_bf16 v[112:115], v[188:191], v[196:199], v[112:115]
	v_mfma_f32_16x16x32_bf16 v[100:103], v[180:183], v[204:207], v[100:103]
	v_mfma_f32_16x16x32_bf16 v[96:99], v[188:191], v[204:207], v[96:99]
	v_mfma_f32_16x16x32_bf16 v[84:87], v[180:183], v[212:215], v[84:87]
	v_mfma_f32_16x16x32_bf16 v[80:83], v[188:191], v[212:215], v[80:83]
	v_mfma_f32_16x16x32_bf16 v[68:71], v[180:183], v[222:225], v[68:71]
	v_mfma_f32_16x16x32_bf16 v[64:67], v[188:191], v[222:225], v[64:67]
	s_barrier
	s_add_i32 s53, s95, s15
	v_lshl_add_u64 v[226:227], s[28:29], 0, v[132:133]
	s_mov_b32 m0, s53
	ds_read_b128 v[192:195], v163 offset:16384
	ds_read_b128 v[196:199], v163 offset:17408
	ds_read_b128 v[200:203], v163 offset:18432
	ds_read_b128 v[204:207], v163 offset:19456
	ds_read_b128 v[208:211], v163 offset:20480
	ds_read_b128 v[212:215], v163 offset:21504
	ds_read_b128 v[216:219], v163 offset:22528
	ds_read_b128 v[222:225], v163 offset:23552
	global_load_lds_dwordx4 v[226:227], off
	s_add_i32 m0, s53, 0x2000
	s_add_u32 s54, s28, 0x80000
	v_lshl_add_u64 v[228:229], s[28:29], 0, v[128:129]
	s_addc_u32 s55, s29, 0
	s_add_i32 s53, s33, s15
	global_load_lds_dwordx4 v[228:229], off
	s_mov_b32 m0, s53
	v_lshl_add_u64 v[232:233], s[30:31], 0, v[130:131]
	global_load_lds_dwordx4 v132, s[54:55]
	s_add_i32 m0, s53, 0x2000
	s_nop 0
	global_load_lds_dwordx4 v128, s[54:55]
	v_lshl_add_u64 v[230:231], s[30:31], 0, v[134:135]
	s_mov_b32 m0, s35
	s_nop 0
	global_load_lds_dwordx4 v[230:231], off
	s_mov_b32 m0, s36
	s_nop 0
	global_load_lds_dwordx4 v[232:233], off
	s_waitcnt vmcnt(8)
	s_waitcnt lgkmcnt(0)
	s_waitcnt lgkmcnt(0)
	v_mfma_f32_16x16x32_bf16 v[60:63], v[156:159], v[192:195], v[60:63]
	v_mfma_f32_16x16x32_bf16 v[56:59], v[168:171], v[192:195], v[56:59]
	v_mfma_f32_16x16x32_bf16 v[60:63], v[164:167], v[196:199], v[60:63]
	v_mfma_f32_16x16x32_bf16 v[56:59], v[172:175], v[196:199], v[56:59]
	s_barrier
	v_mfma_f32_16x16x32_bf16 v[44:47], v[156:159], v[200:203], v[44:47]
	v_mfma_f32_16x16x32_bf16 v[40:43], v[168:171], v[200:203], v[40:43]
	v_mfma_f32_16x16x32_bf16 v[28:31], v[156:159], v[208:211], v[28:31]
	v_mfma_f32_16x16x32_bf16 v[24:27], v[168:171], v[208:211], v[24:27]
	v_mfma_f32_16x16x32_bf16 v[12:15], v[156:159], v[216:219], v[12:15]
	v_mfma_f32_16x16x32_bf16 v[8:11], v[168:171], v[216:219], v[8:11]
	v_mfma_f32_16x16x32_bf16 v[52:55], v[176:179], v[192:195], v[52:55]
	v_mfma_f32_16x16x32_bf16 v[48:51], v[184:187], v[192:195], v[48:51]
	v_mfma_f32_16x16x32_bf16 v[36:39], v[176:179], v[200:203], v[36:39]
	v_mfma_f32_16x16x32_bf16 v[32:35], v[184:187], v[200:203], v[32:35]
	v_mfma_f32_16x16x32_bf16 v[20:23], v[176:179], v[208:211], v[20:23]
	v_mfma_f32_16x16x32_bf16 v[16:19], v[184:187], v[208:211], v[16:19]
	v_mfma_f32_16x16x32_bf16 v[4:7], v[176:179], v[216:219], v[4:7]
	v_mfma_f32_16x16x32_bf16 v[0:3], v[184:187], v[216:219], v[0:3]
	v_mfma_f32_16x16x32_bf16 v[44:47], v[164:167], v[204:207], v[44:47]
	v_mfma_f32_16x16x32_bf16 v[40:43], v[172:175], v[204:207], v[40:43]
	v_mfma_f32_16x16x32_bf16 v[28:31], v[164:167], v[212:215], v[28:31]
	v_mfma_f32_16x16x32_bf16 v[24:27], v[172:175], v[212:215], v[24:27]
	v_mfma_f32_16x16x32_bf16 v[12:15], v[164:167], v[222:225], v[12:15]
	v_mfma_f32_16x16x32_bf16 v[8:11], v[172:175], v[222:225], v[8:11]
	v_mfma_f32_16x16x32_bf16 v[52:55], v[180:183], v[196:199], v[52:55]
	v_mfma_f32_16x16x32_bf16 v[48:51], v[188:191], v[196:199], v[48:51]
	v_mfma_f32_16x16x32_bf16 v[36:39], v[180:183], v[204:207], v[36:39]
	v_mfma_f32_16x16x32_bf16 v[32:35], v[188:191], v[204:207], v[32:35]
	v_mfma_f32_16x16x32_bf16 v[20:23], v[180:183], v[212:215], v[20:23]
	v_mfma_f32_16x16x32_bf16 v[16:19], v[188:191], v[212:215], v[16:19]
	v_mfma_f32_16x16x32_bf16 v[4:7], v[180:183], v[222:225], v[4:7]
	v_mfma_f32_16x16x32_bf16 v[0:3], v[188:191], v[222:225], v[0:3]
	s_barrier
	v_add_u32_e32 v153, s3, v161
	ds_read_b128 v[156:159], v153
	ds_read_b128 v[164:167], v153 offset:1024
	ds_read_b128 v[168:171], v153 offset:2048
	ds_read_b128 v[172:175], v153 offset:3072
	v_add_u32_e32 v153, s58, v161
	ds_read_b128 v[176:179], v153
	ds_read_b128 v[180:183], v153 offset:1024
	ds_read_b128 v[184:187], v153 offset:2048
	ds_read_b128 v[188:191], v153 offset:3072
	s_add_u32 s30, s30, 0x80000
	s_addc_u32 s31, s31, 0
	s_mov_b32 m0, s37
	ds_read_b128 v[192:195], v163 offset:32768
	ds_read_b128 v[196:199], v163 offset:33792
	ds_read_b128 v[200:203], v163 offset:34816
	ds_read_b128 v[204:207], v163 offset:35840
	ds_read_b128 v[208:211], v163 offset:36864
	ds_read_b128 v[212:215], v163 offset:37888
	ds_read_b128 v[216:219], v163 offset:38912
	ds_read_b128 v[222:225], v163 offset:39936
	global_load_lds_dwordx4 v134, s[30:31]
	s_mov_b32 m0, s38
	s_nop 0
	global_load_lds_dwordx4 v130, s[30:31]
	s_waitcnt vmcnt(8)
	s_waitcnt lgkmcnt(0)
	s_waitcnt lgkmcnt(0)
	v_mfma_f32_16x16x32_bf16 v[124:127], v[156:159], v[192:195], v[124:127]
	v_mfma_f32_16x16x32_bf16 v[120:123], v[168:171], v[192:195], v[120:123]
	v_mfma_f32_16x16x32_bf16 v[124:127], v[164:167], v[196:199], v[124:127]
	v_mfma_f32_16x16x32_bf16 v[120:123], v[172:175], v[196:199], v[120:123]
	s_barrier
	v_mfma_f32_16x16x32_bf16 v[108:111], v[156:159], v[200:203], v[108:111]
	v_mfma_f32_16x16x32_bf16 v[104:107], v[168:171], v[200:203], v[104:107]
	v_mfma_f32_16x16x32_bf16 v[92:95], v[156:159], v[208:211], v[92:95]
	v_mfma_f32_16x16x32_bf16 v[88:91], v[168:171], v[208:211], v[88:91]
	v_mfma_f32_16x16x32_bf16 v[76:79], v[156:159], v[216:219], v[76:79]
	v_mfma_f32_16x16x32_bf16 v[72:75], v[168:171], v[216:219], v[72:75]
	v_mfma_f32_16x16x32_bf16 v[116:119], v[176:179], v[192:195], v[116:119]
	v_mfma_f32_16x16x32_bf16 v[112:115], v[184:187], v[192:195], v[112:115]
	v_mfma_f32_16x16x32_bf16 v[100:103], v[176:179], v[200:203], v[100:103]
	v_mfma_f32_16x16x32_bf16 v[96:99], v[184:187], v[200:203], v[96:99]
	v_mfma_f32_16x16x32_bf16 v[84:87], v[176:179], v[208:211], v[84:87]
	v_mfma_f32_16x16x32_bf16 v[80:83], v[184:187], v[208:211], v[80:83]
	v_mfma_f32_16x16x32_bf16 v[68:71], v[176:179], v[216:219], v[68:71]
	v_mfma_f32_16x16x32_bf16 v[64:67], v[184:187], v[216:219], v[64:67]
	v_mfma_f32_16x16x32_bf16 v[108:111], v[164:167], v[204:207], v[108:111]
	v_mfma_f32_16x16x32_bf16 v[104:107], v[172:175], v[204:207], v[104:107]
	v_mfma_f32_16x16x32_bf16 v[92:95], v[164:167], v[212:215], v[92:95]
	v_mfma_f32_16x16x32_bf16 v[88:91], v[172:175], v[212:215], v[88:91]
	v_mfma_f32_16x16x32_bf16 v[76:79], v[164:167], v[222:225], v[76:79]
	v_mfma_f32_16x16x32_bf16 v[72:75], v[172:175], v[222:225], v[72:75]
	v_mfma_f32_16x16x32_bf16 v[116:119], v[180:183], v[196:199], v[116:119]
	v_mfma_f32_16x16x32_bf16 v[112:115], v[188:191], v[196:199], v[112:115]
	v_mfma_f32_16x16x32_bf16 v[100:103], v[180:183], v[204:207], v[100:103]
	v_mfma_f32_16x16x32_bf16 v[96:99], v[188:191], v[204:207], v[96:99]
	v_mfma_f32_16x16x32_bf16 v[84:87], v[180:183], v[212:215], v[84:87]
	v_mfma_f32_16x16x32_bf16 v[80:83], v[188:191], v[212:215], v[80:83]
	v_mfma_f32_16x16x32_bf16 v[68:71], v[180:183], v[222:225], v[68:71]
	v_mfma_f32_16x16x32_bf16 v[64:67], v[188:191], v[222:225], v[64:67]
	s_barrier
	s_add_i32 s30, s3, s15
	v_lshl_add_u64 v[226:227], v[226:227], 0, s[8:9]
	s_mov_b32 m0, s30
	ds_read_b128 v[192:195], v163 offset:49152
	ds_read_b128 v[196:199], v163 offset:50176
	ds_read_b128 v[200:203], v163 offset:51200
	ds_read_b128 v[204:207], v163 offset:52224
	ds_read_b128 v[208:211], v163 offset:53248
	ds_read_b128 v[212:215], v163 offset:54272
	ds_read_b128 v[216:219], v163 offset:55296
	ds_read_b128 v[222:225], v163 offset:56320
	global_load_lds_dwordx4 v[226:227], off
	s_add_i32 m0, s30, 0x2000
	s_add_u32 s28, s28, 0x80080
	v_lshl_add_u64 v[226:227], v[228:229], 0, s[8:9]
	s_addc_u32 s29, s29, 0
	s_add_i32 s30, s58, s15
	global_load_lds_dwordx4 v[226:227], off
	s_mov_b32 m0, s30
	s_nop 0
	global_load_lds_dwordx4 v132, s[28:29]
	s_add_i32 m0, s30, 0x2000
	s_nop 0
	global_load_lds_dwordx4 v128, s[28:29]
	v_lshl_add_u64 v[226:227], v[230:231], 0, s[8:9]
	s_mov_b32 m0, s40
	s_nop 0
	global_load_lds_dwordx4 v[226:227], off
	v_lshl_add_u64 v[226:227], v[232:233], 0, s[8:9]
	s_mov_b32 m0, s41
	s_nop 0
	global_load_lds_dwordx4 v[226:227], off
	s_waitcnt vmcnt(8)
	s_waitcnt lgkmcnt(0)
	s_waitcnt lgkmcnt(0)
	v_mfma_f32_16x16x32_bf16 v[60:63], v[156:159], v[192:195], v[60:63]
	v_mfma_f32_16x16x32_bf16 v[56:59], v[168:171], v[192:195], v[56:59]
	v_mfma_f32_16x16x32_bf16 v[60:63], v[164:167], v[196:199], v[60:63]
	v_mfma_f32_16x16x32_bf16 v[56:59], v[172:175], v[196:199], v[56:59]
	s_barrier
	v_mfma_f32_16x16x32_bf16 v[44:47], v[156:159], v[200:203], v[44:47]
	v_mfma_f32_16x16x32_bf16 v[40:43], v[168:171], v[200:203], v[40:43]
	v_mfma_f32_16x16x32_bf16 v[28:31], v[156:159], v[208:211], v[28:31]
	v_mfma_f32_16x16x32_bf16 v[24:27], v[168:171], v[208:211], v[24:27]
	v_mfma_f32_16x16x32_bf16 v[12:15], v[156:159], v[216:219], v[12:15]
	v_mfma_f32_16x16x32_bf16 v[8:11], v[168:171], v[216:219], v[8:11]
	v_mfma_f32_16x16x32_bf16 v[52:55], v[176:179], v[192:195], v[52:55]
	v_mfma_f32_16x16x32_bf16 v[48:51], v[184:187], v[192:195], v[48:51]
	v_mfma_f32_16x16x32_bf16 v[36:39], v[176:179], v[200:203], v[36:39]
	v_mfma_f32_16x16x32_bf16 v[32:35], v[184:187], v[200:203], v[32:35]
	v_mfma_f32_16x16x32_bf16 v[20:23], v[176:179], v[208:211], v[20:23]
	v_mfma_f32_16x16x32_bf16 v[16:19], v[184:187], v[208:211], v[16:19]
	v_mfma_f32_16x16x32_bf16 v[4:7], v[176:179], v[216:219], v[4:7]
	v_mfma_f32_16x16x32_bf16 v[0:3], v[184:187], v[216:219], v[0:3]
	v_mfma_f32_16x16x32_bf16 v[44:47], v[164:167], v[204:207], v[44:47]
	v_mfma_f32_16x16x32_bf16 v[40:43], v[172:175], v[204:207], v[40:43]
	v_mfma_f32_16x16x32_bf16 v[28:31], v[164:167], v[212:215], v[28:31]
	v_mfma_f32_16x16x32_bf16 v[24:27], v[172:175], v[212:215], v[24:27]
	v_mfma_f32_16x16x32_bf16 v[12:15], v[164:167], v[222:225], v[12:15]
	v_mfma_f32_16x16x32_bf16 v[8:11], v[172:175], v[222:225], v[8:11]
	v_mfma_f32_16x16x32_bf16 v[52:55], v[180:183], v[196:199], v[52:55]
	v_mfma_f32_16x16x32_bf16 v[48:51], v[188:191], v[196:199], v[48:51]
	v_mfma_f32_16x16x32_bf16 v[36:39], v[180:183], v[204:207], v[36:39]
	v_mfma_f32_16x16x32_bf16 v[32:35], v[188:191], v[204:207], v[32:35]
	v_mfma_f32_16x16x32_bf16 v[20:23], v[180:183], v[212:215], v[20:23]
	v_mfma_f32_16x16x32_bf16 v[16:19], v[188:191], v[212:215], v[16:19]
	v_mfma_f32_16x16x32_bf16 v[4:7], v[180:183], v[222:225], v[4:7]
	v_mfma_f32_16x16x32_bf16 v[0:3], v[188:191], v[222:225], v[0:3]
	s_barrier
	s_add_i32 s51, s51, 2
	s_add_u32 s26, s26, 0x100
	s_addc_u32 s27, s27, 0
	s_add_u32 s49, s49, 0x100
	s_addc_u32 s50, s50, 0
	s_cmp_gt_u32 s51, 29
	s_cbranch_scc1 .LBB0_1952

.LBB0_2044:
	ds_read_b128 v[144:147], v157
	ds_read_b128 v[148:151], v157 offset:1024
	ds_read_b128 v[162:165], v157 offset:2048
	ds_read_b128 v[166:169], v157 offset:3072
	ds_read_b128 v[170:173], v158
	ds_read_b128 v[174:177], v158 offset:1024
	ds_read_b128 v[178:181], v158 offset:2048
	ds_read_b128 v[182:185], v158 offset:3072
	s_add_u32 s4, s6, 0x100
	s_addc_u32 s5, s7, 0
	s_cmpk_eq_i32 s56, 0x54
	s_cselect_b32 s37, s29, s5
	s_cselect_b32 s36, s28, s4
	s_cselect_b32 s35, s31, s55
	s_cselect_b32 s34, s30, s54
	v_lshl_add_u64 v[152:153], s[6:7], 0, v[136:137]
	s_add_i32 m0, s40, 0xc000
	ds_read_b128 v[186:189], v159
	ds_read_b128 v[190:193], v159 offset:1024
	ds_read_b128 v[194:197], v159 offset:2048
	ds_read_b128 v[198:201], v159 offset:3072
	ds_read_b128 v[202:205], v159 offset:4096
	ds_read_b128 v[206:209], v159 offset:5120
	ds_read_b128 v[210:213], v159 offset:6144
	ds_read_b128 v[214:217], v159 offset:7168
	global_load_lds_dwordx4 v[152:153], off
	v_lshl_add_u64 v[152:153], s[6:7], 0, v[138:139]
	s_add_i32 m0, s40, 0xe000
	s_nop 0
	global_load_lds_dwordx4 v[152:153], off
	s_waitcnt vmcnt(8)
	s_waitcnt lgkmcnt(0)
	s_waitcnt lgkmcnt(0)
	v_mfma_f32_16x16x32_bf16 v[124:127], v[144:147], v[186:189], v[124:127]
	v_mfma_f32_16x16x32_bf16 v[120:123], v[162:165], v[186:189], v[120:123]
	v_mfma_f32_16x16x32_bf16 v[124:127], v[148:151], v[190:193], v[124:127]
	v_mfma_f32_16x16x32_bf16 v[120:123], v[166:169], v[190:193], v[120:123]
	s_barrier
	v_mfma_f32_16x16x32_bf16 v[108:111], v[144:147], v[194:197], v[108:111]
	v_mfma_f32_16x16x32_bf16 v[104:107], v[162:165], v[194:197], v[104:107]
	v_mfma_f32_16x16x32_bf16 v[92:95], v[144:147], v[202:205], v[92:95]
	v_mfma_f32_16x16x32_bf16 v[88:91], v[162:165], v[202:205], v[88:91]
	v_mfma_f32_16x16x32_bf16 v[76:79], v[144:147], v[210:213], v[76:79]
	v_mfma_f32_16x16x32_bf16 v[72:75], v[162:165], v[210:213], v[72:75]
	v_mfma_f32_16x16x32_bf16 v[116:119], v[170:173], v[186:189], v[116:119]
	v_mfma_f32_16x16x32_bf16 v[112:115], v[178:181], v[186:189], v[112:115]
	v_mfma_f32_16x16x32_bf16 v[100:103], v[170:173], v[194:197], v[100:103]
	v_mfma_f32_16x16x32_bf16 v[96:99], v[178:181], v[194:197], v[96:99]
	v_mfma_f32_16x16x32_bf16 v[84:87], v[170:173], v[202:205], v[84:87]
	v_mfma_f32_16x16x32_bf16 v[80:83], v[178:181], v[202:205], v[80:83]
	v_mfma_f32_16x16x32_bf16 v[68:71], v[170:173], v[210:213], v[68:71]
	v_mfma_f32_16x16x32_bf16 v[64:67], v[178:181], v[210:213], v[64:67]
	v_mfma_f32_16x16x32_bf16 v[108:111], v[148:151], v[198:201], v[108:111]
	v_mfma_f32_16x16x32_bf16 v[104:107], v[166:169], v[198:201], v[104:107]
	v_mfma_f32_16x16x32_bf16 v[92:95], v[148:151], v[206:209], v[92:95]
	v_mfma_f32_16x16x32_bf16 v[88:91], v[166:169], v[206:209], v[88:91]
	v_mfma_f32_16x16x32_bf16 v[76:79], v[148:151], v[214:217], v[76:79]
	v_mfma_f32_16x16x32_bf16 v[72:75], v[166:169], v[214:217], v[72:75]
	v_mfma_f32_16x16x32_bf16 v[116:119], v[174:177], v[190:193], v[116:119]
	v_mfma_f32_16x16x32_bf16 v[112:115], v[182:185], v[190:193], v[112:115]
	v_mfma_f32_16x16x32_bf16 v[100:103], v[174:177], v[198:201], v[100:103]
	v_mfma_f32_16x16x32_bf16 v[96:99], v[182:185], v[198:201], v[96:99]
	v_mfma_f32_16x16x32_bf16 v[84:87], v[174:177], v[206:209], v[84:87]
	v_mfma_f32_16x16x32_bf16 v[80:83], v[182:185], v[206:209], v[80:83]
	v_mfma_f32_16x16x32_bf16 v[68:71], v[174:177], v[214:217], v[68:71]
	v_mfma_f32_16x16x32_bf16 v[64:67], v[182:185], v[214:217], v[64:67]
	s_barrier
	s_add_i32 s6, s95, s39
	v_lshl_add_u64 v[152:153], s[34:35], 0, v[130:131]
	s_mov_b32 m0, s6
	ds_read_b128 v[186:189], v159 offset:16384
	ds_read_b128 v[190:193], v159 offset:17408
	ds_read_b128 v[194:197], v159 offset:18432
	ds_read_b128 v[198:201], v159 offset:19456
	ds_read_b128 v[202:205], v159 offset:20480
	ds_read_b128 v[206:209], v159 offset:21504
	ds_read_b128 v[210:213], v159 offset:22528
	ds_read_b128 v[214:217], v159 offset:23552
	global_load_lds_dwordx4 v[152:153], off
	s_add_i32 m0, s6, 0x2000
	s_add_u32 s6, s34, 0x160000
	v_lshl_add_u64 v[218:219], s[34:35], 0, v[134:135]
	s_addc_u32 s7, s35, 0
	s_add_i32 s57, s33, s39
	global_load_lds_dwordx4 v[218:219], off
	s_mov_b32 m0, s57
	v_lshl_add_u64 v[222:223], s[36:37], 0, v[132:133]
	global_load_lds_dwordx4 v130, s[6:7]
	s_add_i32 m0, s57, 0x2000
	s_nop 0
	global_load_lds_dwordx4 v134, s[6:7]
	v_lshl_add_u64 v[220:221], s[36:37], 0, v[128:129]
	s_mov_b32 m0, s40
	s_nop 0
	global_load_lds_dwordx4 v[220:221], off
	s_mov_b32 m0, s41
	s_nop 0
	global_load_lds_dwordx4 v[222:223], off
	s_waitcnt vmcnt(8)
	s_waitcnt lgkmcnt(0)
	s_waitcnt lgkmcnt(0)
	v_mfma_f32_16x16x32_bf16 v[60:63], v[144:147], v[186:189], v[60:63]
	v_mfma_f32_16x16x32_bf16 v[56:59], v[162:165], v[186:189], v[56:59]
	v_mfma_f32_16x16x32_bf16 v[60:63], v[148:151], v[190:193], v[60:63]
	v_mfma_f32_16x16x32_bf16 v[56:59], v[166:169], v[190:193], v[56:59]
	s_barrier
	v_mfma_f32_16x16x32_bf16 v[44:47], v[144:147], v[194:197], v[44:47]
	v_mfma_f32_16x16x32_bf16 v[40:43], v[162:165], v[194:197], v[40:43]
	v_mfma_f32_16x16x32_bf16 v[28:31], v[144:147], v[202:205], v[28:31]
	v_mfma_f32_16x16x32_bf16 v[24:27], v[162:165], v[202:205], v[24:27]
	v_mfma_f32_16x16x32_bf16 v[12:15], v[144:147], v[210:213], v[12:15]
	v_mfma_f32_16x16x32_bf16 v[8:11], v[162:165], v[210:213], v[8:11]
	v_mfma_f32_16x16x32_bf16 v[52:55], v[170:173], v[186:189], v[52:55]
	v_mfma_f32_16x16x32_bf16 v[48:51], v[178:181], v[186:189], v[48:51]
	v_mfma_f32_16x16x32_bf16 v[36:39], v[170:173], v[194:197], v[36:39]
	v_mfma_f32_16x16x32_bf16 v[32:35], v[178:181], v[194:197], v[32:35]
	v_mfma_f32_16x16x32_bf16 v[20:23], v[170:173], v[202:205], v[20:23]
	v_mfma_f32_16x16x32_bf16 v[16:19], v[178:181], v[202:205], v[16:19]
	v_mfma_f32_16x16x32_bf16 v[4:7], v[170:173], v[210:213], v[4:7]
	v_mfma_f32_16x16x32_bf16 v[0:3], v[178:181], v[210:213], v[0:3]
	v_mfma_f32_16x16x32_bf16 v[44:47], v[148:151], v[198:201], v[44:47]
	v_mfma_f32_16x16x32_bf16 v[40:43], v[166:169], v[198:201], v[40:43]
	v_mfma_f32_16x16x32_bf16 v[28:31], v[148:151], v[206:209], v[28:31]
	v_mfma_f32_16x16x32_bf16 v[24:27], v[166:169], v[206:209], v[24:27]
	v_mfma_f32_16x16x32_bf16 v[12:15], v[148:151], v[214:217], v[12:15]
	v_mfma_f32_16x16x32_bf16 v[8:11], v[166:169], v[214:217], v[8:11]
	v_mfma_f32_16x16x32_bf16 v[52:55], v[174:177], v[190:193], v[52:55]
	v_mfma_f32_16x16x32_bf16 v[48:51], v[182:185], v[190:193], v[48:51]
	v_mfma_f32_16x16x32_bf16 v[36:39], v[174:177], v[198:201], v[36:39]
	v_mfma_f32_16x16x32_bf16 v[32:35], v[182:185], v[198:201], v[32:35]
	v_mfma_f32_16x16x32_bf16 v[20:23], v[174:177], v[206:209], v[20:23]
	v_mfma_f32_16x16x32_bf16 v[16:19], v[182:185], v[206:209], v[16:19]
	v_mfma_f32_16x16x32_bf16 v[4:7], v[174:177], v[214:217], v[4:7]
	v_mfma_f32_16x16x32_bf16 v[0:3], v[182:185], v[214:217], v[0:3]
	s_barrier
	v_add_u32_e32 v161, s3, v155
	ds_read_b128 v[144:147], v161
	ds_read_b128 v[148:151], v161 offset:1024
	ds_read_b128 v[162:165], v161 offset:2048
	ds_read_b128 v[166:169], v161 offset:3072
	v_add_u32_e32 v161, s58, v155
	ds_read_b128 v[170:173], v161
	ds_read_b128 v[174:177], v161 offset:1024
	ds_read_b128 v[178:181], v161 offset:2048
	ds_read_b128 v[182:185], v161 offset:3072
	s_add_u32 s6, s36, 0x160000
	s_addc_u32 s7, s37, 0
	s_mov_b32 m0, s42
	ds_read_b128 v[186:189], v159 offset:32768
	ds_read_b128 v[190:193], v159 offset:33792
	ds_read_b128 v[194:197], v159 offset:34816
	ds_read_b128 v[198:201], v159 offset:35840
	ds_read_b128 v[202:205], v159 offset:36864
	ds_read_b128 v[206:209], v159 offset:37888
	ds_read_b128 v[210:213], v159 offset:38912
	ds_read_b128 v[214:217], v159 offset:39936
	global_load_lds_dwordx4 v128, s[6:7]
	s_mov_b32 m0, s43
	s_nop 0
	global_load_lds_dwordx4 v132, s[6:7]
	s_waitcnt vmcnt(8)
	s_waitcnt lgkmcnt(0)
	s_waitcnt lgkmcnt(0)
	v_mfma_f32_16x16x32_bf16 v[124:127], v[144:147], v[186:189], v[124:127]
	v_mfma_f32_16x16x32_bf16 v[120:123], v[162:165], v[186:189], v[120:123]
	v_mfma_f32_16x16x32_bf16 v[124:127], v[148:151], v[190:193], v[124:127]
	v_mfma_f32_16x16x32_bf16 v[120:123], v[166:169], v[190:193], v[120:123]
	s_barrier
	v_mfma_f32_16x16x32_bf16 v[108:111], v[144:147], v[194:197], v[108:111]
	v_mfma_f32_16x16x32_bf16 v[104:107], v[162:165], v[194:197], v[104:107]
	v_mfma_f32_16x16x32_bf16 v[92:95], v[144:147], v[202:205], v[92:95]
	v_mfma_f32_16x16x32_bf16 v[88:91], v[162:165], v[202:205], v[88:91]
	v_mfma_f32_16x16x32_bf16 v[76:79], v[144:147], v[210:213], v[76:79]
	v_mfma_f32_16x16x32_bf16 v[72:75], v[162:165], v[210:213], v[72:75]
	v_mfma_f32_16x16x32_bf16 v[116:119], v[170:173], v[186:189], v[116:119]
	v_mfma_f32_16x16x32_bf16 v[112:115], v[178:181], v[186:189], v[112:115]
	v_mfma_f32_16x16x32_bf16 v[100:103], v[170:173], v[194:197], v[100:103]
	v_mfma_f32_16x16x32_bf16 v[96:99], v[178:181], v[194:197], v[96:99]
	v_mfma_f32_16x16x32_bf16 v[84:87], v[170:173], v[202:205], v[84:87]
	v_mfma_f32_16x16x32_bf16 v[80:83], v[178:181], v[202:205], v[80:83]
	v_mfma_f32_16x16x32_bf16 v[68:71], v[170:173], v[210:213], v[68:71]
	v_mfma_f32_16x16x32_bf16 v[64:67], v[178:181], v[210:213], v[64:67]
	v_mfma_f32_16x16x32_bf16 v[108:111], v[148:151], v[198:201], v[108:111]
	v_mfma_f32_16x16x32_bf16 v[104:107], v[166:169], v[198:201], v[104:107]
	v_mfma_f32_16x16x32_bf16 v[92:95], v[148:151], v[206:209], v[92:95]
	v_mfma_f32_16x16x32_bf16 v[88:91], v[166:169], v[206:209], v[88:91]
	v_mfma_f32_16x16x32_bf16 v[76:79], v[148:151], v[214:217], v[76:79]
	v_mfma_f32_16x16x32_bf16 v[72:75], v[166:169], v[214:217], v[72:75]
	v_mfma_f32_16x16x32_bf16 v[116:119], v[174:177], v[190:193], v[116:119]
	v_mfma_f32_16x16x32_bf16 v[112:115], v[182:185], v[190:193], v[112:115]
	v_mfma_f32_16x16x32_bf16 v[100:103], v[174:177], v[198:201], v[100:103]
	v_mfma_f32_16x16x32_bf16 v[96:99], v[182:185], v[198:201], v[96:99]
	v_mfma_f32_16x16x32_bf16 v[84:87], v[174:177], v[206:209], v[84:87]
	v_mfma_f32_16x16x32_bf16 v[80:83], v[182:185], v[206:209], v[80:83]
	v_mfma_f32_16x16x32_bf16 v[68:71], v[174:177], v[214:217], v[68:71]
	v_mfma_f32_16x16x32_bf16 v[64:67], v[182:185], v[214:217], v[64:67]
	s_barrier
	s_add_i32 s6, s3, s39
	v_lshl_add_u64 v[152:153], v[152:153], 0, s[12:13]
	s_mov_b32 m0, s6
	ds_read_b128 v[186:189], v159 offset:49152
	ds_read_b128 v[190:193], v159 offset:50176
	ds_read_b128 v[194:197], v159 offset:51200
	ds_read_b128 v[198:201], v159 offset:52224
	ds_read_b128 v[202:205], v159 offset:53248
	ds_read_b128 v[206:209], v159 offset:54272
	ds_read_b128 v[210:213], v159 offset:55296
	ds_read_b128 v[214:217], v159 offset:56320
	global_load_lds_dwordx4 v[152:153], off
	s_add_i32 m0, s6, 0x2000
	s_add_u32 s6, s34, 0x160080
	v_lshl_add_u64 v[152:153], v[218:219], 0, s[12:13]
	s_addc_u32 s7, s35, 0
	s_add_i32 s34, s58, s39
	global_load_lds_dwordx4 v[152:153], off
	s_mov_b32 m0, s34
	s_nop 0
	global_load_lds_dwordx4 v130, s[6:7]
	s_add_i32 m0, s34, 0x2000
	s_nop 0
	global_load_lds_dwordx4 v134, s[6:7]
	v_lshl_add_u64 v[152:153], v[220:221], 0, s[12:13]
	s_mov_b32 m0, s45
	s_nop 0
	global_load_lds_dwordx4 v[152:153], off
	v_lshl_add_u64 v[152:153], v[222:223], 0, s[12:13]
	s_mov_b32 m0, s46
	s_nop 0
	global_load_lds_dwordx4 v[152:153], off
	s_waitcnt vmcnt(8)
	s_waitcnt lgkmcnt(0)
	s_waitcnt lgkmcnt(0)
	v_mfma_f32_16x16x32_bf16 v[60:63], v[144:147], v[186:189], v[60:63]
	v_mfma_f32_16x16x32_bf16 v[56:59], v[162:165], v[186:189], v[56:59]
	v_mfma_f32_16x16x32_bf16 v[60:63], v[148:151], v[190:193], v[60:63]
	v_mfma_f32_16x16x32_bf16 v[56:59], v[166:169], v[190:193], v[56:59]
	s_barrier
	v_mfma_f32_16x16x32_bf16 v[44:47], v[144:147], v[194:197], v[44:47]
	v_mfma_f32_16x16x32_bf16 v[40:43], v[162:165], v[194:197], v[40:43]
	v_mfma_f32_16x16x32_bf16 v[28:31], v[144:147], v[202:205], v[28:31]
	v_mfma_f32_16x16x32_bf16 v[24:27], v[162:165], v[202:205], v[24:27]
	v_mfma_f32_16x16x32_bf16 v[12:15], v[144:147], v[210:213], v[12:15]
	v_mfma_f32_16x16x32_bf16 v[8:11], v[162:165], v[210:213], v[8:11]
	v_mfma_f32_16x16x32_bf16 v[52:55], v[170:173], v[186:189], v[52:55]
	v_mfma_f32_16x16x32_bf16 v[48:51], v[178:181], v[186:189], v[48:51]
	v_mfma_f32_16x16x32_bf16 v[36:39], v[170:173], v[194:197], v[36:39]
	v_mfma_f32_16x16x32_bf16 v[32:35], v[178:181], v[194:197], v[32:35]
	v_mfma_f32_16x16x32_bf16 v[20:23], v[170:173], v[202:205], v[20:23]
	v_mfma_f32_16x16x32_bf16 v[16:19], v[178:181], v[202:205], v[16:19]
	v_mfma_f32_16x16x32_bf16 v[4:7], v[170:173], v[210:213], v[4:7]
	v_mfma_f32_16x16x32_bf16 v[0:3], v[178:181], v[210:213], v[0:3]
	v_mfma_f32_16x16x32_bf16 v[44:47], v[148:151], v[198:201], v[44:47]
	v_mfma_f32_16x16x32_bf16 v[40:43], v[166:169], v[198:201], v[40:43]
	v_mfma_f32_16x16x32_bf16 v[28:31], v[148:151], v[206:209], v[28:31]
	v_mfma_f32_16x16x32_bf16 v[24:27], v[166:169], v[206:209], v[24:27]
	v_mfma_f32_16x16x32_bf16 v[12:15], v[148:151], v[214:217], v[12:15]
	v_mfma_f32_16x16x32_bf16 v[8:11], v[166:169], v[214:217], v[8:11]
	v_mfma_f32_16x16x32_bf16 v[52:55], v[174:177], v[190:193], v[52:55]
	v_mfma_f32_16x16x32_bf16 v[48:51], v[182:185], v[190:193], v[48:51]
	v_mfma_f32_16x16x32_bf16 v[36:39], v[174:177], v[198:201], v[36:39]
	v_mfma_f32_16x16x32_bf16 v[32:35], v[182:185], v[198:201], v[32:35]
	v_mfma_f32_16x16x32_bf16 v[20:23], v[174:177], v[206:209], v[20:23]
	v_mfma_f32_16x16x32_bf16 v[16:19], v[182:185], v[206:209], v[16:19]
	v_mfma_f32_16x16x32_bf16 v[4:7], v[174:177], v[214:217], v[4:7]
	v_mfma_f32_16x16x32_bf16 v[0:3], v[182:185], v[214:217], v[0:3]
	s_barrier
	s_add_i32 s56, s56, 2
	s_add_u32 s54, s54, 0x100
	s_addc_u32 s55, s55, 0
	s_cmpk_gt_u32 s56, 0x55
	s_mov_b64 s[6:7], s[4:5]
	s_cbranch_scc0 .LBB0_2044
	s_and_b64 vcc, exec, s[14:15]
	s_cbranch_vccz .LBB0_2047
	s_barrier
